# opt17+opt18: epilogue/natten quad reductions via v_permlane16/32_swap instead of ds_bpermute (no LDS round trips), on the v042 stack
# baseline (speedup 1.0000x reference)
.LBB0_389:
	v_lshl_add_u32 v150, s48, 8, v131
	v_ashrrev_i32_e32 v151, 31, v150
	v_lshl_or_b32 v148, s0, 8, v153
	v_lshlrev_b64 v[160:161], 11, v[150:151]
	v_ashrrev_i32_e32 v149, 31, v148
	v_lshl_add_u64 v[160:161], s[14:15], 0, v[160:161]
	v_lshl_add_u64 v[164:165], v[148:149], 1, v[160:161]
	v_mov_b32_e32 v232, v164
	v_mov_b32_e32 v233, v165
	global_load_dwordx4 v[188:191], v[232:233], off
	global_load_dwordx4 v[192:195], v[232:233], off offset:256
	s_mov_b64 s[100:101], 0x8000
	v_lshl_add_u64 v[230:231], v[232:233], 0, s[100:101]
	global_load_dwordx4 v[196:199], v[230:231], off
	global_load_dwordx4 v[200:203], v[230:231], off offset:256
	s_mov_b64 s[100:101], 0x10000
	v_lshl_add_u64 v[230:231], v[232:233], 0, s[100:101]
	global_load_dwordx4 v[204:207], v[230:231], off
	global_load_dwordx4 v[208:211], v[230:231], off offset:256
	s_mov_b64 s[100:101], 0x18000
	v_lshl_add_u64 v[230:231], v[232:233], 0, s[100:101]
	global_load_dwordx4 v[212:215], v[230:231], off
	global_load_dwordx4 v[216:219], v[230:231], off offset:256
	v_and_b32_e32 v170, 64, v158
	v_add_u32_e32 v170, 64, v170
	v_xor_b32_e32 v171, 32, v158
	s_lshl_b32 s48, s0, 2
	s_ashr_i32 s49, s48, 31
	s_waitcnt vmcnt(7)
	v_lshlrev_b32_e32 v159, 16, v188
	v_and_b32_e32 v160, 0xffff0000, v188
	v_lshlrev_b32_e32 v166, 16, v189
	v_and_b32_e32 v161, 0xffff0000, v189
	v_lshlrev_b32_e32 v167, 16, v190
	v_and_b32_e32 v162, 0xffff0000, v190
	v_lshlrev_b32_e32 v168, 16, v191
	v_and_b32_e32 v163, 0xffff0000, v191
	v_add_f32_e32 v159, v124, v159
	v_add_f32_e32 v169, v125, v160
	v_add_f32_e32 v126, v126, v166
	v_add_f32_e32 v127, v127, v161
	v_add_f32_e32 v166, v120, v167
	v_add_f32_e32 v121, v121, v162
	v_add_f32_e32 v167, v122, v168
	v_add_f32_e32 v168, v123, v163
	v_cvt_pk_bf16_f32 v122, v159, v169
	v_cvt_pk_bf16_f32 v123, v126, v127
	v_cvt_pk_bf16_f32 v124, v166, v121
	v_cvt_pk_bf16_f32 v125, v167, v168
	v_mul_f32_e32 v169, v169, v169
	v_mul_f32_e32 v127, v127, v127
	v_mul_f32_e32 v121, v121, v121
	v_mul_f32_e32 v168, v168, v168
	v_fmac_f32_e32 v169, v159, v159
	v_fmac_f32_e32 v127, v126, v126
	v_fmac_f32_e32 v121, v166, v166
	v_fmac_f32_e32 v168, v167, v167
	v_add_f32_e32 v126, v169, v127
	v_add_f32_e32 v121, v121, v168
	v_add_f32_e32 v121, v126, v121
	v_xor_b32_e32 v120, 16, v158
	v_cmp_lt_i32_e32 vcc, v120, v170
	global_store_dwordx4 v[164:165], v[122:125], off
	s_waitcnt vmcnt(7)
	v_lshlrev_b32_e32 v126, 16, v192
	v_and_b32_e32 v127, 0xffff0000, v192
	v_lshlrev_b32_e32 v159, 16, v193
	v_and_b32_e32 v160, 0xffff0000, v193
	v_lshlrev_b32_e32 v161, 16, v194
	v_and_b32_e32 v162, 0xffff0000, v194
	v_lshlrev_b32_e32 v166, 16, v195
	v_and_b32_e32 v163, 0xffff0000, v195
	v_add_f32_e32 v117, v117, v127
	v_add_f32_e32 v119, v119, v160
	v_add_f32_e32 v127, v113, v162
	v_add_f32_e32 v115, v115, v163
	v_add_f32_e32 v116, v116, v126
	v_add_f32_e32 v118, v118, v159
	v_add_f32_e32 v126, v112, v161
	v_add_f32_e32 v159, v114, v166
	v_mul_f32_e32 v112, v117, v117
	v_mul_f32_e32 v113, v119, v119
	v_mul_f32_e32 v114, v127, v127
	v_mul_f32_e32 v160, v115, v115
	v_fmac_f32_e32 v112, v116, v116
	v_fmac_f32_e32 v113, v118, v118
	v_fmac_f32_e32 v114, v126, v126
	v_fmac_f32_e32 v160, v159, v159
	v_add_f32_e32 v112, v112, v113
	v_add_f32_e32 v113, v114, v160
	v_cndmask_b32_e32 v120, v158, v120, vcc
	v_add_f32_e32 v112, v112, v113
	v_lshlrev_b32_e32 v120, 2, v120
	v_add_f32_e32 v112, v121, v112
	v_mov_b32_e32 v113, v112
	s_nop 1
	v_permlane16_swap_b32_e32 v113, v112
	v_cmp_lt_i32_e32 vcc, v171, v170
	v_cvt_pk_bf16_f32 v116, v116, v117
	v_cvt_pk_bf16_f32 v117, v118, v119
	v_cvt_pk_bf16_f32 v118, v126, v127
	s_waitcnt lgkmcnt(0)
	v_add_f32_e32 v112, v112, v113
	v_cvt_pk_bf16_f32 v119, v159, v115
	v_cndmask_b32_e32 v114, v158, v171, vcc
	v_lshlrev_b32_e32 v114, 2, v114
	v_mov_b32_e32 v113, v112
	s_nop 1
	v_permlane32_swap_b32_e32 v113, v112
	global_store_dwordx4 v[164:165], v[116:119], off offset:256
	s_and_saveexec_b64 s[50:51], s[4:5]
	s_cbranch_execz .LBB0_391
	v_lshlrev_b64 v[116:117], 6, v[150:151]
	v_lshl_add_u64 v[116:117], s[18:19], 0, v[116:117]
	v_lshl_add_u64 v[116:117], s[48:49], 2, v[116:117]
	s_lshl_b32 s0, s64, 2
	v_lshl_add_u64 v[116:117], v[116:117], 0, s[0:1]
	s_waitcnt lgkmcnt(0)
	v_add_f32_e32 v112, v112, v113
	global_store_dword v[116:117], v112, off
.LBB0_391:
	s_or_b64 exec, exec, s[50:51]
	v_or_b32_e32 v112, 16, v150
	s_waitcnt lgkmcnt(0)
	v_ashrrev_i32_e32 v113, 31, v112
	v_lshlrev_b64 v[116:117], 11, v[112:113]
	v_lshl_add_u64 v[116:117], s[14:15], 0, v[116:117]
	v_lshl_add_u64 v[122:123], v[148:149], 1, v[116:117]
	s_mov_b64 s[100:101], 0x40000
	v_lshl_add_u64 v[230:231], v[232:233], 0, s[100:101]
	global_load_dwordx4 v[188:191], v[230:231], off
	global_load_dwordx4 v[192:195], v[230:231], off offset:256
	s_waitcnt vmcnt(9)
	v_lshlrev_b32_e32 v115, 16, v196
	v_and_b32_e32 v116, 0xffff0000, v196
	v_lshlrev_b32_e32 v121, 16, v197
	v_and_b32_e32 v117, 0xffff0000, v197
	v_lshlrev_b32_e32 v124, 16, v198
	v_and_b32_e32 v118, 0xffff0000, v198
	v_lshlrev_b32_e32 v125, 16, v199
	v_and_b32_e32 v119, 0xffff0000, v199
	v_add_f32_e32 v115, v108, v115
	v_add_f32_e32 v116, v109, v116
	v_add_f32_e32 v121, v110, v121
	v_add_f32_e32 v117, v111, v117
	v_add_f32_e32 v124, v104, v124
	v_add_f32_e32 v118, v105, v118
	v_add_f32_e32 v125, v106, v125
	v_add_f32_e32 v119, v107, v119
	v_cvt_pk_bf16_f32 v104, v115, v116
	v_cvt_pk_bf16_f32 v105, v121, v117
	v_cvt_pk_bf16_f32 v106, v124, v118
	v_cvt_pk_bf16_f32 v107, v125, v119
	v_mul_f32_e32 v116, v116, v116
	v_mul_f32_e32 v117, v117, v117
	v_mul_f32_e32 v118, v118, v118
	v_mul_f32_e32 v119, v119, v119
	v_fmac_f32_e32 v116, v115, v115
	v_fmac_f32_e32 v117, v121, v121
	v_fmac_f32_e32 v118, v124, v124
	v_fmac_f32_e32 v119, v125, v125
	v_add_f32_e32 v115, v116, v117
	v_add_f32_e32 v116, v118, v119
	v_add_f32_e32 v115, v115, v116
	global_store_dwordx4 v[122:123], v[104:107], off
	s_waitcnt vmcnt(9)
	v_lshlrev_b32_e32 v116, 16, v200
	v_and_b32_e32 v108, 0xffff0000, v200
	v_lshlrev_b32_e32 v117, 16, v201
	v_and_b32_e32 v109, 0xffff0000, v201
	v_lshlrev_b32_e32 v118, 16, v202
	v_and_b32_e32 v110, 0xffff0000, v202
	v_lshlrev_b32_e32 v119, 16, v203
	v_and_b32_e32 v111, 0xffff0000, v203
	v_add_f32_e32 v101, v101, v108
	v_add_f32_e32 v103, v103, v109
	v_add_f32_e32 v109, v97, v110
	v_add_f32_e32 v111, v99, v111
	v_add_f32_e32 v100, v100, v116
	v_add_f32_e32 v102, v102, v117
	v_add_f32_e32 v108, v96, v118
	v_add_f32_e32 v110, v98, v119
	v_mul_f32_e32 v96, v101, v101
	v_mul_f32_e32 v97, v103, v103
	v_mul_f32_e32 v98, v109, v109
	v_mul_f32_e32 v99, v111, v111
	v_fmac_f32_e32 v96, v100, v100
	v_fmac_f32_e32 v97, v102, v102
	v_fmac_f32_e32 v98, v108, v108
	v_fmac_f32_e32 v99, v110, v110
	v_add_f32_e32 v96, v96, v97
	v_add_f32_e32 v97, v98, v99
	v_add_f32_e32 v96, v96, v97
	v_add_f32_e32 v96, v115, v96
	v_mov_b32_e32 v97, v96
	s_nop 1
	v_permlane16_swap_b32_e32 v97, v96
	v_cvt_pk_bf16_f32 v98, v100, v101
	v_cvt_pk_bf16_f32 v99, v102, v103
	v_cvt_pk_bf16_f32 v100, v108, v109
	v_cvt_pk_bf16_f32 v101, v110, v111
	s_waitcnt lgkmcnt(0)
	v_add_f32_e32 v96, v96, v97
	v_mov_b32_e32 v97, v96
	s_nop 1
	v_permlane32_swap_b32_e32 v97, v96
	global_store_dwordx4 v[122:123], v[98:101], off offset:256
	s_and_saveexec_b64 s[50:51], s[4:5]
	s_cbranch_execz .LBB0_393
	v_lshlrev_b64 v[98:99], 6, v[112:113]
	v_lshl_add_u64 v[98:99], s[18:19], 0, v[98:99]
	v_lshl_add_u64 v[98:99], s[48:49], 2, v[98:99]
	s_lshl_b32 s0, s64, 2
	v_lshl_add_u64 v[98:99], v[98:99], 0, s[0:1]
	s_waitcnt lgkmcnt(0)
	v_add_f32_e32 v96, v96, v97
	global_store_dword v[98:99], v96, off
.LBB0_393:
	s_or_b64 exec, exec, s[50:51]
	v_or_b32_e32 v96, 32, v150
	s_waitcnt lgkmcnt(0)
	v_ashrrev_i32_e32 v97, 31, v96
	v_lshlrev_b64 v[98:99], 11, v[96:97]
	v_lshl_add_u64 v[98:99], s[14:15], 0, v[98:99]
	v_lshl_add_u64 v[102:103], v[148:149], 1, v[98:99]
	s_mov_b64 s[100:101], 0x48000
	v_lshl_add_u64 v[230:231], v[232:233], 0, s[100:101]
	global_load_dwordx4 v[196:199], v[230:231], off
	global_load_dwordx4 v[200:203], v[230:231], off offset:256
	s_waitcnt vmcnt(11)
	v_lshlrev_b32_e32 v104, 16, v204
	v_and_b32_e32 v98, 0xffff0000, v204
	v_lshlrev_b32_e32 v105, 16, v205
	v_and_b32_e32 v99, 0xffff0000, v205
	v_lshlrev_b32_e32 v106, 16, v206
	v_and_b32_e32 v100, 0xffff0000, v206
	v_lshlrev_b32_e32 v107, 16, v207
	v_and_b32_e32 v101, 0xffff0000, v207
	v_add_f32_e32 v104, v92, v104
	v_add_f32_e32 v98, v93, v98
	v_add_f32_e32 v105, v94, v105
	v_add_f32_e32 v99, v95, v99
	v_add_f32_e32 v106, v88, v106
	v_add_f32_e32 v100, v89, v100
	v_add_f32_e32 v107, v90, v107
	v_add_f32_e32 v101, v91, v101
	v_cvt_pk_bf16_f32 v88, v104, v98
	v_cvt_pk_bf16_f32 v89, v105, v99
	v_cvt_pk_bf16_f32 v90, v106, v100
	v_cvt_pk_bf16_f32 v91, v107, v101
	v_mul_f32_e32 v98, v98, v98
	v_mul_f32_e32 v99, v99, v99
	v_mul_f32_e32 v100, v100, v100
	v_mul_f32_e32 v101, v101, v101
	v_fmac_f32_e32 v98, v104, v104
	v_fmac_f32_e32 v99, v105, v105
	v_fmac_f32_e32 v100, v106, v106
	v_fmac_f32_e32 v101, v107, v107
	v_add_f32_e32 v98, v98, v99
	v_add_f32_e32 v99, v100, v101
	v_add_f32_e32 v98, v98, v99
	global_store_dwordx4 v[102:103], v[88:91], off
	s_waitcnt vmcnt(11)
	v_lshlrev_b32_e32 v99, 16, v208
	v_and_b32_e32 v92, 0xffff0000, v208
	v_lshlrev_b32_e32 v100, 16, v209
	v_and_b32_e32 v93, 0xffff0000, v209
	v_lshlrev_b32_e32 v101, 16, v210
	v_and_b32_e32 v94, 0xffff0000, v210
	v_lshlrev_b32_e32 v104, 16, v211
	v_and_b32_e32 v95, 0xffff0000, v211
	v_add_f32_e32 v85, v85, v92
	v_add_f32_e32 v87, v87, v93
	v_add_f32_e32 v93, v81, v94
	v_add_f32_e32 v95, v83, v95
	v_add_f32_e32 v84, v84, v99
	v_add_f32_e32 v86, v86, v100
	v_add_f32_e32 v92, v80, v101
	v_add_f32_e32 v94, v82, v104
	v_mul_f32_e32 v80, v85, v85
	v_mul_f32_e32 v81, v87, v87
	v_mul_f32_e32 v82, v93, v93
	v_mul_f32_e32 v83, v95, v95
	v_fmac_f32_e32 v80, v84, v84
	v_fmac_f32_e32 v81, v86, v86
	v_fmac_f32_e32 v82, v92, v92
	v_fmac_f32_e32 v83, v94, v94
	v_add_f32_e32 v80, v80, v81
	v_add_f32_e32 v81, v82, v83
	v_add_f32_e32 v80, v80, v81
	v_add_f32_e32 v80, v98, v80
	v_mov_b32_e32 v81, v80
	s_nop 1
	v_permlane16_swap_b32_e32 v81, v80
	v_cvt_pk_bf16_f32 v82, v84, v85
	v_cvt_pk_bf16_f32 v83, v86, v87
	v_cvt_pk_bf16_f32 v84, v92, v93
	v_cvt_pk_bf16_f32 v85, v94, v95
	s_waitcnt lgkmcnt(0)
	v_add_f32_e32 v80, v80, v81
	v_mov_b32_e32 v81, v80
	s_nop 1
	v_permlane32_swap_b32_e32 v81, v80
	global_store_dwordx4 v[102:103], v[82:85], off offset:256
	s_and_saveexec_b64 s[50:51], s[4:5]
	s_cbranch_execz .LBB0_395
	v_lshlrev_b64 v[82:83], 6, v[96:97]
	v_lshl_add_u64 v[82:83], s[18:19], 0, v[82:83]
	v_lshl_add_u64 v[82:83], s[48:49], 2, v[82:83]
	s_lshl_b32 s0, s64, 2
	v_lshl_add_u64 v[82:83], v[82:83], 0, s[0:1]
	s_waitcnt lgkmcnt(0)
	v_add_f32_e32 v80, v80, v81
	global_store_dword v[82:83], v80, off
.LBB0_395:
	s_or_b64 exec, exec, s[50:51]
	v_or_b32_e32 v80, 48, v150
	s_waitcnt lgkmcnt(0)
	v_ashrrev_i32_e32 v81, 31, v80
	v_lshlrev_b64 v[82:83], 11, v[80:81]
	v_lshl_add_u64 v[82:83], s[14:15], 0, v[82:83]
	v_lshl_add_u64 v[86:87], v[148:149], 1, v[82:83]
	s_mov_b64 s[100:101], 0x50000
	v_lshl_add_u64 v[230:231], v[232:233], 0, s[100:101]
	global_load_dwordx4 v[204:207], v[230:231], off
	global_load_dwordx4 v[208:211], v[230:231], off offset:256
	s_waitcnt vmcnt(13)
	v_lshlrev_b32_e32 v88, 16, v212
	v_and_b32_e32 v82, 0xffff0000, v212
	v_lshlrev_b32_e32 v89, 16, v213
	v_and_b32_e32 v83, 0xffff0000, v213
	v_lshlrev_b32_e32 v90, 16, v214
	v_and_b32_e32 v84, 0xffff0000, v214
	v_lshlrev_b32_e32 v91, 16, v215
	v_and_b32_e32 v85, 0xffff0000, v215
	v_add_f32_e32 v88, v76, v88
	v_add_f32_e32 v82, v77, v82
	v_add_f32_e32 v89, v78, v89
	v_add_f32_e32 v83, v79, v83
	v_add_f32_e32 v90, v72, v90
	v_add_f32_e32 v84, v73, v84
	v_add_f32_e32 v91, v74, v91
	v_add_f32_e32 v85, v75, v85
	v_cvt_pk_bf16_f32 v72, v88, v82
	v_cvt_pk_bf16_f32 v73, v89, v83
	v_cvt_pk_bf16_f32 v74, v90, v84
	v_cvt_pk_bf16_f32 v75, v91, v85
	v_mul_f32_e32 v82, v82, v82
	v_mul_f32_e32 v83, v83, v83
	v_mul_f32_e32 v84, v84, v84
	v_mul_f32_e32 v85, v85, v85
	v_fmac_f32_e32 v82, v88, v88
	v_fmac_f32_e32 v83, v89, v89
	v_fmac_f32_e32 v84, v90, v90
	v_fmac_f32_e32 v85, v91, v91
	v_add_f32_e32 v82, v82, v83
	v_add_f32_e32 v83, v84, v85
	v_add_f32_e32 v82, v82, v83
	global_store_dwordx4 v[86:87], v[72:75], off
	s_waitcnt vmcnt(13)
	v_lshlrev_b32_e32 v83, 16, v216
	v_and_b32_e32 v76, 0xffff0000, v216
	v_lshlrev_b32_e32 v84, 16, v217
	v_and_b32_e32 v77, 0xffff0000, v217
	v_lshlrev_b32_e32 v85, 16, v218
	v_and_b32_e32 v78, 0xffff0000, v218
	v_lshlrev_b32_e32 v88, 16, v219
	v_and_b32_e32 v79, 0xffff0000, v219
	v_add_f32_e32 v69, v69, v76
	v_add_f32_e32 v71, v71, v77
	v_add_f32_e32 v77, v65, v78
	v_add_f32_e32 v79, v67, v79
	v_add_f32_e32 v68, v68, v83
	v_add_f32_e32 v70, v70, v84
	v_add_f32_e32 v76, v64, v85
	v_add_f32_e32 v78, v66, v88
	v_mul_f32_e32 v64, v69, v69
	v_mul_f32_e32 v65, v71, v71
	v_mul_f32_e32 v66, v77, v77
	v_mul_f32_e32 v67, v79, v79
	v_fmac_f32_e32 v64, v68, v68
	v_fmac_f32_e32 v65, v70, v70
	v_fmac_f32_e32 v66, v76, v76
	v_fmac_f32_e32 v67, v78, v78
	v_add_f32_e32 v64, v64, v65
	v_add_f32_e32 v65, v66, v67
	v_add_f32_e32 v64, v64, v65
	v_add_f32_e32 v64, v82, v64
	v_mov_b32_e32 v65, v64
	s_nop 1
	v_permlane16_swap_b32_e32 v65, v64
	v_cvt_pk_bf16_f32 v66, v68, v69
	v_cvt_pk_bf16_f32 v67, v70, v71
	v_cvt_pk_bf16_f32 v68, v76, v77
	v_cvt_pk_bf16_f32 v69, v78, v79
	s_waitcnt lgkmcnt(0)
	v_add_f32_e32 v64, v64, v65
	v_mov_b32_e32 v65, v64
	s_nop 1
	v_permlane32_swap_b32_e32 v65, v64
	global_store_dwordx4 v[86:87], v[66:69], off offset:256
	s_and_saveexec_b64 s[50:51], s[4:5]
	s_cbranch_execz .LBB0_397
	v_lshlrev_b64 v[66:67], 6, v[80:81]
	v_lshl_add_u64 v[66:67], s[18:19], 0, v[66:67]
	v_lshl_add_u64 v[66:67], s[48:49], 2, v[66:67]
	s_lshl_b32 s0, s64, 2
	v_lshl_add_u64 v[66:67], v[66:67], 0, s[0:1]
	s_waitcnt lgkmcnt(0)
	v_add_f32_e32 v64, v64, v65
	global_store_dword v[66:67], v64, off
.LBB0_397:
	s_or_b64 exec, exec, s[50:51]
	v_add_u32_e32 v64, 0x80, v150
	s_waitcnt lgkmcnt(0)
	v_ashrrev_i32_e32 v65, 31, v64
	v_lshlrev_b64 v[66:67], 11, v[64:65]
	v_lshl_add_u64 v[66:67], s[14:15], 0, v[66:67]
	v_lshl_add_u64 v[70:71], v[148:149], 1, v[66:67]
	s_mov_b64 s[100:101], 0x58000
	v_lshl_add_u64 v[230:231], v[232:233], 0, s[100:101]
	global_load_dwordx4 v[212:215], v[230:231], off
	global_load_dwordx4 v[216:219], v[230:231], off offset:256
	s_waitcnt vmcnt(13)
	v_lshlrev_b32_e32 v72, 16, v188
	v_and_b32_e32 v66, 0xffff0000, v188
	v_lshlrev_b32_e32 v73, 16, v189
	v_and_b32_e32 v67, 0xffff0000, v189
	v_lshlrev_b32_e32 v74, 16, v190
	v_and_b32_e32 v68, 0xffff0000, v190
	v_lshlrev_b32_e32 v75, 16, v191
	v_and_b32_e32 v69, 0xffff0000, v191
	v_add_f32_e32 v72, v60, v72
	v_add_f32_e32 v66, v61, v66
	v_add_f32_e32 v73, v62, v73
	v_add_f32_e32 v67, v63, v67
	v_add_f32_e32 v74, v56, v74
	v_add_f32_e32 v68, v57, v68
	v_add_f32_e32 v75, v58, v75
	v_add_f32_e32 v69, v59, v69
	v_cvt_pk_bf16_f32 v56, v72, v66
	v_cvt_pk_bf16_f32 v57, v73, v67
	v_cvt_pk_bf16_f32 v58, v74, v68
	v_cvt_pk_bf16_f32 v59, v75, v69
	v_mul_f32_e32 v66, v66, v66
	v_mul_f32_e32 v67, v67, v67
	v_mul_f32_e32 v68, v68, v68
	v_mul_f32_e32 v69, v69, v69
	v_fmac_f32_e32 v66, v72, v72
	v_fmac_f32_e32 v67, v73, v73
	v_fmac_f32_e32 v68, v74, v74
	v_fmac_f32_e32 v69, v75, v75
	v_add_f32_e32 v66, v66, v67
	v_add_f32_e32 v67, v68, v69
	v_add_f32_e32 v66, v66, v67
	global_store_dwordx4 v[70:71], v[56:59], off
	s_waitcnt vmcnt(13)
	v_lshlrev_b32_e32 v67, 16, v192
	v_and_b32_e32 v60, 0xffff0000, v192
	v_lshlrev_b32_e32 v68, 16, v193
	v_and_b32_e32 v61, 0xffff0000, v193
	v_lshlrev_b32_e32 v69, 16, v194
	v_and_b32_e32 v62, 0xffff0000, v194
	v_lshlrev_b32_e32 v72, 16, v195
	v_and_b32_e32 v63, 0xffff0000, v195
	v_add_f32_e32 v53, v53, v60
	v_add_f32_e32 v55, v55, v61
	v_add_f32_e32 v61, v49, v62
	v_add_f32_e32 v63, v51, v63
	v_add_f32_e32 v52, v52, v67
	v_add_f32_e32 v54, v54, v68
	v_add_f32_e32 v60, v48, v69
	v_add_f32_e32 v62, v50, v72
	v_mul_f32_e32 v48, v53, v53
	v_mul_f32_e32 v49, v55, v55
	v_mul_f32_e32 v50, v61, v61
	v_mul_f32_e32 v51, v63, v63
	v_fmac_f32_e32 v48, v52, v52
	v_fmac_f32_e32 v49, v54, v54
	v_fmac_f32_e32 v50, v60, v60
	v_fmac_f32_e32 v51, v62, v62
	v_add_f32_e32 v48, v48, v49
	v_add_f32_e32 v49, v50, v51
	v_add_f32_e32 v48, v48, v49
	v_add_f32_e32 v48, v66, v48
	v_mov_b32_e32 v49, v48
	s_nop 1
	v_permlane16_swap_b32_e32 v49, v48
	v_cvt_pk_bf16_f32 v50, v52, v53
	v_cvt_pk_bf16_f32 v51, v54, v55
	v_cvt_pk_bf16_f32 v52, v60, v61
	v_cvt_pk_bf16_f32 v53, v62, v63
	s_waitcnt lgkmcnt(0)
	v_add_f32_e32 v48, v48, v49
	v_mov_b32_e32 v49, v48
	s_nop 1
	v_permlane32_swap_b32_e32 v49, v48
	global_store_dwordx4 v[70:71], v[50:53], off offset:256
	s_and_saveexec_b64 s[50:51], s[4:5]
	s_cbranch_execz .LBB0_399
	v_lshlrev_b64 v[50:51], 6, v[64:65]
	v_lshl_add_u64 v[50:51], s[18:19], 0, v[50:51]
	v_lshl_add_u64 v[50:51], s[48:49], 2, v[50:51]
	s_lshl_b32 s0, s64, 2
	v_lshl_add_u64 v[50:51], v[50:51], 0, s[0:1]
	s_waitcnt lgkmcnt(0)
	v_add_f32_e32 v48, v48, v49
	global_store_dword v[50:51], v48, off
.LBB0_399:
	s_or_b64 exec, exec, s[50:51]
	v_add_u32_e32 v48, 0x90, v150
	s_waitcnt lgkmcnt(0)
	v_ashrrev_i32_e32 v49, 31, v48
	v_lshlrev_b64 v[50:51], 11, v[48:49]
	v_lshl_add_u64 v[50:51], s[14:15], 0, v[50:51]
	v_lshl_add_u64 v[54:55], v[148:149], 1, v[50:51]
	s_waitcnt vmcnt(11)
	v_lshlrev_b32_e32 v56, 16, v196
	v_and_b32_e32 v50, 0xffff0000, v196
	v_lshlrev_b32_e32 v57, 16, v197
	v_and_b32_e32 v51, 0xffff0000, v197
	v_lshlrev_b32_e32 v58, 16, v198
	v_and_b32_e32 v52, 0xffff0000, v198
	v_lshlrev_b32_e32 v59, 16, v199
	v_and_b32_e32 v53, 0xffff0000, v199
	v_add_f32_e32 v56, v44, v56
	v_add_f32_e32 v50, v45, v50
	v_add_f32_e32 v57, v46, v57
	v_add_f32_e32 v51, v47, v51
	v_add_f32_e32 v58, v40, v58
	v_add_f32_e32 v52, v41, v52
	v_add_f32_e32 v59, v42, v59
	v_add_f32_e32 v53, v43, v53
	v_cvt_pk_bf16_f32 v40, v56, v50
	v_cvt_pk_bf16_f32 v41, v57, v51
	v_cvt_pk_bf16_f32 v42, v58, v52
	v_cvt_pk_bf16_f32 v43, v59, v53
	v_mul_f32_e32 v50, v50, v50
	v_mul_f32_e32 v51, v51, v51
	v_mul_f32_e32 v52, v52, v52
	v_mul_f32_e32 v53, v53, v53
	v_fmac_f32_e32 v50, v56, v56
	v_fmac_f32_e32 v51, v57, v57
	v_fmac_f32_e32 v52, v58, v58
	v_fmac_f32_e32 v53, v59, v59
	v_add_f32_e32 v50, v50, v51
	v_add_f32_e32 v51, v52, v53
	v_add_f32_e32 v50, v50, v51
	global_store_dwordx4 v[54:55], v[40:43], off
	s_waitcnt vmcnt(11)
	v_lshlrev_b32_e32 v51, 16, v200
	v_and_b32_e32 v44, 0xffff0000, v200
	v_lshlrev_b32_e32 v52, 16, v201
	v_and_b32_e32 v45, 0xffff0000, v201
	v_lshlrev_b32_e32 v53, 16, v202
	v_and_b32_e32 v46, 0xffff0000, v202
	v_lshlrev_b32_e32 v56, 16, v203
	v_and_b32_e32 v47, 0xffff0000, v203
	v_add_f32_e32 v37, v37, v44
	v_add_f32_e32 v39, v39, v45
	v_add_f32_e32 v45, v33, v46
	v_add_f32_e32 v47, v35, v47
	v_add_f32_e32 v36, v36, v51
	v_add_f32_e32 v38, v38, v52
	v_add_f32_e32 v44, v32, v53
	v_add_f32_e32 v46, v34, v56
	v_mul_f32_e32 v32, v37, v37
	v_mul_f32_e32 v33, v39, v39
	v_mul_f32_e32 v34, v45, v45
	v_mul_f32_e32 v35, v47, v47
	v_fmac_f32_e32 v32, v36, v36
	v_fmac_f32_e32 v33, v38, v38
	v_fmac_f32_e32 v34, v44, v44
	v_fmac_f32_e32 v35, v46, v46
	v_add_f32_e32 v32, v32, v33
	v_add_f32_e32 v33, v34, v35
	v_add_f32_e32 v32, v32, v33
	v_add_f32_e32 v32, v50, v32
	v_mov_b32_e32 v33, v32
	s_nop 1
	v_permlane16_swap_b32_e32 v33, v32
	v_cvt_pk_bf16_f32 v34, v36, v37
	v_cvt_pk_bf16_f32 v35, v38, v39
	v_cvt_pk_bf16_f32 v36, v44, v45
	v_cvt_pk_bf16_f32 v37, v46, v47
	s_waitcnt lgkmcnt(0)
	v_add_f32_e32 v32, v32, v33
	v_mov_b32_e32 v33, v32
	s_nop 1
	v_permlane32_swap_b32_e32 v33, v32
	global_store_dwordx4 v[54:55], v[34:37], off offset:256
	s_and_saveexec_b64 s[50:51], s[4:5]
	s_cbranch_execz .LBB0_401
	v_lshlrev_b64 v[34:35], 6, v[48:49]
	v_lshl_add_u64 v[34:35], s[18:19], 0, v[34:35]
	v_lshl_add_u64 v[34:35], s[48:49], 2, v[34:35]
	s_lshl_b32 s0, s64, 2
	v_lshl_add_u64 v[34:35], v[34:35], 0, s[0:1]
	s_waitcnt lgkmcnt(0)
	v_add_f32_e32 v32, v32, v33
	global_store_dword v[34:35], v32, off
.LBB0_401:
	s_or_b64 exec, exec, s[50:51]
	v_add_u32_e32 v32, 0xa0, v150
	s_waitcnt lgkmcnt(0)
	v_ashrrev_i32_e32 v33, 31, v32
	v_lshlrev_b64 v[34:35], 11, v[32:33]
	v_lshl_add_u64 v[34:35], s[14:15], 0, v[34:35]
	v_lshl_add_u64 v[38:39], v[148:149], 1, v[34:35]
	s_waitcnt vmcnt(9)
	v_lshlrev_b32_e32 v40, 16, v204
	v_and_b32_e32 v34, 0xffff0000, v204
	v_lshlrev_b32_e32 v41, 16, v205
	v_and_b32_e32 v35, 0xffff0000, v205
	v_lshlrev_b32_e32 v42, 16, v206
	v_and_b32_e32 v36, 0xffff0000, v206
	v_lshlrev_b32_e32 v43, 16, v207
	v_and_b32_e32 v37, 0xffff0000, v207
	v_add_f32_e32 v40, v28, v40
	v_add_f32_e32 v34, v29, v34
	v_add_f32_e32 v41, v30, v41
	v_add_f32_e32 v35, v31, v35
	v_add_f32_e32 v42, v24, v42
	v_add_f32_e32 v36, v25, v36
	v_add_f32_e32 v43, v26, v43
	v_add_f32_e32 v37, v27, v37
	v_cvt_pk_bf16_f32 v24, v40, v34
	v_cvt_pk_bf16_f32 v25, v41, v35
	v_cvt_pk_bf16_f32 v26, v42, v36
	v_cvt_pk_bf16_f32 v27, v43, v37
	v_mul_f32_e32 v34, v34, v34
	v_mul_f32_e32 v35, v35, v35
	v_mul_f32_e32 v36, v36, v36
	v_mul_f32_e32 v37, v37, v37
	v_fmac_f32_e32 v34, v40, v40
	v_fmac_f32_e32 v35, v41, v41
	v_fmac_f32_e32 v36, v42, v42
	v_fmac_f32_e32 v37, v43, v43
	v_add_f32_e32 v34, v34, v35
	v_add_f32_e32 v35, v36, v37
	v_add_f32_e32 v34, v34, v35
	global_store_dwordx4 v[38:39], v[24:27], off
	s_waitcnt vmcnt(9)
	v_lshlrev_b32_e32 v35, 16, v208
	v_and_b32_e32 v28, 0xffff0000, v208
	v_lshlrev_b32_e32 v36, 16, v209
	v_and_b32_e32 v29, 0xffff0000, v209
	v_lshlrev_b32_e32 v37, 16, v210
	v_and_b32_e32 v30, 0xffff0000, v210
	v_lshlrev_b32_e32 v40, 16, v211
	v_and_b32_e32 v31, 0xffff0000, v211
	v_add_f32_e32 v21, v21, v28
	v_add_f32_e32 v23, v23, v29
	v_add_f32_e32 v29, v17, v30
	v_add_f32_e32 v31, v19, v31
	v_add_f32_e32 v20, v20, v35
	v_add_f32_e32 v22, v22, v36
	v_add_f32_e32 v28, v16, v37
	v_add_f32_e32 v30, v18, v40
	v_mul_f32_e32 v16, v21, v21
	v_mul_f32_e32 v17, v23, v23
	v_mul_f32_e32 v18, v29, v29
	v_mul_f32_e32 v19, v31, v31
	v_fmac_f32_e32 v16, v20, v20
	v_fmac_f32_e32 v17, v22, v22
	v_fmac_f32_e32 v18, v28, v28
	v_fmac_f32_e32 v19, v30, v30
	v_add_f32_e32 v16, v16, v17
	v_add_f32_e32 v17, v18, v19
	v_add_f32_e32 v16, v16, v17
	v_add_f32_e32 v16, v34, v16
	v_mov_b32_e32 v17, v16
	s_nop 1
	v_permlane16_swap_b32_e32 v17, v16
	v_cvt_pk_bf16_f32 v18, v20, v21
	v_cvt_pk_bf16_f32 v19, v22, v23
	v_cvt_pk_bf16_f32 v20, v28, v29
	v_cvt_pk_bf16_f32 v21, v30, v31
	s_waitcnt lgkmcnt(0)
	v_add_f32_e32 v16, v16, v17
	v_mov_b32_e32 v17, v16
	s_nop 1
	v_permlane32_swap_b32_e32 v17, v16
	global_store_dwordx4 v[38:39], v[18:21], off offset:256
	s_and_saveexec_b64 s[50:51], s[4:5]
	s_cbranch_execz .LBB0_403
	v_lshlrev_b64 v[18:19], 6, v[32:33]
	v_lshl_add_u64 v[18:19], s[18:19], 0, v[18:19]
	v_lshl_add_u64 v[18:19], s[48:49], 2, v[18:19]
	s_lshl_b32 s0, s64, 2
	v_lshl_add_u64 v[18:19], v[18:19], 0, s[0:1]
	s_waitcnt lgkmcnt(0)
	v_add_f32_e32 v16, v16, v17
	global_store_dword v[18:19], v16, off
.LBB0_403:
	s_or_b64 exec, exec, s[50:51]
	v_add_u32_e32 v16, 0xb0, v150
	s_waitcnt lgkmcnt(0)
	v_ashrrev_i32_e32 v17, 31, v16
	v_lshlrev_b64 v[18:19], 11, v[16:17]
	v_lshl_add_u64 v[18:19], s[14:15], 0, v[18:19]
	v_lshl_add_u64 v[22:23], v[148:149], 1, v[18:19]
	s_waitcnt vmcnt(7)
	v_lshlrev_b32_e32 v24, 16, v212
	v_and_b32_e32 v18, 0xffff0000, v212
	v_lshlrev_b32_e32 v25, 16, v213
	v_and_b32_e32 v19, 0xffff0000, v213
	v_lshlrev_b32_e32 v26, 16, v214
	v_and_b32_e32 v20, 0xffff0000, v214
	v_lshlrev_b32_e32 v27, 16, v215
	v_and_b32_e32 v21, 0xffff0000, v215
	v_add_f32_e32 v24, v12, v24
	v_add_f32_e32 v18, v13, v18
	v_add_f32_e32 v25, v14, v25
	v_add_f32_e32 v19, v15, v19
	v_add_f32_e32 v26, v8, v26
	v_add_f32_e32 v20, v9, v20
	v_add_f32_e32 v27, v10, v27
	v_add_f32_e32 v21, v11, v21
	v_cvt_pk_bf16_f32 v8, v24, v18
	v_cvt_pk_bf16_f32 v9, v25, v19
	v_cvt_pk_bf16_f32 v10, v26, v20
	v_cvt_pk_bf16_f32 v11, v27, v21
	v_mul_f32_e32 v18, v18, v18
	v_mul_f32_e32 v19, v19, v19
	v_mul_f32_e32 v20, v20, v20
	v_mul_f32_e32 v21, v21, v21
	v_fmac_f32_e32 v18, v24, v24
	v_fmac_f32_e32 v19, v25, v25
	v_fmac_f32_e32 v20, v26, v26
	v_fmac_f32_e32 v21, v27, v27
	v_add_f32_e32 v18, v18, v19
	v_add_f32_e32 v19, v20, v21
	v_add_f32_e32 v18, v18, v19
	global_store_dwordx4 v[22:23], v[8:11], off
	s_waitcnt vmcnt(7)
	v_lshlrev_b32_e32 v19, 16, v216
	v_and_b32_e32 v12, 0xffff0000, v216
	v_lshlrev_b32_e32 v20, 16, v217
	v_and_b32_e32 v13, 0xffff0000, v217
	v_lshlrev_b32_e32 v21, 16, v218
	v_and_b32_e32 v14, 0xffff0000, v218
	v_lshlrev_b32_e32 v24, 16, v219
	v_and_b32_e32 v15, 0xffff0000, v219
	v_add_f32_e32 v5, v5, v12
	v_add_f32_e32 v7, v7, v13
	v_add_f32_e32 v13, v1, v14
	v_add_f32_e32 v15, v3, v15
	v_add_f32_e32 v4, v4, v19
	v_add_f32_e32 v6, v6, v20
	v_add_f32_e32 v12, v0, v21
	v_add_f32_e32 v14, v2, v24
	v_mul_f32_e32 v0, v5, v5
	v_mul_f32_e32 v1, v7, v7
	v_mul_f32_e32 v2, v13, v13
	v_mul_f32_e32 v3, v15, v15
	v_fmac_f32_e32 v0, v4, v4
	v_fmac_f32_e32 v1, v6, v6
	v_fmac_f32_e32 v2, v12, v12
	v_fmac_f32_e32 v3, v14, v14
	v_add_f32_e32 v0, v0, v1
	v_add_f32_e32 v1, v2, v3
	v_add_f32_e32 v0, v0, v1
	v_add_f32_e32 v0, v18, v0
	v_mov_b32_e32 v1, v0
	s_nop 1
	v_permlane16_swap_b32_e32 v1, v0
	v_cvt_pk_bf16_f32 v2, v4, v5
	v_cvt_pk_bf16_f32 v3, v6, v7
	v_cvt_pk_bf16_f32 v4, v12, v13
	v_cvt_pk_bf16_f32 v5, v14, v15
	s_waitcnt lgkmcnt(0)
	v_add_f32_e32 v0, v0, v1
	v_mov_b32_e32 v1, v0
	s_nop 1
	v_permlane32_swap_b32_e32 v1, v0
	global_store_dwordx4 v[22:23], v[2:5], off offset:256
	s_and_saveexec_b64 s[50:51], s[4:5]
	s_cbranch_execz .LBB0_405
	v_lshlrev_b64 v[2:3], 6, v[16:17]
	v_lshl_add_u64 v[2:3], s[18:19], 0, v[2:3]
	v_lshl_add_u64 v[2:3], s[48:49], 2, v[2:3]
	s_lshl_b32 s0, s64, 2
	v_lshl_add_u64 v[2:3], v[2:3], 0, s[0:1]
	s_waitcnt lgkmcnt(0)
	v_add_f32_e32 v0, v0, v1
	global_store_dword v[2:3], v0, off

.LBB0_565:
	v_lshl_add_u32 v150, s12, 8, v131
	v_ashrrev_i32_e32 v151, 31, v150
	v_lshl_or_b32 v148, s8, 8, v153
	v_lshlrev_b64 v[160:161], 11, v[150:151]
	v_ashrrev_i32_e32 v149, 31, v148
	v_lshl_add_u64 v[160:161], s[14:15], 0, v[160:161]
	v_lshl_add_u64 v[164:165], v[148:149], 1, v[160:161]
	v_mov_b32_e32 v232, v164
	v_mov_b32_e32 v233, v165
	global_load_dwordx4 v[188:191], v[232:233], off
	global_load_dwordx4 v[192:195], v[232:233], off offset:256
	s_mov_b64 s[100:101], 0x8000
	v_lshl_add_u64 v[230:231], v[232:233], 0, s[100:101]
	global_load_dwordx4 v[196:199], v[230:231], off
	global_load_dwordx4 v[200:203], v[230:231], off offset:256
	s_mov_b64 s[100:101], 0x10000
	v_lshl_add_u64 v[230:231], v[232:233], 0, s[100:101]
	global_load_dwordx4 v[204:207], v[230:231], off
	global_load_dwordx4 v[208:211], v[230:231], off offset:256
	s_mov_b64 s[100:101], 0x18000
	v_lshl_add_u64 v[230:231], v[232:233], 0, s[100:101]
	global_load_dwordx4 v[212:215], v[230:231], off
	global_load_dwordx4 v[216:219], v[230:231], off offset:256
	v_and_b32_e32 v170, 64, v158
	v_add_u32_e32 v170, 64, v170
	v_xor_b32_e32 v171, 32, v158
	s_lshl_b32 s40, s8, 2
	s_ashr_i32 s41, s40, 31
	s_waitcnt vmcnt(7)
	v_lshlrev_b32_e32 v159, 16, v188
	v_and_b32_e32 v160, 0xffff0000, v188
	v_lshlrev_b32_e32 v166, 16, v189
	v_and_b32_e32 v161, 0xffff0000, v189
	v_lshlrev_b32_e32 v167, 16, v190
	v_and_b32_e32 v162, 0xffff0000, v190
	v_lshlrev_b32_e32 v168, 16, v191
	v_and_b32_e32 v163, 0xffff0000, v191
	v_add_f32_e32 v159, v124, v159
	v_add_f32_e32 v169, v125, v160
	v_add_f32_e32 v126, v126, v166
	v_add_f32_e32 v127, v127, v161
	v_add_f32_e32 v166, v120, v167
	v_add_f32_e32 v121, v121, v162
	v_add_f32_e32 v167, v122, v168
	v_add_f32_e32 v168, v123, v163
	v_cvt_pk_bf16_f32 v122, v159, v169
	v_cvt_pk_bf16_f32 v123, v126, v127
	v_cvt_pk_bf16_f32 v124, v166, v121
	v_cvt_pk_bf16_f32 v125, v167, v168
	v_mul_f32_e32 v169, v169, v169
	v_mul_f32_e32 v127, v127, v127
	v_mul_f32_e32 v121, v121, v121
	v_mul_f32_e32 v168, v168, v168
	v_fmac_f32_e32 v169, v159, v159
	v_fmac_f32_e32 v127, v126, v126
	v_fmac_f32_e32 v121, v166, v166
	v_fmac_f32_e32 v168, v167, v167
	v_add_f32_e32 v126, v169, v127
	v_add_f32_e32 v121, v121, v168
	v_add_f32_e32 v121, v126, v121
	v_xor_b32_e32 v120, 16, v158
	v_cmp_lt_i32_e32 vcc, v120, v170
	global_store_dwordx4 v[164:165], v[122:125], off
	s_waitcnt vmcnt(7)
	v_lshlrev_b32_e32 v126, 16, v192
	v_and_b32_e32 v127, 0xffff0000, v192
	v_lshlrev_b32_e32 v159, 16, v193
	v_and_b32_e32 v160, 0xffff0000, v193
	v_lshlrev_b32_e32 v161, 16, v194
	v_and_b32_e32 v162, 0xffff0000, v194
	v_lshlrev_b32_e32 v166, 16, v195
	v_and_b32_e32 v163, 0xffff0000, v195
	v_add_f32_e32 v117, v117, v127
	v_add_f32_e32 v119, v119, v160
	v_add_f32_e32 v127, v113, v162
	v_add_f32_e32 v115, v115, v163
	v_add_f32_e32 v116, v116, v126
	v_add_f32_e32 v118, v118, v159
	v_add_f32_e32 v126, v112, v161
	v_add_f32_e32 v159, v114, v166
	v_mul_f32_e32 v112, v117, v117
	v_mul_f32_e32 v113, v119, v119
	v_mul_f32_e32 v114, v127, v127
	v_mul_f32_e32 v160, v115, v115
	v_fmac_f32_e32 v112, v116, v116
	v_fmac_f32_e32 v113, v118, v118
	v_fmac_f32_e32 v114, v126, v126
	v_fmac_f32_e32 v160, v159, v159
	v_add_f32_e32 v112, v112, v113
	v_add_f32_e32 v113, v114, v160
	v_cndmask_b32_e32 v120, v158, v120, vcc
	v_add_f32_e32 v112, v112, v113
	v_lshlrev_b32_e32 v120, 2, v120
	v_add_f32_e32 v112, v121, v112
	v_mov_b32_e32 v113, v112
	s_nop 1
	v_permlane16_swap_b32_e32 v113, v112
	v_cmp_lt_i32_e32 vcc, v171, v170
	v_cvt_pk_bf16_f32 v116, v116, v117
	v_cvt_pk_bf16_f32 v117, v118, v119
	v_cvt_pk_bf16_f32 v118, v126, v127
	s_waitcnt lgkmcnt(0)
	v_add_f32_e32 v112, v112, v113
	v_cvt_pk_bf16_f32 v119, v159, v115
	v_cndmask_b32_e32 v114, v158, v171, vcc
	v_lshlrev_b32_e32 v114, 2, v114
	v_mov_b32_e32 v113, v112
	s_nop 1
	v_permlane32_swap_b32_e32 v113, v112
	global_store_dwordx4 v[164:165], v[116:119], off offset:256
	s_and_saveexec_b64 s[42:43], s[4:5]
	s_cbranch_execz .LBB0_567
	v_lshlrev_b64 v[116:117], 6, v[150:151]
	v_lshl_add_u64 v[116:117], s[18:19], 0, v[116:117]
	v_lshl_add_u64 v[116:117], s[40:41], 2, v[116:117]
	s_lshl_b32 s8, s56, 2
	v_lshl_add_u64 v[116:117], v[116:117], 0, s[8:9]
	s_waitcnt lgkmcnt(0)
	v_add_f32_e32 v112, v112, v113
	global_store_dword v[116:117], v112, off
.LBB0_567:
	s_or_b64 exec, exec, s[42:43]
	v_or_b32_e32 v112, 16, v150
	s_waitcnt lgkmcnt(0)
	v_ashrrev_i32_e32 v113, 31, v112
	v_lshlrev_b64 v[116:117], 11, v[112:113]
	v_lshl_add_u64 v[116:117], s[14:15], 0, v[116:117]
	v_lshl_add_u64 v[122:123], v[148:149], 1, v[116:117]
	s_mov_b64 s[100:101], 0x40000
	v_lshl_add_u64 v[230:231], v[232:233], 0, s[100:101]
	global_load_dwordx4 v[188:191], v[230:231], off
	global_load_dwordx4 v[192:195], v[230:231], off offset:256
	s_waitcnt vmcnt(9)
	v_lshlrev_b32_e32 v115, 16, v196
	v_and_b32_e32 v116, 0xffff0000, v196
	v_lshlrev_b32_e32 v121, 16, v197
	v_and_b32_e32 v117, 0xffff0000, v197
	v_lshlrev_b32_e32 v124, 16, v198
	v_and_b32_e32 v118, 0xffff0000, v198
	v_lshlrev_b32_e32 v125, 16, v199
	v_and_b32_e32 v119, 0xffff0000, v199
	v_add_f32_e32 v115, v108, v115
	v_add_f32_e32 v116, v109, v116
	v_add_f32_e32 v121, v110, v121
	v_add_f32_e32 v117, v111, v117
	v_add_f32_e32 v124, v104, v124
	v_add_f32_e32 v118, v105, v118
	v_add_f32_e32 v125, v106, v125
	v_add_f32_e32 v119, v107, v119
	v_cvt_pk_bf16_f32 v104, v115, v116
	v_cvt_pk_bf16_f32 v105, v121, v117
	v_cvt_pk_bf16_f32 v106, v124, v118
	v_cvt_pk_bf16_f32 v107, v125, v119
	v_mul_f32_e32 v116, v116, v116
	v_mul_f32_e32 v117, v117, v117
	v_mul_f32_e32 v118, v118, v118
	v_mul_f32_e32 v119, v119, v119
	v_fmac_f32_e32 v116, v115, v115
	v_fmac_f32_e32 v117, v121, v121
	v_fmac_f32_e32 v118, v124, v124
	v_fmac_f32_e32 v119, v125, v125
	v_add_f32_e32 v115, v116, v117
	v_add_f32_e32 v116, v118, v119
	v_add_f32_e32 v115, v115, v116
	global_store_dwordx4 v[122:123], v[104:107], off
	s_waitcnt vmcnt(9)
	v_lshlrev_b32_e32 v116, 16, v200
	v_and_b32_e32 v108, 0xffff0000, v200
	v_lshlrev_b32_e32 v117, 16, v201
	v_and_b32_e32 v109, 0xffff0000, v201
	v_lshlrev_b32_e32 v118, 16, v202
	v_and_b32_e32 v110, 0xffff0000, v202
	v_lshlrev_b32_e32 v119, 16, v203
	v_and_b32_e32 v111, 0xffff0000, v203
	v_add_f32_e32 v101, v101, v108
	v_add_f32_e32 v103, v103, v109
	v_add_f32_e32 v109, v97, v110
	v_add_f32_e32 v111, v99, v111
	v_add_f32_e32 v100, v100, v116
	v_add_f32_e32 v102, v102, v117
	v_add_f32_e32 v108, v96, v118
	v_add_f32_e32 v110, v98, v119
	v_mul_f32_e32 v96, v101, v101
	v_mul_f32_e32 v97, v103, v103
	v_mul_f32_e32 v98, v109, v109
	v_mul_f32_e32 v99, v111, v111
	v_fmac_f32_e32 v96, v100, v100
	v_fmac_f32_e32 v97, v102, v102
	v_fmac_f32_e32 v98, v108, v108
	v_fmac_f32_e32 v99, v110, v110
	v_add_f32_e32 v96, v96, v97
	v_add_f32_e32 v97, v98, v99
	v_add_f32_e32 v96, v96, v97
	v_add_f32_e32 v96, v115, v96
	v_mov_b32_e32 v97, v96
	s_nop 1
	v_permlane16_swap_b32_e32 v97, v96
	v_cvt_pk_bf16_f32 v98, v100, v101
	v_cvt_pk_bf16_f32 v99, v102, v103
	v_cvt_pk_bf16_f32 v100, v108, v109
	v_cvt_pk_bf16_f32 v101, v110, v111
	s_waitcnt lgkmcnt(0)
	v_add_f32_e32 v96, v96, v97
	v_mov_b32_e32 v97, v96
	s_nop 1
	v_permlane32_swap_b32_e32 v97, v96
	global_store_dwordx4 v[122:123], v[98:101], off offset:256
	s_and_saveexec_b64 s[42:43], s[4:5]
	s_cbranch_execz .LBB0_569
	v_lshlrev_b64 v[98:99], 6, v[112:113]
	v_lshl_add_u64 v[98:99], s[18:19], 0, v[98:99]
	v_lshl_add_u64 v[98:99], s[40:41], 2, v[98:99]
	s_lshl_b32 s8, s56, 2
	v_lshl_add_u64 v[98:99], v[98:99], 0, s[8:9]
	s_waitcnt lgkmcnt(0)
	v_add_f32_e32 v96, v96, v97
	global_store_dword v[98:99], v96, off
.LBB0_569:
	s_or_b64 exec, exec, s[42:43]
	v_or_b32_e32 v96, 32, v150
	s_waitcnt lgkmcnt(0)
	v_ashrrev_i32_e32 v97, 31, v96
	v_lshlrev_b64 v[98:99], 11, v[96:97]
	v_lshl_add_u64 v[98:99], s[14:15], 0, v[98:99]
	v_lshl_add_u64 v[102:103], v[148:149], 1, v[98:99]
	s_mov_b64 s[100:101], 0x48000
	v_lshl_add_u64 v[230:231], v[232:233], 0, s[100:101]
	global_load_dwordx4 v[196:199], v[230:231], off
	global_load_dwordx4 v[200:203], v[230:231], off offset:256
	s_waitcnt vmcnt(11)
	v_lshlrev_b32_e32 v104, 16, v204
	v_and_b32_e32 v98, 0xffff0000, v204
	v_lshlrev_b32_e32 v105, 16, v205
	v_and_b32_e32 v99, 0xffff0000, v205
	v_lshlrev_b32_e32 v106, 16, v206
	v_and_b32_e32 v100, 0xffff0000, v206
	v_lshlrev_b32_e32 v107, 16, v207
	v_and_b32_e32 v101, 0xffff0000, v207
	v_add_f32_e32 v104, v92, v104
	v_add_f32_e32 v98, v93, v98
	v_add_f32_e32 v105, v94, v105
	v_add_f32_e32 v99, v95, v99
	v_add_f32_e32 v106, v88, v106
	v_add_f32_e32 v100, v89, v100
	v_add_f32_e32 v107, v90, v107
	v_add_f32_e32 v101, v91, v101
	v_cvt_pk_bf16_f32 v88, v104, v98
	v_cvt_pk_bf16_f32 v89, v105, v99
	v_cvt_pk_bf16_f32 v90, v106, v100
	v_cvt_pk_bf16_f32 v91, v107, v101
	v_mul_f32_e32 v98, v98, v98
	v_mul_f32_e32 v99, v99, v99
	v_mul_f32_e32 v100, v100, v100
	v_mul_f32_e32 v101, v101, v101
	v_fmac_f32_e32 v98, v104, v104
	v_fmac_f32_e32 v99, v105, v105
	v_fmac_f32_e32 v100, v106, v106
	v_fmac_f32_e32 v101, v107, v107
	v_add_f32_e32 v98, v98, v99
	v_add_f32_e32 v99, v100, v101
	v_add_f32_e32 v98, v98, v99
	global_store_dwordx4 v[102:103], v[88:91], off
	s_waitcnt vmcnt(11)
	v_lshlrev_b32_e32 v99, 16, v208
	v_and_b32_e32 v92, 0xffff0000, v208
	v_lshlrev_b32_e32 v100, 16, v209
	v_and_b32_e32 v93, 0xffff0000, v209
	v_lshlrev_b32_e32 v101, 16, v210
	v_and_b32_e32 v94, 0xffff0000, v210
	v_lshlrev_b32_e32 v104, 16, v211
	v_and_b32_e32 v95, 0xffff0000, v211
	v_add_f32_e32 v85, v85, v92
	v_add_f32_e32 v87, v87, v93
	v_add_f32_e32 v93, v81, v94
	v_add_f32_e32 v95, v83, v95
	v_add_f32_e32 v84, v84, v99
	v_add_f32_e32 v86, v86, v100
	v_add_f32_e32 v92, v80, v101
	v_add_f32_e32 v94, v82, v104
	v_mul_f32_e32 v80, v85, v85
	v_mul_f32_e32 v81, v87, v87
	v_mul_f32_e32 v82, v93, v93
	v_mul_f32_e32 v83, v95, v95
	v_fmac_f32_e32 v80, v84, v84
	v_fmac_f32_e32 v81, v86, v86
	v_fmac_f32_e32 v82, v92, v92
	v_fmac_f32_e32 v83, v94, v94
	v_add_f32_e32 v80, v80, v81
	v_add_f32_e32 v81, v82, v83
	v_add_f32_e32 v80, v80, v81
	v_add_f32_e32 v80, v98, v80
	v_mov_b32_e32 v81, v80
	s_nop 1
	v_permlane16_swap_b32_e32 v81, v80
	v_cvt_pk_bf16_f32 v82, v84, v85
	v_cvt_pk_bf16_f32 v83, v86, v87
	v_cvt_pk_bf16_f32 v84, v92, v93
	v_cvt_pk_bf16_f32 v85, v94, v95
	s_waitcnt lgkmcnt(0)
	v_add_f32_e32 v80, v80, v81
	v_mov_b32_e32 v81, v80
	s_nop 1
	v_permlane32_swap_b32_e32 v81, v80
	global_store_dwordx4 v[102:103], v[82:85], off offset:256
	s_and_saveexec_b64 s[42:43], s[4:5]
	s_cbranch_execz .LBB0_571
	v_lshlrev_b64 v[82:83], 6, v[96:97]
	v_lshl_add_u64 v[82:83], s[18:19], 0, v[82:83]
	v_lshl_add_u64 v[82:83], s[40:41], 2, v[82:83]
	s_lshl_b32 s8, s56, 2
	v_lshl_add_u64 v[82:83], v[82:83], 0, s[8:9]
	s_waitcnt lgkmcnt(0)
	v_add_f32_e32 v80, v80, v81
	global_store_dword v[82:83], v80, off
.LBB0_571:
	s_or_b64 exec, exec, s[42:43]
	v_or_b32_e32 v80, 48, v150
	s_waitcnt lgkmcnt(0)
	v_ashrrev_i32_e32 v81, 31, v80
	v_lshlrev_b64 v[82:83], 11, v[80:81]
	v_lshl_add_u64 v[82:83], s[14:15], 0, v[82:83]
	v_lshl_add_u64 v[86:87], v[148:149], 1, v[82:83]
	s_mov_b64 s[100:101], 0x50000
	v_lshl_add_u64 v[230:231], v[232:233], 0, s[100:101]
	global_load_dwordx4 v[204:207], v[230:231], off
	global_load_dwordx4 v[208:211], v[230:231], off offset:256
	s_waitcnt vmcnt(13)
	v_lshlrev_b32_e32 v88, 16, v212
	v_and_b32_e32 v82, 0xffff0000, v212
	v_lshlrev_b32_e32 v89, 16, v213
	v_and_b32_e32 v83, 0xffff0000, v213
	v_lshlrev_b32_e32 v90, 16, v214
	v_and_b32_e32 v84, 0xffff0000, v214
	v_lshlrev_b32_e32 v91, 16, v215
	v_and_b32_e32 v85, 0xffff0000, v215
	v_add_f32_e32 v88, v76, v88
	v_add_f32_e32 v82, v77, v82
	v_add_f32_e32 v89, v78, v89
	v_add_f32_e32 v83, v79, v83
	v_add_f32_e32 v90, v72, v90
	v_add_f32_e32 v84, v73, v84
	v_add_f32_e32 v91, v74, v91
	v_add_f32_e32 v85, v75, v85
	v_cvt_pk_bf16_f32 v72, v88, v82
	v_cvt_pk_bf16_f32 v73, v89, v83
	v_cvt_pk_bf16_f32 v74, v90, v84
	v_cvt_pk_bf16_f32 v75, v91, v85
	v_mul_f32_e32 v82, v82, v82
	v_mul_f32_e32 v83, v83, v83
	v_mul_f32_e32 v84, v84, v84
	v_mul_f32_e32 v85, v85, v85
	v_fmac_f32_e32 v82, v88, v88
	v_fmac_f32_e32 v83, v89, v89
	v_fmac_f32_e32 v84, v90, v90
	v_fmac_f32_e32 v85, v91, v91
	v_add_f32_e32 v82, v82, v83
	v_add_f32_e32 v83, v84, v85
	v_add_f32_e32 v82, v82, v83
	global_store_dwordx4 v[86:87], v[72:75], off
	s_waitcnt vmcnt(13)
	v_lshlrev_b32_e32 v83, 16, v216
	v_and_b32_e32 v76, 0xffff0000, v216
	v_lshlrev_b32_e32 v84, 16, v217
	v_and_b32_e32 v77, 0xffff0000, v217
	v_lshlrev_b32_e32 v85, 16, v218
	v_and_b32_e32 v78, 0xffff0000, v218
	v_lshlrev_b32_e32 v88, 16, v219
	v_and_b32_e32 v79, 0xffff0000, v219
	v_add_f32_e32 v69, v69, v76
	v_add_f32_e32 v71, v71, v77
	v_add_f32_e32 v77, v65, v78
	v_add_f32_e32 v79, v67, v79
	v_add_f32_e32 v68, v68, v83
	v_add_f32_e32 v70, v70, v84
	v_add_f32_e32 v76, v64, v85
	v_add_f32_e32 v78, v66, v88
	v_mul_f32_e32 v64, v69, v69
	v_mul_f32_e32 v65, v71, v71
	v_mul_f32_e32 v66, v77, v77
	v_mul_f32_e32 v67, v79, v79
	v_fmac_f32_e32 v64, v68, v68
	v_fmac_f32_e32 v65, v70, v70
	v_fmac_f32_e32 v66, v76, v76
	v_fmac_f32_e32 v67, v78, v78
	v_add_f32_e32 v64, v64, v65
	v_add_f32_e32 v65, v66, v67
	v_add_f32_e32 v64, v64, v65
	v_add_f32_e32 v64, v82, v64
	v_mov_b32_e32 v65, v64
	s_nop 1
	v_permlane16_swap_b32_e32 v65, v64
	v_cvt_pk_bf16_f32 v66, v68, v69
	v_cvt_pk_bf16_f32 v67, v70, v71
	v_cvt_pk_bf16_f32 v68, v76, v77
	v_cvt_pk_bf16_f32 v69, v78, v79
	s_waitcnt lgkmcnt(0)
	v_add_f32_e32 v64, v64, v65
	v_mov_b32_e32 v65, v64
	s_nop 1
	v_permlane32_swap_b32_e32 v65, v64
	global_store_dwordx4 v[86:87], v[66:69], off offset:256
	s_and_saveexec_b64 s[42:43], s[4:5]
	s_cbranch_execz .LBB0_573
	v_lshlrev_b64 v[66:67], 6, v[80:81]
	v_lshl_add_u64 v[66:67], s[18:19], 0, v[66:67]
	v_lshl_add_u64 v[66:67], s[40:41], 2, v[66:67]
	s_lshl_b32 s8, s56, 2
	v_lshl_add_u64 v[66:67], v[66:67], 0, s[8:9]
	s_waitcnt lgkmcnt(0)
	v_add_f32_e32 v64, v64, v65
	global_store_dword v[66:67], v64, off
.LBB0_573:
	s_or_b64 exec, exec, s[42:43]
	v_add_u32_e32 v64, 0x80, v150
	s_waitcnt lgkmcnt(0)
	v_ashrrev_i32_e32 v65, 31, v64
	v_lshlrev_b64 v[66:67], 11, v[64:65]
	v_lshl_add_u64 v[66:67], s[14:15], 0, v[66:67]
	v_lshl_add_u64 v[70:71], v[148:149], 1, v[66:67]
	s_mov_b64 s[100:101], 0x58000
	v_lshl_add_u64 v[230:231], v[232:233], 0, s[100:101]
	global_load_dwordx4 v[212:215], v[230:231], off
	global_load_dwordx4 v[216:219], v[230:231], off offset:256
	s_waitcnt vmcnt(13)
	v_lshlrev_b32_e32 v72, 16, v188
	v_and_b32_e32 v66, 0xffff0000, v188
	v_lshlrev_b32_e32 v73, 16, v189
	v_and_b32_e32 v67, 0xffff0000, v189
	v_lshlrev_b32_e32 v74, 16, v190
	v_and_b32_e32 v68, 0xffff0000, v190
	v_lshlrev_b32_e32 v75, 16, v191
	v_and_b32_e32 v69, 0xffff0000, v191
	v_add_f32_e32 v72, v60, v72
	v_add_f32_e32 v66, v61, v66
	v_add_f32_e32 v73, v62, v73
	v_add_f32_e32 v67, v63, v67
	v_add_f32_e32 v74, v56, v74
	v_add_f32_e32 v68, v57, v68
	v_add_f32_e32 v75, v58, v75
	v_add_f32_e32 v69, v59, v69
	v_cvt_pk_bf16_f32 v56, v72, v66
	v_cvt_pk_bf16_f32 v57, v73, v67
	v_cvt_pk_bf16_f32 v58, v74, v68
	v_cvt_pk_bf16_f32 v59, v75, v69
	v_mul_f32_e32 v66, v66, v66
	v_mul_f32_e32 v67, v67, v67
	v_mul_f32_e32 v68, v68, v68
	v_mul_f32_e32 v69, v69, v69
	v_fmac_f32_e32 v66, v72, v72
	v_fmac_f32_e32 v67, v73, v73
	v_fmac_f32_e32 v68, v74, v74
	v_fmac_f32_e32 v69, v75, v75
	v_add_f32_e32 v66, v66, v67
	v_add_f32_e32 v67, v68, v69
	v_add_f32_e32 v66, v66, v67
	global_store_dwordx4 v[70:71], v[56:59], off
	s_waitcnt vmcnt(13)
	v_lshlrev_b32_e32 v67, 16, v192
	v_and_b32_e32 v60, 0xffff0000, v192
	v_lshlrev_b32_e32 v68, 16, v193
	v_and_b32_e32 v61, 0xffff0000, v193
	v_lshlrev_b32_e32 v69, 16, v194
	v_and_b32_e32 v62, 0xffff0000, v194
	v_lshlrev_b32_e32 v72, 16, v195
	v_and_b32_e32 v63, 0xffff0000, v195
	v_add_f32_e32 v53, v53, v60
	v_add_f32_e32 v55, v55, v61
	v_add_f32_e32 v61, v49, v62
	v_add_f32_e32 v63, v51, v63
	v_add_f32_e32 v52, v52, v67
	v_add_f32_e32 v54, v54, v68
	v_add_f32_e32 v60, v48, v69
	v_add_f32_e32 v62, v50, v72
	v_mul_f32_e32 v48, v53, v53
	v_mul_f32_e32 v49, v55, v55
	v_mul_f32_e32 v50, v61, v61
	v_mul_f32_e32 v51, v63, v63
	v_fmac_f32_e32 v48, v52, v52
	v_fmac_f32_e32 v49, v54, v54
	v_fmac_f32_e32 v50, v60, v60
	v_fmac_f32_e32 v51, v62, v62
	v_add_f32_e32 v48, v48, v49
	v_add_f32_e32 v49, v50, v51
	v_add_f32_e32 v48, v48, v49
	v_add_f32_e32 v48, v66, v48
	v_mov_b32_e32 v49, v48
	s_nop 1
	v_permlane16_swap_b32_e32 v49, v48
	v_cvt_pk_bf16_f32 v50, v52, v53
	v_cvt_pk_bf16_f32 v51, v54, v55
	v_cvt_pk_bf16_f32 v52, v60, v61
	v_cvt_pk_bf16_f32 v53, v62, v63
	s_waitcnt lgkmcnt(0)
	v_add_f32_e32 v48, v48, v49
	v_mov_b32_e32 v49, v48
	s_nop 1
	v_permlane32_swap_b32_e32 v49, v48
	global_store_dwordx4 v[70:71], v[50:53], off offset:256
	s_and_saveexec_b64 s[42:43], s[4:5]
	s_cbranch_execz .LBB0_575
	v_lshlrev_b64 v[50:51], 6, v[64:65]
	v_lshl_add_u64 v[50:51], s[18:19], 0, v[50:51]
	v_lshl_add_u64 v[50:51], s[40:41], 2, v[50:51]
	s_lshl_b32 s8, s56, 2
	v_lshl_add_u64 v[50:51], v[50:51], 0, s[8:9]
	s_waitcnt lgkmcnt(0)
	v_add_f32_e32 v48, v48, v49
	global_store_dword v[50:51], v48, off
.LBB0_575:
	s_or_b64 exec, exec, s[42:43]
	v_add_u32_e32 v48, 0x90, v150
	s_waitcnt lgkmcnt(0)
	v_ashrrev_i32_e32 v49, 31, v48
	v_lshlrev_b64 v[50:51], 11, v[48:49]
	v_lshl_add_u64 v[50:51], s[14:15], 0, v[50:51]
	v_lshl_add_u64 v[54:55], v[148:149], 1, v[50:51]
	s_waitcnt vmcnt(11)
	v_lshlrev_b32_e32 v56, 16, v196
	v_and_b32_e32 v50, 0xffff0000, v196
	v_lshlrev_b32_e32 v57, 16, v197
	v_and_b32_e32 v51, 0xffff0000, v197
	v_lshlrev_b32_e32 v58, 16, v198
	v_and_b32_e32 v52, 0xffff0000, v198
	v_lshlrev_b32_e32 v59, 16, v199
	v_and_b32_e32 v53, 0xffff0000, v199
	v_add_f32_e32 v56, v44, v56
	v_add_f32_e32 v50, v45, v50
	v_add_f32_e32 v57, v46, v57
	v_add_f32_e32 v51, v47, v51
	v_add_f32_e32 v58, v40, v58
	v_add_f32_e32 v52, v41, v52
	v_add_f32_e32 v59, v42, v59
	v_add_f32_e32 v53, v43, v53
	v_cvt_pk_bf16_f32 v40, v56, v50
	v_cvt_pk_bf16_f32 v41, v57, v51
	v_cvt_pk_bf16_f32 v42, v58, v52
	v_cvt_pk_bf16_f32 v43, v59, v53
	v_mul_f32_e32 v50, v50, v50
	v_mul_f32_e32 v51, v51, v51
	v_mul_f32_e32 v52, v52, v52
	v_mul_f32_e32 v53, v53, v53
	v_fmac_f32_e32 v50, v56, v56
	v_fmac_f32_e32 v51, v57, v57
	v_fmac_f32_e32 v52, v58, v58
	v_fmac_f32_e32 v53, v59, v59
	v_add_f32_e32 v50, v50, v51
	v_add_f32_e32 v51, v52, v53
	v_add_f32_e32 v50, v50, v51
	global_store_dwordx4 v[54:55], v[40:43], off
	s_waitcnt vmcnt(11)
	v_lshlrev_b32_e32 v51, 16, v200
	v_and_b32_e32 v44, 0xffff0000, v200
	v_lshlrev_b32_e32 v52, 16, v201
	v_and_b32_e32 v45, 0xffff0000, v201
	v_lshlrev_b32_e32 v53, 16, v202
	v_and_b32_e32 v46, 0xffff0000, v202
	v_lshlrev_b32_e32 v56, 16, v203
	v_and_b32_e32 v47, 0xffff0000, v203
	v_add_f32_e32 v37, v37, v44
	v_add_f32_e32 v39, v39, v45
	v_add_f32_e32 v45, v33, v46
	v_add_f32_e32 v47, v35, v47
	v_add_f32_e32 v36, v36, v51
	v_add_f32_e32 v38, v38, v52
	v_add_f32_e32 v44, v32, v53
	v_add_f32_e32 v46, v34, v56
	v_mul_f32_e32 v32, v37, v37
	v_mul_f32_e32 v33, v39, v39
	v_mul_f32_e32 v34, v45, v45
	v_mul_f32_e32 v35, v47, v47
	v_fmac_f32_e32 v32, v36, v36
	v_fmac_f32_e32 v33, v38, v38
	v_fmac_f32_e32 v34, v44, v44
	v_fmac_f32_e32 v35, v46, v46
	v_add_f32_e32 v32, v32, v33
	v_add_f32_e32 v33, v34, v35
	v_add_f32_e32 v32, v32, v33
	v_add_f32_e32 v32, v50, v32
	v_mov_b32_e32 v33, v32
	s_nop 1
	v_permlane16_swap_b32_e32 v33, v32
	v_cvt_pk_bf16_f32 v34, v36, v37
	v_cvt_pk_bf16_f32 v35, v38, v39
	v_cvt_pk_bf16_f32 v36, v44, v45
	v_cvt_pk_bf16_f32 v37, v46, v47
	s_waitcnt lgkmcnt(0)
	v_add_f32_e32 v32, v32, v33
	v_mov_b32_e32 v33, v32
	s_nop 1
	v_permlane32_swap_b32_e32 v33, v32
	global_store_dwordx4 v[54:55], v[34:37], off offset:256
	s_and_saveexec_b64 s[42:43], s[4:5]
	s_cbranch_execz .LBB0_577
	v_lshlrev_b64 v[34:35], 6, v[48:49]
	v_lshl_add_u64 v[34:35], s[18:19], 0, v[34:35]
	v_lshl_add_u64 v[34:35], s[40:41], 2, v[34:35]
	s_lshl_b32 s8, s56, 2
	v_lshl_add_u64 v[34:35], v[34:35], 0, s[8:9]
	s_waitcnt lgkmcnt(0)
	v_add_f32_e32 v32, v32, v33
	global_store_dword v[34:35], v32, off
.LBB0_577:
	s_or_b64 exec, exec, s[42:43]
	v_add_u32_e32 v32, 0xa0, v150
	s_waitcnt lgkmcnt(0)
	v_ashrrev_i32_e32 v33, 31, v32
	v_lshlrev_b64 v[34:35], 11, v[32:33]
	v_lshl_add_u64 v[34:35], s[14:15], 0, v[34:35]
	v_lshl_add_u64 v[38:39], v[148:149], 1, v[34:35]
	s_waitcnt vmcnt(9)
	v_lshlrev_b32_e32 v40, 16, v204
	v_and_b32_e32 v34, 0xffff0000, v204
	v_lshlrev_b32_e32 v41, 16, v205
	v_and_b32_e32 v35, 0xffff0000, v205
	v_lshlrev_b32_e32 v42, 16, v206
	v_and_b32_e32 v36, 0xffff0000, v206
	v_lshlrev_b32_e32 v43, 16, v207
	v_and_b32_e32 v37, 0xffff0000, v207
	v_add_f32_e32 v40, v28, v40
	v_add_f32_e32 v34, v29, v34
	v_add_f32_e32 v41, v30, v41
	v_add_f32_e32 v35, v31, v35
	v_add_f32_e32 v42, v24, v42
	v_add_f32_e32 v36, v25, v36
	v_add_f32_e32 v43, v26, v43
	v_add_f32_e32 v37, v27, v37
	v_cvt_pk_bf16_f32 v24, v40, v34
	v_cvt_pk_bf16_f32 v25, v41, v35
	v_cvt_pk_bf16_f32 v26, v42, v36
	v_cvt_pk_bf16_f32 v27, v43, v37
	v_mul_f32_e32 v34, v34, v34
	v_mul_f32_e32 v35, v35, v35
	v_mul_f32_e32 v36, v36, v36
	v_mul_f32_e32 v37, v37, v37
	v_fmac_f32_e32 v34, v40, v40
	v_fmac_f32_e32 v35, v41, v41
	v_fmac_f32_e32 v36, v42, v42
	v_fmac_f32_e32 v37, v43, v43
	v_add_f32_e32 v34, v34, v35
	v_add_f32_e32 v35, v36, v37
	v_add_f32_e32 v34, v34, v35
	global_store_dwordx4 v[38:39], v[24:27], off
	s_waitcnt vmcnt(9)
	v_lshlrev_b32_e32 v35, 16, v208
	v_and_b32_e32 v28, 0xffff0000, v208
	v_lshlrev_b32_e32 v36, 16, v209
	v_and_b32_e32 v29, 0xffff0000, v209
	v_lshlrev_b32_e32 v37, 16, v210
	v_and_b32_e32 v30, 0xffff0000, v210
	v_lshlrev_b32_e32 v40, 16, v211
	v_and_b32_e32 v31, 0xffff0000, v211
	v_add_f32_e32 v21, v21, v28
	v_add_f32_e32 v23, v23, v29
	v_add_f32_e32 v29, v17, v30
	v_add_f32_e32 v31, v19, v31
	v_add_f32_e32 v20, v20, v35
	v_add_f32_e32 v22, v22, v36
	v_add_f32_e32 v28, v16, v37
	v_add_f32_e32 v30, v18, v40
	v_mul_f32_e32 v16, v21, v21
	v_mul_f32_e32 v17, v23, v23
	v_mul_f32_e32 v18, v29, v29
	v_mul_f32_e32 v19, v31, v31
	v_fmac_f32_e32 v16, v20, v20
	v_fmac_f32_e32 v17, v22, v22
	v_fmac_f32_e32 v18, v28, v28
	v_fmac_f32_e32 v19, v30, v30
	v_add_f32_e32 v16, v16, v17
	v_add_f32_e32 v17, v18, v19
	v_add_f32_e32 v16, v16, v17
	v_add_f32_e32 v16, v34, v16
	v_mov_b32_e32 v17, v16
	s_nop 1
	v_permlane16_swap_b32_e32 v17, v16
	v_cvt_pk_bf16_f32 v18, v20, v21
	v_cvt_pk_bf16_f32 v19, v22, v23
	v_cvt_pk_bf16_f32 v20, v28, v29
	v_cvt_pk_bf16_f32 v21, v30, v31
	s_waitcnt lgkmcnt(0)
	v_add_f32_e32 v16, v16, v17
	v_mov_b32_e32 v17, v16
	s_nop 1
	v_permlane32_swap_b32_e32 v17, v16
	global_store_dwordx4 v[38:39], v[18:21], off offset:256
	s_and_saveexec_b64 s[42:43], s[4:5]
	s_cbranch_execz .LBB0_579
	v_lshlrev_b64 v[18:19], 6, v[32:33]
	v_lshl_add_u64 v[18:19], s[18:19], 0, v[18:19]
	v_lshl_add_u64 v[18:19], s[40:41], 2, v[18:19]
	s_lshl_b32 s8, s56, 2
	v_lshl_add_u64 v[18:19], v[18:19], 0, s[8:9]
	s_waitcnt lgkmcnt(0)
	v_add_f32_e32 v16, v16, v17
	global_store_dword v[18:19], v16, off
.LBB0_579:
	s_or_b64 exec, exec, s[42:43]
	v_add_u32_e32 v16, 0xb0, v150
	s_waitcnt lgkmcnt(0)
	v_ashrrev_i32_e32 v17, 31, v16
	v_lshlrev_b64 v[18:19], 11, v[16:17]
	v_lshl_add_u64 v[18:19], s[14:15], 0, v[18:19]
	v_lshl_add_u64 v[22:23], v[148:149], 1, v[18:19]
	s_waitcnt vmcnt(7)
	v_lshlrev_b32_e32 v24, 16, v212
	v_and_b32_e32 v18, 0xffff0000, v212
	v_lshlrev_b32_e32 v25, 16, v213
	v_and_b32_e32 v19, 0xffff0000, v213
	v_lshlrev_b32_e32 v26, 16, v214
	v_and_b32_e32 v20, 0xffff0000, v214
	v_lshlrev_b32_e32 v27, 16, v215
	v_and_b32_e32 v21, 0xffff0000, v215
	v_add_f32_e32 v24, v12, v24
	v_add_f32_e32 v18, v13, v18
	v_add_f32_e32 v25, v14, v25
	v_add_f32_e32 v19, v15, v19
	v_add_f32_e32 v26, v8, v26
	v_add_f32_e32 v20, v9, v20
	v_add_f32_e32 v27, v10, v27
	v_add_f32_e32 v21, v11, v21
	v_cvt_pk_bf16_f32 v8, v24, v18
	v_cvt_pk_bf16_f32 v9, v25, v19
	v_cvt_pk_bf16_f32 v10, v26, v20
	v_cvt_pk_bf16_f32 v11, v27, v21
	v_mul_f32_e32 v18, v18, v18
	v_mul_f32_e32 v19, v19, v19
	v_mul_f32_e32 v20, v20, v20
	v_mul_f32_e32 v21, v21, v21
	v_fmac_f32_e32 v18, v24, v24
	v_fmac_f32_e32 v19, v25, v25
	v_fmac_f32_e32 v20, v26, v26
	v_fmac_f32_e32 v21, v27, v27
	v_add_f32_e32 v18, v18, v19
	v_add_f32_e32 v19, v20, v21
	v_add_f32_e32 v18, v18, v19
	global_store_dwordx4 v[22:23], v[8:11], off
	s_waitcnt vmcnt(7)
	v_lshlrev_b32_e32 v19, 16, v216
	v_and_b32_e32 v12, 0xffff0000, v216
	v_lshlrev_b32_e32 v20, 16, v217
	v_and_b32_e32 v13, 0xffff0000, v217
	v_lshlrev_b32_e32 v21, 16, v218
	v_and_b32_e32 v14, 0xffff0000, v218
	v_lshlrev_b32_e32 v24, 16, v219
	v_and_b32_e32 v15, 0xffff0000, v219
	v_add_f32_e32 v5, v5, v12
	v_add_f32_e32 v7, v7, v13
	v_add_f32_e32 v13, v1, v14
	v_add_f32_e32 v15, v3, v15
	v_add_f32_e32 v4, v4, v19
	v_add_f32_e32 v6, v6, v20
	v_add_f32_e32 v12, v0, v21
	v_add_f32_e32 v14, v2, v24
	v_mul_f32_e32 v0, v5, v5
	v_mul_f32_e32 v1, v7, v7
	v_mul_f32_e32 v2, v13, v13
	v_mul_f32_e32 v3, v15, v15
	v_fmac_f32_e32 v0, v4, v4
	v_fmac_f32_e32 v1, v6, v6
	v_fmac_f32_e32 v2, v12, v12
	v_fmac_f32_e32 v3, v14, v14
	v_add_f32_e32 v0, v0, v1
	v_add_f32_e32 v1, v2, v3
	v_add_f32_e32 v0, v0, v1
	v_add_f32_e32 v0, v18, v0
	v_mov_b32_e32 v1, v0
	s_nop 1
	v_permlane16_swap_b32_e32 v1, v0
	v_cvt_pk_bf16_f32 v2, v4, v5
	v_cvt_pk_bf16_f32 v3, v6, v7
	v_cvt_pk_bf16_f32 v4, v12, v13
	v_cvt_pk_bf16_f32 v5, v14, v15
	s_waitcnt lgkmcnt(0)
	v_add_f32_e32 v0, v0, v1
	v_mov_b32_e32 v1, v0
	s_nop 1
	v_permlane32_swap_b32_e32 v1, v0
	global_store_dwordx4 v[22:23], v[2:5], off offset:256
	s_and_saveexec_b64 s[42:43], s[4:5]
	s_cbranch_execz .LBB0_581
	v_lshlrev_b64 v[2:3], 6, v[16:17]
	v_lshl_add_u64 v[2:3], s[18:19], 0, v[2:3]
	v_lshl_add_u64 v[2:3], s[40:41], 2, v[2:3]
	s_lshl_b32 s8, s56, 2
	v_lshl_add_u64 v[2:3], v[2:3], 0, s[8:9]
	s_waitcnt lgkmcnt(0)
	v_add_f32_e32 v0, v0, v1
	global_store_dword v[2:3], v0, off

.LBB0_658:
	s_and_b32 s9, s0, -4
	s_cmp_eq_u32 s9, 4
	s_cselect_b64 s[52:53], -1, 0
	s_lshl_b32 s1, s1, 10
	v_add_u32_e32 v164, s1, v159
	ds_read_b32 v154, v164
	ds_read_b32 v174, v164 offset:64
	ds_read_b32 v176, v164 offset:128
	ds_read_b32 v178, v164 offset:192
	ds_read_b32 v180, v164 offset:512
	ds_read_b32 v182, v164 offset:576
	ds_read_b32 v184, v164 offset:640
	ds_read_b32 v186, v164 offset:704
	v_lshl_or_b32 v150, s0, 8, v158
	v_lshl_add_u32 v148, s8, 8, v131
	v_mov_b64_e32 v[152:153], s[16:17]
	s_cmp_lg_u32 s9, 4
	v_ashrrev_i32_e32 v151, 31, v150
	v_mad_i64_i32 v[152:153], s[8:9], v148, s92, v[152:153]
	v_ashrrev_i32_e32 v149, 31, v148
	v_lshl_add_u64 v[152:153], v[150:151], 1, v[152:153]
	s_waitcnt lgkmcnt(0)
	v_pk_mul_f32 v[126:127], v[126:127], v[154:155] op_sel_hi:[1,0]
	v_pk_mul_f32 v[124:125], v[124:125], v[154:155] op_sel_hi:[1,0]
	v_pk_mul_f32 v[122:123], v[122:123], v[154:155] op_sel_hi:[1,0]
	v_pk_mul_f32 v[120:121], v[120:121], v[154:155] op_sel_hi:[1,0]
	v_cvt_pk_bf16_f32 v166, v124, v125
	v_cvt_pk_bf16_f32 v167, v126, v127
	s_nop 0
	v_cvt_pk_bf16_f32 v168, v120, v121
	v_cvt_pk_bf16_f32 v169, v122, v123
	global_store_dwordx4 v[152:153], v[166:169], off
	s_cbranch_scc1 .LBB0_662
	v_mul_f32_e32 v121, v121, v121
	v_fmac_f32_e32 v121, v120, v120
	v_mul_f32_e32 v120, v123, v123
	v_mul_f32_e32 v125, v125, v125
	v_fmac_f32_e32 v120, v122, v122
	v_and_b32_e32 v122, 64, v163
	v_fmac_f32_e32 v125, v124, v124
	v_mul_f32_e32 v124, v127, v127
	v_add_f32_e32 v120, v121, v120
	v_xor_b32_e32 v121, 16, v163
	v_add_u32_e32 v122, 64, v122
	v_fmac_f32_e32 v124, v126, v126
	v_cmp_lt_i32_e32 vcc, v121, v122
	v_add_f32_e32 v124, v125, v124
	v_add_f32_e32 v120, v124, v120
	v_cndmask_b32_e32 v121, v163, v121, vcc
	v_lshlrev_b32_e32 v121, 2, v121
	v_mov_b32_e32 v121, v120
	s_nop 1
	v_permlane16_swap_b32_e32 v121, v120
	s_waitcnt lgkmcnt(0)
	v_add_f32_e32 v120, v120, v121
	v_xor_b32_e32 v121, 32, v163
	v_cmp_lt_i32_e32 vcc, v121, v122
	s_nop 1
	v_cndmask_b32_e32 v121, v163, v121, vcc
	v_lshlrev_b32_e32 v121, 2, v121
	v_mov_b32_e32 v121, v120
	s_nop 1
	v_permlane32_swap_b32_e32 v121, v120
	s_and_saveexec_b64 s[8:9], s[4:5]
	s_cbranch_execz .LBB0_661
	s_lshl_b32 s1, s0, 18
	s_add_i32 s10, s1, s85
	s_lshl_b64 s[12:13], s[10:11], 2
	s_add_u32 s12, s81, s12
	s_addc_u32 s13, s82, s13
	s_waitcnt lgkmcnt(0)
	v_add_f32_e32 v122, v120, v121
	v_lshl_add_u64 v[120:121], v[148:149], 2, s[12:13]
	global_store_dword v[120:121], v122, off

.LBB0_662:
	v_mov_b32_e32 v155, v154
	v_mov_b32_e32 v120, v154
	s_waitcnt lgkmcnt(0)
	v_mov_b32_e32 v121, v154
	v_cndmask_b32_e64 v124, 0, 1, s[52:53]
	v_pk_mul_f32 v[118:119], v[118:119], v[120:121]
	v_pk_mul_f32 v[116:117], v[116:117], v[154:155]
	v_pk_mul_f32 v[114:115], v[114:115], v[120:121]
	v_pk_mul_f32 v[112:113], v[112:113], v[154:155]
	v_cmp_ne_u32_e64 s[8:9], 1, v124
	s_andn2_b64 vcc, exec, s[52:53]
	v_cvt_pk_bf16_f32 v120, v116, v117
	v_cvt_pk_bf16_f32 v121, v118, v119
	v_cvt_pk_bf16_f32 v122, v112, v113
	v_cvt_pk_bf16_f32 v123, v114, v115
	global_store_dwordx4 v[152:153], v[120:123], off offset:256
	s_cbranch_vccnz .LBB0_666
	v_mul_f32_e32 v113, v113, v113
	v_fmac_f32_e32 v113, v112, v112
	v_mul_f32_e32 v112, v115, v115
	v_mul_f32_e32 v117, v117, v117
	v_fmac_f32_e32 v112, v114, v114
	v_and_b32_e32 v114, 64, v163
	v_fmac_f32_e32 v117, v116, v116
	v_mul_f32_e32 v116, v119, v119
	v_add_f32_e32 v112, v113, v112
	v_xor_b32_e32 v113, 16, v163
	v_add_u32_e32 v114, 64, v114
	v_fmac_f32_e32 v116, v118, v118
	v_cmp_lt_i32_e32 vcc, v113, v114
	v_add_f32_e32 v116, v117, v116
	v_add_f32_e32 v112, v116, v112
	v_cndmask_b32_e32 v113, v163, v113, vcc
	v_lshlrev_b32_e32 v113, 2, v113
	v_mov_b32_e32 v113, v112
	s_nop 1
	v_permlane16_swap_b32_e32 v113, v112
	s_waitcnt lgkmcnt(0)
	v_add_f32_e32 v112, v112, v113
	v_xor_b32_e32 v113, 32, v163
	v_cmp_lt_i32_e32 vcc, v113, v114
	s_nop 1
	v_cndmask_b32_e32 v113, v163, v113, vcc
	v_lshlrev_b32_e32 v113, 2, v113
	v_mov_b32_e32 v113, v112
	s_nop 1
	v_permlane32_swap_b32_e32 v113, v112
	s_and_saveexec_b64 s[52:53], s[4:5]
	s_cbranch_execz .LBB0_665
	s_lshl_b32 s1, s0, 18
	s_add_i32 s10, s1, s86
	s_lshl_b64 s[12:13], s[10:11], 2
	s_add_u32 s12, s81, s12
	s_addc_u32 s13, s82, s13
	s_waitcnt lgkmcnt(0)
	v_add_f32_e32 v114, v112, v113
	v_lshl_add_u64 v[112:113], v[148:149], 2, s[12:13]
	global_store_dword v[112:113], v114, off

.LBB0_666:
	s_nop 1
	v_mov_b32_e32 v114, v174
	v_or_b32_e32 v115, 16, v148
	s_waitcnt lgkmcnt(0)
	v_mov_b64_e32 v[112:113], s[16:17]
	v_mad_i64_i32 v[112:113], s[12:13], v115, s92, v[112:113]
	v_lshl_add_u64 v[112:113], v[150:151], 1, v[112:113]
	v_pk_mul_f32 v[110:111], v[110:111], v[114:115] op_sel_hi:[1,0]
	v_pk_mul_f32 v[108:109], v[108:109], v[114:115] op_sel_hi:[1,0]
	v_pk_mul_f32 v[106:107], v[106:107], v[114:115] op_sel_hi:[1,0]
	v_pk_mul_f32 v[104:105], v[104:105], v[114:115] op_sel_hi:[1,0]
	s_and_b64 vcc, exec, s[8:9]
	v_cvt_pk_bf16_f32 v116, v108, v109
	v_cvt_pk_bf16_f32 v117, v110, v111
	v_cvt_pk_bf16_f32 v118, v104, v105
	v_cvt_pk_bf16_f32 v119, v106, v107
	global_store_dwordx4 v[112:113], v[116:119], off
	s_cbranch_vccnz .LBB0_670
	v_mul_f32_e32 v105, v105, v105
	v_fmac_f32_e32 v105, v104, v104
	v_mul_f32_e32 v104, v107, v107
	v_mul_f32_e32 v109, v109, v109
	v_fmac_f32_e32 v104, v106, v106
	v_and_b32_e32 v106, 64, v163
	v_fmac_f32_e32 v109, v108, v108
	v_mul_f32_e32 v108, v111, v111
	v_add_f32_e32 v104, v105, v104
	v_xor_b32_e32 v105, 16, v163
	v_add_u32_e32 v106, 64, v106
	v_fmac_f32_e32 v108, v110, v110
	v_cmp_lt_i32_e32 vcc, v105, v106
	v_add_f32_e32 v108, v109, v108
	v_add_f32_e32 v104, v108, v104
	v_cndmask_b32_e32 v105, v163, v105, vcc
	v_lshlrev_b32_e32 v105, 2, v105
	v_mov_b32_e32 v105, v104
	s_nop 1
	v_permlane16_swap_b32_e32 v105, v104
	s_waitcnt lgkmcnt(0)
	v_add_f32_e32 v104, v104, v105
	v_xor_b32_e32 v105, 32, v163
	v_cmp_lt_i32_e32 vcc, v105, v106
	s_nop 1
	v_cndmask_b32_e32 v105, v163, v105, vcc
	v_lshlrev_b32_e32 v105, 2, v105
	v_mov_b32_e32 v105, v104
	s_nop 1
	v_permlane32_swap_b32_e32 v105, v104
	s_and_saveexec_b64 s[52:53], s[4:5]
	s_cbranch_execz .LBB0_669
	s_lshl_b32 s1, s0, 18
	s_add_i32 s10, s1, s85
	s_lshl_b64 s[12:13], s[10:11], 2
	s_add_u32 s12, s81, s12
	s_addc_u32 s13, s82, s13
	s_waitcnt lgkmcnt(0)
	v_add_f32_e32 v106, v104, v105
	v_lshl_add_u64 v[104:105], v[148:149], 2, s[12:13]
	global_store_dword v[104:105], v106, off offset:64

.LBB0_670:
	v_mov_b32_e32 v115, v114
	v_mov_b32_e32 v104, v114
	s_waitcnt lgkmcnt(0)
	v_mov_b32_e32 v105, v114
	v_pk_mul_f32 v[102:103], v[102:103], v[104:105]
	v_pk_mul_f32 v[100:101], v[100:101], v[114:115]
	v_pk_mul_f32 v[98:99], v[98:99], v[104:105]
	v_pk_mul_f32 v[96:97], v[96:97], v[114:115]
	s_and_b64 vcc, exec, s[8:9]
	v_cvt_pk_bf16_f32 v104, v100, v101
	v_cvt_pk_bf16_f32 v105, v102, v103
	v_cvt_pk_bf16_f32 v106, v96, v97
	v_cvt_pk_bf16_f32 v107, v98, v99
	global_store_dwordx4 v[112:113], v[104:107], off offset:256
	s_cbranch_vccnz .LBB0_674
	v_mul_f32_e32 v97, v97, v97
	v_fmac_f32_e32 v97, v96, v96
	v_mul_f32_e32 v96, v99, v99
	v_mul_f32_e32 v101, v101, v101
	v_fmac_f32_e32 v96, v98, v98
	v_and_b32_e32 v98, 64, v163
	v_fmac_f32_e32 v101, v100, v100
	v_mul_f32_e32 v100, v103, v103
	v_add_f32_e32 v96, v97, v96
	v_xor_b32_e32 v97, 16, v163
	v_add_u32_e32 v98, 64, v98
	v_fmac_f32_e32 v100, v102, v102
	v_cmp_lt_i32_e32 vcc, v97, v98
	v_add_f32_e32 v100, v101, v100
	v_add_f32_e32 v96, v100, v96
	v_cndmask_b32_e32 v97, v163, v97, vcc
	v_lshlrev_b32_e32 v97, 2, v97
	v_mov_b32_e32 v97, v96
	s_nop 1
	v_permlane16_swap_b32_e32 v97, v96
	s_waitcnt lgkmcnt(0)
	v_add_f32_e32 v96, v96, v97
	v_xor_b32_e32 v97, 32, v163
	v_cmp_lt_i32_e32 vcc, v97, v98
	s_nop 1
	v_cndmask_b32_e32 v97, v163, v97, vcc
	v_lshlrev_b32_e32 v97, 2, v97
	v_mov_b32_e32 v97, v96
	s_nop 1
	v_permlane32_swap_b32_e32 v97, v96
	s_and_saveexec_b64 s[52:53], s[4:5]
	s_cbranch_execz .LBB0_673
	s_lshl_b32 s1, s0, 18
	s_add_i32 s10, s1, s86
	s_lshl_b64 s[12:13], s[10:11], 2
	s_add_u32 s12, s81, s12
	s_addc_u32 s13, s82, s13
	s_waitcnt lgkmcnt(0)
	v_add_f32_e32 v98, v96, v97
	v_lshl_add_u64 v[96:97], v[148:149], 2, s[12:13]
	global_store_dword v[96:97], v98, off offset:64

.LBB0_674:
	s_nop 1
	v_mov_b32_e32 v98, v176
	v_or_b32_e32 v99, 32, v148
	s_waitcnt lgkmcnt(0)
	v_mov_b64_e32 v[96:97], s[16:17]
	v_mad_i64_i32 v[96:97], s[12:13], v99, s92, v[96:97]
	v_lshl_add_u64 v[96:97], v[150:151], 1, v[96:97]
	v_pk_mul_f32 v[94:95], v[94:95], v[98:99] op_sel_hi:[1,0]
	v_pk_mul_f32 v[92:93], v[92:93], v[98:99] op_sel_hi:[1,0]
	v_pk_mul_f32 v[90:91], v[90:91], v[98:99] op_sel_hi:[1,0]
	v_pk_mul_f32 v[88:89], v[88:89], v[98:99] op_sel_hi:[1,0]
	s_and_b64 vcc, exec, s[8:9]
	v_cvt_pk_bf16_f32 v100, v92, v93
	v_cvt_pk_bf16_f32 v101, v94, v95
	v_cvt_pk_bf16_f32 v102, v88, v89
	v_cvt_pk_bf16_f32 v103, v90, v91
	global_store_dwordx4 v[96:97], v[100:103], off
	s_cbranch_vccnz .LBB0_678
	v_mul_f32_e32 v89, v89, v89
	v_fmac_f32_e32 v89, v88, v88
	v_mul_f32_e32 v88, v91, v91
	v_mul_f32_e32 v93, v93, v93
	v_fmac_f32_e32 v88, v90, v90
	v_and_b32_e32 v90, 64, v163
	v_fmac_f32_e32 v93, v92, v92
	v_mul_f32_e32 v92, v95, v95
	v_add_f32_e32 v88, v89, v88
	v_xor_b32_e32 v89, 16, v163
	v_add_u32_e32 v90, 64, v90
	v_fmac_f32_e32 v92, v94, v94
	v_cmp_lt_i32_e32 vcc, v89, v90
	v_add_f32_e32 v92, v93, v92
	v_add_f32_e32 v88, v92, v88
	v_cndmask_b32_e32 v89, v163, v89, vcc
	v_lshlrev_b32_e32 v89, 2, v89
	v_mov_b32_e32 v89, v88
	s_nop 1
	v_permlane16_swap_b32_e32 v89, v88
	s_waitcnt lgkmcnt(0)
	v_add_f32_e32 v88, v88, v89
	v_xor_b32_e32 v89, 32, v163
	v_cmp_lt_i32_e32 vcc, v89, v90
	s_nop 1
	v_cndmask_b32_e32 v89, v163, v89, vcc
	v_lshlrev_b32_e32 v89, 2, v89
	v_mov_b32_e32 v89, v88
	s_nop 1
	v_permlane32_swap_b32_e32 v89, v88
	s_and_saveexec_b64 s[52:53], s[4:5]
	s_cbranch_execz .LBB0_677
	s_lshl_b32 s1, s0, 18
	s_add_i32 s10, s1, s85
	s_lshl_b64 s[12:13], s[10:11], 2
	s_add_u32 s12, s81, s12
	s_addc_u32 s13, s82, s13
	s_waitcnt lgkmcnt(0)
	v_add_f32_e32 v90, v88, v89
	v_lshl_add_u64 v[88:89], v[148:149], 2, s[12:13]
	global_store_dword v[88:89], v90, off offset:128

.LBB0_678:
	v_mov_b32_e32 v99, v98
	v_mov_b32_e32 v88, v98
	s_waitcnt lgkmcnt(0)
	v_mov_b32_e32 v89, v98
	v_pk_mul_f32 v[86:87], v[86:87], v[88:89]
	v_pk_mul_f32 v[84:85], v[84:85], v[98:99]
	v_pk_mul_f32 v[82:83], v[82:83], v[88:89]
	v_pk_mul_f32 v[80:81], v[80:81], v[98:99]
	s_and_b64 vcc, exec, s[8:9]
	v_cvt_pk_bf16_f32 v88, v84, v85
	v_cvt_pk_bf16_f32 v89, v86, v87
	v_cvt_pk_bf16_f32 v90, v80, v81
	v_cvt_pk_bf16_f32 v91, v82, v83
	global_store_dwordx4 v[96:97], v[88:91], off offset:256
	s_cbranch_vccnz .LBB0_682
	v_mul_f32_e32 v81, v81, v81
	v_fmac_f32_e32 v81, v80, v80
	v_mul_f32_e32 v80, v83, v83
	v_mul_f32_e32 v85, v85, v85
	v_fmac_f32_e32 v80, v82, v82
	v_and_b32_e32 v82, 64, v163
	v_fmac_f32_e32 v85, v84, v84
	v_mul_f32_e32 v84, v87, v87
	v_add_f32_e32 v80, v81, v80
	v_xor_b32_e32 v81, 16, v163
	v_add_u32_e32 v82, 64, v82
	v_fmac_f32_e32 v84, v86, v86
	v_cmp_lt_i32_e32 vcc, v81, v82
	v_add_f32_e32 v84, v85, v84
	v_add_f32_e32 v80, v84, v80
	v_cndmask_b32_e32 v81, v163, v81, vcc
	v_lshlrev_b32_e32 v81, 2, v81
	v_mov_b32_e32 v81, v80
	s_nop 1
	v_permlane16_swap_b32_e32 v81, v80
	s_waitcnt lgkmcnt(0)
	v_add_f32_e32 v80, v80, v81
	v_xor_b32_e32 v81, 32, v163
	v_cmp_lt_i32_e32 vcc, v81, v82
	s_nop 1
	v_cndmask_b32_e32 v81, v163, v81, vcc
	v_lshlrev_b32_e32 v81, 2, v81
	v_mov_b32_e32 v81, v80
	s_nop 1
	v_permlane32_swap_b32_e32 v81, v80
	s_and_saveexec_b64 s[52:53], s[4:5]
	s_cbranch_execz .LBB0_681
	s_lshl_b32 s1, s0, 18
	s_add_i32 s10, s1, s86
	s_lshl_b64 s[12:13], s[10:11], 2
	s_add_u32 s12, s81, s12
	s_addc_u32 s13, s82, s13
	s_waitcnt lgkmcnt(0)
	v_add_f32_e32 v82, v80, v81
	v_lshl_add_u64 v[80:81], v[148:149], 2, s[12:13]
	global_store_dword v[80:81], v82, off offset:128

.LBB0_682:
	s_nop 1
	v_mov_b32_e32 v82, v178
	v_or_b32_e32 v83, 48, v148
	s_waitcnt lgkmcnt(0)
	v_mov_b64_e32 v[80:81], s[16:17]
	v_mad_i64_i32 v[80:81], s[12:13], v83, s92, v[80:81]
	v_lshl_add_u64 v[80:81], v[150:151], 1, v[80:81]
	v_pk_mul_f32 v[78:79], v[78:79], v[82:83] op_sel_hi:[1,0]
	v_pk_mul_f32 v[76:77], v[76:77], v[82:83] op_sel_hi:[1,0]
	v_pk_mul_f32 v[74:75], v[74:75], v[82:83] op_sel_hi:[1,0]
	v_pk_mul_f32 v[72:73], v[72:73], v[82:83] op_sel_hi:[1,0]
	s_and_b64 vcc, exec, s[8:9]
	v_cvt_pk_bf16_f32 v84, v76, v77
	v_cvt_pk_bf16_f32 v85, v78, v79
	v_cvt_pk_bf16_f32 v86, v72, v73
	v_cvt_pk_bf16_f32 v87, v74, v75
	global_store_dwordx4 v[80:81], v[84:87], off
	s_cbranch_vccnz .LBB0_686
	v_mul_f32_e32 v73, v73, v73
	v_fmac_f32_e32 v73, v72, v72
	v_mul_f32_e32 v72, v75, v75
	v_mul_f32_e32 v77, v77, v77
	v_fmac_f32_e32 v72, v74, v74
	v_and_b32_e32 v74, 64, v163
	v_fmac_f32_e32 v77, v76, v76
	v_mul_f32_e32 v76, v79, v79
	v_add_f32_e32 v72, v73, v72
	v_xor_b32_e32 v73, 16, v163
	v_add_u32_e32 v74, 64, v74
	v_fmac_f32_e32 v76, v78, v78
	v_cmp_lt_i32_e32 vcc, v73, v74
	v_add_f32_e32 v76, v77, v76
	v_add_f32_e32 v72, v76, v72
	v_cndmask_b32_e32 v73, v163, v73, vcc
	v_lshlrev_b32_e32 v73, 2, v73
	v_mov_b32_e32 v73, v72
	s_nop 1
	v_permlane16_swap_b32_e32 v73, v72
	s_waitcnt lgkmcnt(0)
	v_add_f32_e32 v72, v72, v73
	v_xor_b32_e32 v73, 32, v163
	v_cmp_lt_i32_e32 vcc, v73, v74
	s_nop 1
	v_cndmask_b32_e32 v73, v163, v73, vcc
	v_lshlrev_b32_e32 v73, 2, v73
	v_mov_b32_e32 v73, v72
	s_nop 1
	v_permlane32_swap_b32_e32 v73, v72
	s_and_saveexec_b64 s[52:53], s[4:5]
	s_cbranch_execz .LBB0_685
	s_lshl_b32 s1, s0, 18
	s_add_i32 s10, s1, s85
	s_lshl_b64 s[12:13], s[10:11], 2
	s_add_u32 s12, s81, s12
	s_addc_u32 s13, s82, s13
	s_waitcnt lgkmcnt(0)
	v_add_f32_e32 v74, v72, v73
	v_lshl_add_u64 v[72:73], v[148:149], 2, s[12:13]
	global_store_dword v[72:73], v74, off offset:192

.LBB0_686:
	v_mov_b32_e32 v83, v82
	v_mov_b32_e32 v72, v82
	s_waitcnt lgkmcnt(0)
	v_mov_b32_e32 v73, v82
	v_pk_mul_f32 v[70:71], v[70:71], v[72:73]
	v_pk_mul_f32 v[68:69], v[68:69], v[82:83]
	v_pk_mul_f32 v[66:67], v[66:67], v[72:73]
	v_pk_mul_f32 v[64:65], v[64:65], v[82:83]
	s_and_b64 vcc, exec, s[8:9]
	v_cvt_pk_bf16_f32 v72, v68, v69
	v_cvt_pk_bf16_f32 v73, v70, v71
	v_cvt_pk_bf16_f32 v74, v64, v65
	v_cvt_pk_bf16_f32 v75, v66, v67
	global_store_dwordx4 v[80:81], v[72:75], off offset:256
	s_cbranch_vccnz .LBB0_690
	v_mul_f32_e32 v65, v65, v65
	v_fmac_f32_e32 v65, v64, v64
	v_mul_f32_e32 v64, v67, v67
	v_mul_f32_e32 v69, v69, v69
	v_fmac_f32_e32 v64, v66, v66
	v_and_b32_e32 v66, 64, v163
	v_fmac_f32_e32 v69, v68, v68
	v_mul_f32_e32 v68, v71, v71
	v_add_f32_e32 v64, v65, v64
	v_xor_b32_e32 v65, 16, v163
	v_add_u32_e32 v66, 64, v66
	v_fmac_f32_e32 v68, v70, v70
	v_cmp_lt_i32_e32 vcc, v65, v66
	v_add_f32_e32 v68, v69, v68
	v_add_f32_e32 v64, v68, v64
	v_cndmask_b32_e32 v65, v163, v65, vcc
	v_lshlrev_b32_e32 v65, 2, v65
	v_mov_b32_e32 v65, v64
	s_nop 1
	v_permlane16_swap_b32_e32 v65, v64
	s_waitcnt lgkmcnt(0)
	v_add_f32_e32 v64, v64, v65
	v_xor_b32_e32 v65, 32, v163
	v_cmp_lt_i32_e32 vcc, v65, v66
	s_nop 1
	v_cndmask_b32_e32 v65, v163, v65, vcc
	v_lshlrev_b32_e32 v65, 2, v65
	v_mov_b32_e32 v65, v64
	s_nop 1
	v_permlane32_swap_b32_e32 v65, v64
	s_and_saveexec_b64 s[52:53], s[4:5]
	s_cbranch_execz .LBB0_689
	s_lshl_b32 s1, s0, 18
	s_add_i32 s10, s1, s86
	s_lshl_b64 s[12:13], s[10:11], 2
	s_add_u32 s12, s81, s12
	s_addc_u32 s13, s82, s13
	s_waitcnt lgkmcnt(0)
	v_add_f32_e32 v66, v64, v65
	v_lshl_add_u64 v[64:65], v[148:149], 2, s[12:13]
	global_store_dword v[64:65], v66, off offset:192

.LBB0_690:
	s_nop 1
	v_mov_b32_e32 v66, v180
	v_add_u32_e32 v67, 0x80, v148
	s_waitcnt lgkmcnt(0)
	v_mov_b64_e32 v[64:65], s[16:17]
	v_mad_i64_i32 v[64:65], s[12:13], v67, s92, v[64:65]
	v_lshl_add_u64 v[64:65], v[150:151], 1, v[64:65]
	v_pk_mul_f32 v[62:63], v[62:63], v[66:67] op_sel_hi:[1,0]
	v_pk_mul_f32 v[60:61], v[60:61], v[66:67] op_sel_hi:[1,0]
	v_pk_mul_f32 v[58:59], v[58:59], v[66:67] op_sel_hi:[1,0]
	v_pk_mul_f32 v[56:57], v[56:57], v[66:67] op_sel_hi:[1,0]
	s_and_b64 vcc, exec, s[8:9]
	v_cvt_pk_bf16_f32 v68, v60, v61
	v_cvt_pk_bf16_f32 v69, v62, v63
	v_cvt_pk_bf16_f32 v70, v56, v57
	v_cvt_pk_bf16_f32 v71, v58, v59
	global_store_dwordx4 v[64:65], v[68:71], off
	s_cbranch_vccnz .LBB0_694
	v_mul_f32_e32 v57, v57, v57
	v_fmac_f32_e32 v57, v56, v56
	v_mul_f32_e32 v56, v59, v59
	v_mul_f32_e32 v61, v61, v61
	v_fmac_f32_e32 v56, v58, v58
	v_and_b32_e32 v58, 64, v163
	v_fmac_f32_e32 v61, v60, v60
	v_mul_f32_e32 v60, v63, v63
	v_add_f32_e32 v56, v57, v56
	v_xor_b32_e32 v57, 16, v163
	v_add_u32_e32 v58, 64, v58
	v_fmac_f32_e32 v60, v62, v62
	v_cmp_lt_i32_e32 vcc, v57, v58
	v_add_f32_e32 v60, v61, v60
	v_add_f32_e32 v56, v60, v56
	v_cndmask_b32_e32 v57, v163, v57, vcc
	v_lshlrev_b32_e32 v57, 2, v57
	v_mov_b32_e32 v57, v56
	s_nop 1
	v_permlane16_swap_b32_e32 v57, v56
	s_waitcnt lgkmcnt(0)
	v_add_f32_e32 v56, v56, v57
	v_xor_b32_e32 v57, 32, v163
	v_cmp_lt_i32_e32 vcc, v57, v58
	s_nop 1
	v_cndmask_b32_e32 v57, v163, v57, vcc
	v_lshlrev_b32_e32 v57, 2, v57
	v_mov_b32_e32 v57, v56
	s_nop 1
	v_permlane32_swap_b32_e32 v57, v56
	s_and_saveexec_b64 s[52:53], s[4:5]
	s_cbranch_execz .LBB0_693
	s_lshl_b32 s1, s0, 18
	s_add_i32 s10, s1, s85
	s_lshl_b64 s[12:13], s[10:11], 2
	s_add_u32 s12, s81, s12
	s_addc_u32 s13, s82, s13
	s_waitcnt lgkmcnt(0)
	v_add_f32_e32 v58, v56, v57
	v_lshl_add_u64 v[56:57], v[148:149], 2, s[12:13]
	global_store_dword v[56:57], v58, off offset:512

.LBB0_694:
	v_mov_b32_e32 v67, v66
	v_mov_b32_e32 v56, v66
	s_waitcnt lgkmcnt(0)
	v_mov_b32_e32 v57, v66
	v_pk_mul_f32 v[54:55], v[54:55], v[56:57]
	v_pk_mul_f32 v[52:53], v[52:53], v[66:67]
	v_pk_mul_f32 v[50:51], v[50:51], v[56:57]
	v_pk_mul_f32 v[48:49], v[48:49], v[66:67]
	s_and_b64 vcc, exec, s[8:9]
	v_cvt_pk_bf16_f32 v56, v52, v53
	v_cvt_pk_bf16_f32 v57, v54, v55
	v_cvt_pk_bf16_f32 v58, v48, v49
	v_cvt_pk_bf16_f32 v59, v50, v51
	global_store_dwordx4 v[64:65], v[56:59], off offset:256
	s_cbranch_vccnz .LBB0_698
	v_mul_f32_e32 v49, v49, v49
	v_fmac_f32_e32 v49, v48, v48
	v_mul_f32_e32 v48, v51, v51
	v_mul_f32_e32 v53, v53, v53
	v_fmac_f32_e32 v48, v50, v50
	v_and_b32_e32 v50, 64, v163
	v_fmac_f32_e32 v53, v52, v52
	v_mul_f32_e32 v52, v55, v55
	v_add_f32_e32 v48, v49, v48
	v_xor_b32_e32 v49, 16, v163
	v_add_u32_e32 v50, 64, v50
	v_fmac_f32_e32 v52, v54, v54
	v_cmp_lt_i32_e32 vcc, v49, v50
	v_add_f32_e32 v52, v53, v52
	v_add_f32_e32 v48, v52, v48
	v_cndmask_b32_e32 v49, v163, v49, vcc
	v_lshlrev_b32_e32 v49, 2, v49
	v_mov_b32_e32 v49, v48
	s_nop 1
	v_permlane16_swap_b32_e32 v49, v48
	s_waitcnt lgkmcnt(0)
	v_add_f32_e32 v48, v48, v49
	v_xor_b32_e32 v49, 32, v163
	v_cmp_lt_i32_e32 vcc, v49, v50
	s_nop 1
	v_cndmask_b32_e32 v49, v163, v49, vcc
	v_lshlrev_b32_e32 v49, 2, v49
	v_mov_b32_e32 v49, v48
	s_nop 1
	v_permlane32_swap_b32_e32 v49, v48
	s_and_saveexec_b64 s[52:53], s[4:5]
	s_cbranch_execz .LBB0_697
	s_lshl_b32 s1, s0, 18
	s_add_i32 s10, s1, s86
	s_lshl_b64 s[12:13], s[10:11], 2
	s_add_u32 s12, s81, s12
	s_addc_u32 s13, s82, s13
	s_waitcnt lgkmcnt(0)
	v_add_f32_e32 v50, v48, v49
	v_lshl_add_u64 v[48:49], v[148:149], 2, s[12:13]
	global_store_dword v[48:49], v50, off offset:512

.LBB0_698:
	s_nop 1
	v_mov_b32_e32 v50, v182
	v_add_u32_e32 v51, 0x90, v148
	s_waitcnt lgkmcnt(0)
	v_mov_b64_e32 v[48:49], s[16:17]
	v_mad_i64_i32 v[48:49], s[12:13], v51, s92, v[48:49]
	v_lshl_add_u64 v[48:49], v[150:151], 1, v[48:49]
	v_pk_mul_f32 v[46:47], v[46:47], v[50:51] op_sel_hi:[1,0]
	v_pk_mul_f32 v[44:45], v[44:45], v[50:51] op_sel_hi:[1,0]
	v_pk_mul_f32 v[42:43], v[42:43], v[50:51] op_sel_hi:[1,0]
	v_pk_mul_f32 v[40:41], v[40:41], v[50:51] op_sel_hi:[1,0]
	s_and_b64 vcc, exec, s[8:9]
	v_cvt_pk_bf16_f32 v52, v44, v45
	v_cvt_pk_bf16_f32 v53, v46, v47
	v_cvt_pk_bf16_f32 v54, v40, v41
	v_cvt_pk_bf16_f32 v55, v42, v43
	global_store_dwordx4 v[48:49], v[52:55], off
	s_cbranch_vccnz .LBB0_702
	v_mul_f32_e32 v41, v41, v41
	v_fmac_f32_e32 v41, v40, v40
	v_mul_f32_e32 v40, v43, v43
	v_mul_f32_e32 v45, v45, v45
	v_fmac_f32_e32 v40, v42, v42
	v_and_b32_e32 v42, 64, v163
	v_fmac_f32_e32 v45, v44, v44
	v_mul_f32_e32 v44, v47, v47
	v_add_f32_e32 v40, v41, v40
	v_xor_b32_e32 v41, 16, v163
	v_add_u32_e32 v42, 64, v42
	v_fmac_f32_e32 v44, v46, v46
	v_cmp_lt_i32_e32 vcc, v41, v42
	v_add_f32_e32 v44, v45, v44
	v_add_f32_e32 v40, v44, v40
	v_cndmask_b32_e32 v41, v163, v41, vcc
	v_lshlrev_b32_e32 v41, 2, v41
	v_mov_b32_e32 v41, v40
	s_nop 1
	v_permlane16_swap_b32_e32 v41, v40
	s_waitcnt lgkmcnt(0)
	v_add_f32_e32 v40, v40, v41
	v_xor_b32_e32 v41, 32, v163
	v_cmp_lt_i32_e32 vcc, v41, v42
	s_nop 1
	v_cndmask_b32_e32 v41, v163, v41, vcc
	v_lshlrev_b32_e32 v41, 2, v41
	v_mov_b32_e32 v41, v40
	s_nop 1
	v_permlane32_swap_b32_e32 v41, v40
	s_and_saveexec_b64 s[52:53], s[4:5]
	s_cbranch_execz .LBB0_701
	s_lshl_b32 s1, s0, 18
	s_add_i32 s10, s1, s85
	s_lshl_b64 s[12:13], s[10:11], 2
	s_add_u32 s12, s81, s12
	s_addc_u32 s13, s82, s13
	s_waitcnt lgkmcnt(0)
	v_add_f32_e32 v42, v40, v41
	v_lshl_add_u64 v[40:41], v[148:149], 2, s[12:13]
	global_store_dword v[40:41], v42, off offset:576

.LBB0_702:
	v_mov_b32_e32 v51, v50
	v_mov_b32_e32 v40, v50
	s_waitcnt lgkmcnt(0)
	v_mov_b32_e32 v41, v50
	v_pk_mul_f32 v[38:39], v[38:39], v[40:41]
	v_pk_mul_f32 v[36:37], v[36:37], v[50:51]
	v_pk_mul_f32 v[34:35], v[34:35], v[40:41]
	v_pk_mul_f32 v[32:33], v[32:33], v[50:51]
	s_and_b64 vcc, exec, s[8:9]
	v_cvt_pk_bf16_f32 v40, v36, v37
	v_cvt_pk_bf16_f32 v41, v38, v39
	v_cvt_pk_bf16_f32 v42, v32, v33
	v_cvt_pk_bf16_f32 v43, v34, v35
	global_store_dwordx4 v[48:49], v[40:43], off offset:256
	s_cbranch_vccnz .LBB0_706
	v_mul_f32_e32 v33, v33, v33
	v_fmac_f32_e32 v33, v32, v32
	v_mul_f32_e32 v32, v35, v35
	v_mul_f32_e32 v37, v37, v37
	v_fmac_f32_e32 v32, v34, v34
	v_and_b32_e32 v34, 64, v163
	v_fmac_f32_e32 v37, v36, v36
	v_mul_f32_e32 v36, v39, v39
	v_add_f32_e32 v32, v33, v32
	v_xor_b32_e32 v33, 16, v163
	v_add_u32_e32 v34, 64, v34
	v_fmac_f32_e32 v36, v38, v38
	v_cmp_lt_i32_e32 vcc, v33, v34
	v_add_f32_e32 v36, v37, v36
	v_add_f32_e32 v32, v36, v32
	v_cndmask_b32_e32 v33, v163, v33, vcc
	v_lshlrev_b32_e32 v33, 2, v33
	v_mov_b32_e32 v33, v32
	s_nop 1
	v_permlane16_swap_b32_e32 v33, v32
	s_waitcnt lgkmcnt(0)
	v_add_f32_e32 v32, v32, v33
	v_xor_b32_e32 v33, 32, v163
	v_cmp_lt_i32_e32 vcc, v33, v34
	s_nop 1
	v_cndmask_b32_e32 v33, v163, v33, vcc
	v_lshlrev_b32_e32 v33, 2, v33
	v_mov_b32_e32 v33, v32
	s_nop 1
	v_permlane32_swap_b32_e32 v33, v32
	s_and_saveexec_b64 s[52:53], s[4:5]
	s_cbranch_execz .LBB0_705
	s_lshl_b32 s1, s0, 18
	s_add_i32 s10, s1, s86
	s_lshl_b64 s[12:13], s[10:11], 2
	s_add_u32 s12, s81, s12
	s_addc_u32 s13, s82, s13
	s_waitcnt lgkmcnt(0)
	v_add_f32_e32 v34, v32, v33
	v_lshl_add_u64 v[32:33], v[148:149], 2, s[12:13]
	global_store_dword v[32:33], v34, off offset:576

.LBB0_706:
	s_nop 1
	v_mov_b32_e32 v34, v184
	v_add_u32_e32 v35, 0xa0, v148
	s_waitcnt lgkmcnt(0)
	v_mov_b64_e32 v[32:33], s[16:17]
	v_mad_i64_i32 v[32:33], s[12:13], v35, s92, v[32:33]
	v_lshl_add_u64 v[32:33], v[150:151], 1, v[32:33]
	v_pk_mul_f32 v[30:31], v[30:31], v[34:35] op_sel_hi:[1,0]
	v_pk_mul_f32 v[28:29], v[28:29], v[34:35] op_sel_hi:[1,0]
	v_pk_mul_f32 v[26:27], v[26:27], v[34:35] op_sel_hi:[1,0]
	v_pk_mul_f32 v[24:25], v[24:25], v[34:35] op_sel_hi:[1,0]
	s_and_b64 vcc, exec, s[8:9]
	v_cvt_pk_bf16_f32 v36, v28, v29
	v_cvt_pk_bf16_f32 v37, v30, v31
	v_cvt_pk_bf16_f32 v38, v24, v25
	v_cvt_pk_bf16_f32 v39, v26, v27
	global_store_dwordx4 v[32:33], v[36:39], off
	s_cbranch_vccnz .LBB0_710
	v_mul_f32_e32 v25, v25, v25
	v_fmac_f32_e32 v25, v24, v24
	v_mul_f32_e32 v24, v27, v27
	v_mul_f32_e32 v29, v29, v29
	v_fmac_f32_e32 v24, v26, v26
	v_and_b32_e32 v26, 64, v163
	v_fmac_f32_e32 v29, v28, v28
	v_mul_f32_e32 v28, v31, v31
	v_add_f32_e32 v24, v25, v24
	v_xor_b32_e32 v25, 16, v163
	v_add_u32_e32 v26, 64, v26
	v_fmac_f32_e32 v28, v30, v30
	v_cmp_lt_i32_e32 vcc, v25, v26
	v_add_f32_e32 v28, v29, v28
	v_add_f32_e32 v24, v28, v24
	v_cndmask_b32_e32 v25, v163, v25, vcc
	v_lshlrev_b32_e32 v25, 2, v25
	v_mov_b32_e32 v25, v24
	s_nop 1
	v_permlane16_swap_b32_e32 v25, v24
	s_waitcnt lgkmcnt(0)
	v_add_f32_e32 v24, v24, v25
	v_xor_b32_e32 v25, 32, v163
	v_cmp_lt_i32_e32 vcc, v25, v26
	s_nop 1
	v_cndmask_b32_e32 v25, v163, v25, vcc
	v_lshlrev_b32_e32 v25, 2, v25
	v_mov_b32_e32 v25, v24
	s_nop 1
	v_permlane32_swap_b32_e32 v25, v24
	s_and_saveexec_b64 s[52:53], s[4:5]
	s_cbranch_execz .LBB0_709
	s_lshl_b32 s1, s0, 18
	s_add_i32 s10, s1, s85
	s_lshl_b64 s[12:13], s[10:11], 2
	s_add_u32 s12, s81, s12
	s_addc_u32 s13, s82, s13
	s_waitcnt lgkmcnt(0)
	v_add_f32_e32 v26, v24, v25
	v_lshl_add_u64 v[24:25], v[148:149], 2, s[12:13]
	global_store_dword v[24:25], v26, off offset:640

.LBB0_710:
	v_mov_b32_e32 v35, v34
	v_mov_b32_e32 v24, v34
	s_waitcnt lgkmcnt(0)
	v_mov_b32_e32 v25, v34
	v_pk_mul_f32 v[22:23], v[22:23], v[24:25]
	v_pk_mul_f32 v[20:21], v[20:21], v[34:35]
	v_pk_mul_f32 v[18:19], v[18:19], v[24:25]
	v_pk_mul_f32 v[16:17], v[16:17], v[34:35]
	s_and_b64 vcc, exec, s[8:9]
	v_cvt_pk_bf16_f32 v24, v20, v21
	v_cvt_pk_bf16_f32 v25, v22, v23
	v_cvt_pk_bf16_f32 v26, v16, v17
	v_cvt_pk_bf16_f32 v27, v18, v19
	global_store_dwordx4 v[32:33], v[24:27], off offset:256
	s_cbranch_vccnz .LBB0_714
	v_mul_f32_e32 v17, v17, v17
	v_fmac_f32_e32 v17, v16, v16
	v_mul_f32_e32 v16, v19, v19
	v_mul_f32_e32 v21, v21, v21
	v_fmac_f32_e32 v16, v18, v18
	v_and_b32_e32 v18, 64, v163
	v_fmac_f32_e32 v21, v20, v20
	v_mul_f32_e32 v20, v23, v23
	v_add_f32_e32 v16, v17, v16
	v_xor_b32_e32 v17, 16, v163
	v_add_u32_e32 v18, 64, v18
	v_fmac_f32_e32 v20, v22, v22
	v_cmp_lt_i32_e32 vcc, v17, v18
	v_add_f32_e32 v20, v21, v20
	v_add_f32_e32 v16, v20, v16
	v_cndmask_b32_e32 v17, v163, v17, vcc
	v_lshlrev_b32_e32 v17, 2, v17
	v_mov_b32_e32 v17, v16
	s_nop 1
	v_permlane16_swap_b32_e32 v17, v16
	s_waitcnt lgkmcnt(0)
	v_add_f32_e32 v16, v16, v17
	v_xor_b32_e32 v17, 32, v163
	v_cmp_lt_i32_e32 vcc, v17, v18
	s_nop 1
	v_cndmask_b32_e32 v17, v163, v17, vcc
	v_lshlrev_b32_e32 v17, 2, v17
	v_mov_b32_e32 v17, v16
	s_nop 1
	v_permlane32_swap_b32_e32 v17, v16
	s_and_saveexec_b64 s[52:53], s[4:5]
	s_cbranch_execz .LBB0_713
	s_lshl_b32 s1, s0, 18
	s_add_i32 s10, s1, s86
	s_lshl_b64 s[12:13], s[10:11], 2
	s_add_u32 s12, s81, s12
	s_addc_u32 s13, s82, s13
	s_waitcnt lgkmcnt(0)
	v_add_f32_e32 v18, v16, v17
	v_lshl_add_u64 v[16:17], v[148:149], 2, s[12:13]
	global_store_dword v[16:17], v18, off offset:640

.LBB0_714:
	s_nop 1
	v_mov_b32_e32 v18, v186
	v_add_u32_e32 v19, 0xb0, v148
	s_waitcnt lgkmcnt(0)
	v_mov_b64_e32 v[16:17], s[16:17]
	v_mad_i64_i32 v[16:17], s[12:13], v19, s92, v[16:17]
	v_lshl_add_u64 v[16:17], v[150:151], 1, v[16:17]
	v_pk_mul_f32 v[14:15], v[14:15], v[18:19] op_sel_hi:[1,0]
	v_pk_mul_f32 v[12:13], v[12:13], v[18:19] op_sel_hi:[1,0]
	v_pk_mul_f32 v[10:11], v[10:11], v[18:19] op_sel_hi:[1,0]
	v_pk_mul_f32 v[8:9], v[8:9], v[18:19] op_sel_hi:[1,0]
	s_and_b64 vcc, exec, s[8:9]
	v_cvt_pk_bf16_f32 v20, v12, v13
	v_cvt_pk_bf16_f32 v21, v14, v15
	v_cvt_pk_bf16_f32 v22, v8, v9
	v_cvt_pk_bf16_f32 v23, v10, v11
	global_store_dwordx4 v[16:17], v[20:23], off
	s_cbranch_vccnz .LBB0_718
	v_mul_f32_e32 v9, v9, v9
	v_fmac_f32_e32 v9, v8, v8
	v_mul_f32_e32 v8, v11, v11
	v_mul_f32_e32 v13, v13, v13
	v_fmac_f32_e32 v8, v10, v10
	v_and_b32_e32 v10, 64, v163
	v_fmac_f32_e32 v13, v12, v12
	v_mul_f32_e32 v12, v15, v15
	v_add_f32_e32 v8, v9, v8
	v_xor_b32_e32 v9, 16, v163
	v_add_u32_e32 v10, 64, v10
	v_fmac_f32_e32 v12, v14, v14
	v_cmp_lt_i32_e32 vcc, v9, v10
	v_add_f32_e32 v12, v13, v12
	v_add_f32_e32 v8, v12, v8
	v_cndmask_b32_e32 v9, v163, v9, vcc
	v_lshlrev_b32_e32 v9, 2, v9
	v_mov_b32_e32 v9, v8
	s_nop 1
	v_permlane16_swap_b32_e32 v9, v8
	s_waitcnt lgkmcnt(0)
	v_add_f32_e32 v8, v8, v9
	v_xor_b32_e32 v9, 32, v163
	v_cmp_lt_i32_e32 vcc, v9, v10
	s_nop 1
	v_cndmask_b32_e32 v9, v163, v9, vcc
	v_lshlrev_b32_e32 v9, 2, v9
	v_mov_b32_e32 v9, v8
	s_nop 1
	v_permlane32_swap_b32_e32 v9, v8
	s_and_saveexec_b64 s[52:53], s[4:5]
	s_cbranch_execz .LBB0_717
	s_lshl_b32 s1, s0, 18
	s_add_i32 s10, s1, s85
	s_lshl_b64 s[12:13], s[10:11], 2
	s_add_u32 s12, s81, s12
	s_addc_u32 s13, s82, s13
	s_waitcnt lgkmcnt(0)
	v_add_f32_e32 v10, v8, v9
	v_lshl_add_u64 v[8:9], v[148:149], 2, s[12:13]
	global_store_dword v[8:9], v10, off offset:704

.LBB0_718:
	v_mov_b32_e32 v19, v18
	v_mov_b32_e32 v8, v18
	s_waitcnt lgkmcnt(0)
	v_mov_b32_e32 v9, v18
	v_pk_mul_f32 v[6:7], v[6:7], v[8:9]
	v_pk_mul_f32 v[4:5], v[4:5], v[18:19]
	v_pk_mul_f32 v[2:3], v[2:3], v[8:9]
	v_pk_mul_f32 v[0:1], v[0:1], v[18:19]
	s_and_b64 vcc, exec, s[8:9]
	v_cvt_pk_bf16_f32 v8, v4, v5
	v_cvt_pk_bf16_f32 v9, v6, v7
	v_cvt_pk_bf16_f32 v10, v0, v1
	v_cvt_pk_bf16_f32 v11, v2, v3
	global_store_dwordx4 v[16:17], v[8:11], off offset:256
	s_cbranch_vccnz .LBB0_722
	v_mul_f32_e32 v1, v1, v1
	v_fmac_f32_e32 v1, v0, v0
	v_mul_f32_e32 v0, v3, v3
	v_mul_f32_e32 v5, v5, v5
	v_fmac_f32_e32 v0, v2, v2
	v_and_b32_e32 v2, 64, v163
	v_fmac_f32_e32 v5, v4, v4
	v_mul_f32_e32 v4, v7, v7
	v_add_f32_e32 v0, v1, v0
	v_xor_b32_e32 v1, 16, v163
	v_add_u32_e32 v2, 64, v2
	v_fmac_f32_e32 v4, v6, v6
	v_cmp_lt_i32_e32 vcc, v1, v2
	v_add_f32_e32 v4, v5, v4
	v_add_f32_e32 v0, v4, v0
	v_cndmask_b32_e32 v1, v163, v1, vcc
	v_lshlrev_b32_e32 v1, 2, v1
	v_mov_b32_e32 v1, v0
	s_nop 1
	v_permlane16_swap_b32_e32 v1, v0
	s_waitcnt lgkmcnt(0)
	v_add_f32_e32 v0, v0, v1
	v_xor_b32_e32 v1, 32, v163
	v_cmp_lt_i32_e32 vcc, v1, v2
	s_nop 1
	v_cndmask_b32_e32 v1, v163, v1, vcc
	v_lshlrev_b32_e32 v1, 2, v1
	v_mov_b32_e32 v1, v0
	s_nop 1
	v_permlane32_swap_b32_e32 v1, v0
	s_and_saveexec_b64 s[8:9], s[4:5]
	s_cbranch_execz .LBB0_721
	s_lshl_b32 s0, s0, 18
	s_add_i32 s10, s0, s86
	s_lshl_b64 s[0:1], s[10:11], 2
	s_add_u32 s0, s81, s0
	s_addc_u32 s1, s82, s1
	s_waitcnt lgkmcnt(0)
	v_add_f32_e32 v2, v0, v1
	v_lshl_add_u64 v[0:1], v[148:149], 2, s[0:1]
	global_store_dword v[0:1], v2, off offset:704

.Lmy_slide_done:
	v_lshlrev_b32_e32 v44, 16, v4
	v_and_b32_e32 v45, 0xffff0000, v4
	v_add_f32_e32 v50, v50, v54
	v_pk_mul_f32 v[60:61], v[44:45], v[44:45]
	v_add_f32_e32 v50, v51, v50
	v_lshlrev_b32_e32 v40, 16, v5
	v_and_b32_e32 v41, 0xffff0000, v5
	v_add_f32_e32 v50, v60, v50
	v_pk_mul_f32 v[56:57], v[40:41], v[40:41]
	v_add_f32_e32 v50, v61, v50
	v_lshlrev_b32_e32 v36, 16, v6
	v_and_b32_e32 v37, 0xffff0000, v6
	v_add_f32_e32 v50, v56, v50
	v_pk_mul_f32 v[52:53], v[36:37], v[36:37]
	v_add_f32_e32 v50, v57, v50
	v_lshlrev_b32_e32 v32, 16, v7
	v_and_b32_e32 v33, 0xffff0000, v7
	v_add_f32_e32 v50, v52, v50
	v_pk_mul_f32 v[48:49], v[32:33], v[32:33]
	v_add_f32_e32 v50, v53, v50
	v_add_f32_e32 v48, v48, v50
	v_add_f32_e32 v48, v49, v48
	v_mov_b32_e32 v49, v48
	s_nop 1
	v_permlane16_swap_b32_e32 v49, v48
	s_andn2_b64 vcc, exec, s[58:59]
	s_waitcnt lgkmcnt(0)
	v_add_f32_e32 v48, v48, v49
	v_mov_b32_e32 v49, v48
	s_nop 1
	v_permlane32_swap_b32_e32 v49, v48
	s_cbranch_vccnz .LBB0_821
	global_load_dwordx4 v[0:3], v[92:93], off
	global_load_dwordx4 v[4:7], v[92:93], off offset:64

.LBB0_887:
	s_add_i32 s34, s66, s62
	v_add_u32_e32 v81, s34, v72
	ds_read_b128 v[158:161], v81 offset:16384
	ds_read_b128 v[162:165], v81 offset:16448
	s_add_i32 s34, s66, s85
	s_addk_i32 s62, 0x2000
	s_addk_i32 s85, 0x2000
	s_waitcnt lgkmcnt(1)
	v_fma_f32 v60, v60, v158, v121
	v_fma_f32 v61, v61, v159, v120
	v_exp_f32_e32 v81, v60
	v_fma_f32 v62, v62, v160, v123
	v_exp_f32_e32 v83, v61
	v_fma_f32 v63, v63, v161, v122
	v_exp_f32_e32 v89, v62
	v_exp_f32_e32 v155, v63
	s_waitcnt lgkmcnt(0)
	v_fma_f32 v56, v56, v162, v125
	v_add_f32_e32 v60, 0, v81
	v_exp_f32_e32 v157, v56
	v_add_f32_e32 v56, v83, v60
	v_add_f32_e32 v56, v89, v56
	v_add_f32_e32 v56, v155, v56
	v_add_f32_e32 v158, v157, v56
	v_fma_f32 v56, v57, v163, v124
	v_add_u32_e32 v57, s34, v72
	ds_read_b128 v[60:63], v57 offset:16384
	v_exp_f32_e32 v192, v56
	v_fma_f32 v56, v58, v164, v127
	v_exp_f32_e32 v193, v56
	v_fma_f32 v56, v59, v165, v126
	v_exp_f32_e32 v194, v56
	ds_read_b128 v[56:59], v57 offset:16448
	s_waitcnt lgkmcnt(1)
	v_fma_f32 v52, v52, v60, v132
	v_exp_f32_e32 v195, v52
	v_fma_f32 v53, v53, v61, v131
	v_add_f32_e32 v52, v192, v158
	v_exp_f32_e32 v196, v53
	v_fma_f32 v53, v54, v62, v134
	v_add_f32_e32 v52, v193, v52
	v_exp_f32_e32 v197, v53
	v_fma_f32 v53, v55, v63, v133
	v_add_f32_e32 v52, v194, v52
	v_exp_f32_e32 v198, v53
	s_waitcnt lgkmcnt(0)
	v_fma_f32 v48, v48, v56, v136
	v_add_f32_e32 v52, v195, v52
	v_exp_f32_e32 v199, v48
	v_add_f32_e32 v48, v196, v52
	v_add_f32_e32 v48, v197, v48
	v_add_f32_e32 v48, v198, v48
	s_add_i32 s34, s66, s63
	v_add_f32_e32 v56, v199, v48
	v_fma_f32 v48, v49, v57, v135
	v_add_u32_e32 v49, s34, v72
	ds_read_b128 v[52:55], v49 offset:16384
	v_exp_f32_e32 v200, v48
	v_fma_f32 v48, v50, v58, v138
	v_exp_f32_e32 v201, v48
	v_fma_f32 v48, v51, v59, v137
	v_exp_f32_e32 v202, v48
	ds_read_b128 v[48:51], v49 offset:16448
	s_waitcnt lgkmcnt(1)
	v_fma_f32 v44, v44, v52, v140
	v_exp_f32_e32 v203, v44
	v_fma_f32 v45, v45, v53, v139
	v_add_f32_e32 v44, v200, v56
	v_exp_f32_e32 v204, v45
	v_fma_f32 v45, v46, v54, v142
	v_add_f32_e32 v44, v201, v44
	v_exp_f32_e32 v205, v45
	v_fma_f32 v45, v47, v55, v141
	v_add_f32_e32 v44, v202, v44
	v_exp_f32_e32 v206, v45
	s_waitcnt lgkmcnt(0)
	v_fma_f32 v40, v40, v48, v144
	v_add_f32_e32 v44, v203, v44
	v_exp_f32_e32 v207, v40
	v_add_f32_e32 v40, v204, v44
	v_add_f32_e32 v40, v205, v40
	v_add_f32_e32 v40, v206, v40
	v_add_f32_e32 v44, v207, v40
	v_fma_f32 v40, v41, v49, v143
	v_exp_f32_e32 v208, v40
	v_fma_f32 v40, v42, v50, v146
	s_add_i32 s34, s66, s22
	v_exp_f32_e32 v209, v40
	v_fma_f32 v40, v43, v51, v145
	v_add_u32_e32 v45, s34, v72
	v_exp_f32_e32 v210, v40
	ds_read_b128 v[40:43], v45 offset:16384
	v_add_f32_e32 v44, v208, v44
	v_add_f32_e32 v44, v209, v44
	v_add_f32_e32 v48, v210, v44
	ds_read_b128 v[44:47], v45 offset:16448
	s_waitcnt lgkmcnt(1)
	v_fma_f32 v36, v36, v40, v148
	v_exp_f32_e32 v211, v36
	v_fma_f32 v36, v37, v41, v147
	v_exp_f32_e32 v212, v36
	v_fma_f32 v36, v38, v42, v150
	v_exp_f32_e32 v213, v36
	v_fma_f32 v36, v39, v43, v149
	v_exp_f32_e32 v214, v36
	s_waitcnt lgkmcnt(0)
	v_fma_f32 v32, v32, v44, v152
	v_add_f32_e32 v36, v211, v48
	v_exp_f32_e32 v215, v32
	v_fma_f32 v32, v33, v45, v151
	v_add_f32_e32 v36, v212, v36
	v_exp_f32_e32 v216, v32
	v_fma_f32 v32, v34, v46, v154
	v_add_f32_e32 v36, v213, v36
	v_exp_f32_e32 v217, v32
	v_fma_f32 v32, v35, v47, v153
	v_add_f32_e32 v36, v214, v36
	v_exp_f32_e32 v218, v32
	v_add_f32_e32 v32, v215, v36
	v_add_f32_e32 v32, v216, v32
	v_add_f32_e32 v32, v217, v32
	v_add_f32_e32 v32, v218, v32
	v_mov_b32_e32 v33, v32
	s_nop 1
	v_permlane16_swap_b32_e32 v33, v32
	v_or_b32_e32 v48, s85, v99
	v_add_u32_e32 v60, v48, v100
	v_add_u32_e32 v61, v48, v101
	v_add_u32_e32 v48, v60, v114
	s_waitcnt lgkmcnt(0)
	v_add_f32_e32 v219, v32, v33
	v_or_b32_e32 v32, s62, v99
	v_add_u32_e32 v44, v32, v100
	v_add_u32_e32 v45, v32, v101
	v_add_u32_e32 v32, v44, v114
	v_add_u32_e32 v34, v45, v114
	ds_read_b64_tr_b16 v[32:33], v32
	ds_read_b64_tr_b16 v[34:35], v34
	v_add_u32_e32 v36, v44, v115
	v_add_u32_e32 v38, v45, v115
	ds_read_b64_tr_b16 v[36:37], v36
	ds_read_b64_tr_b16 v[38:39], v38
	v_add_u32_e32 v40, v44, v116
	v_add_u32_e32 v42, v45, v116
	ds_read_b64_tr_b16 v[40:41], v40
	ds_read_b64_tr_b16 v[42:43], v42
	v_add_u32_e32 v44, v44, v117
	v_add_u32_e32 v46, v45, v117
	ds_read_b64_tr_b16 v[44:45], v44
	ds_read_b64_tr_b16 v[46:47], v46
	v_add_u32_e32 v50, v61, v114
	ds_read_b64_tr_b16 v[48:49], v48
	ds_read_b64_tr_b16 v[50:51], v50
	v_add_u32_e32 v52, v60, v115
	v_add_u32_e32 v54, v61, v115
	ds_read_b64_tr_b16 v[52:53], v52
	ds_read_b64_tr_b16 v[54:55], v54
	v_add_u32_e32 v56, v60, v116
	v_add_u32_e32 v58, v61, v116
	ds_read_b64_tr_b16 v[56:57], v56
	s_addk_i32 s63, 0x2000
	ds_read_b64_tr_b16 v[58:59], v58
	v_add_u32_e32 v60, v60, v117
	v_or_b32_e32 v158, s63, v99
	v_add_u32_e32 v62, v61, v117
	ds_read_b64_tr_b16 v[60:61], v60
	v_add_u32_e32 v170, v158, v100
	ds_read_b64_tr_b16 v[62:63], v62
	v_add_u32_e32 v171, v158, v101
	v_add_u32_e32 v158, v170, v114
	v_add_u32_e32 v160, v171, v114
	ds_read_b64_tr_b16 v[158:159], v158
	ds_read_b64_tr_b16 v[160:161], v160
	v_add_u32_e32 v162, v170, v115
	v_add_u32_e32 v164, v171, v115
	ds_read_b64_tr_b16 v[162:163], v162
	ds_read_b64_tr_b16 v[164:165], v164
	v_add_u32_e32 v166, v170, v116
	v_add_u32_e32 v168, v171, v116
	ds_read_b64_tr_b16 v[166:167], v166
	s_addk_i32 s22, 0x2000
	ds_read_b64_tr_b16 v[168:169], v168
	v_add_u32_e32 v170, v170, v117
	v_or_b32_e32 v174, s22, v99
	v_add_u32_e32 v172, v171, v117
	ds_read_b64_tr_b16 v[170:171], v170
	v_add_u32_e32 v186, v174, v100
	ds_read_b64_tr_b16 v[172:173], v172
	v_add_u32_e32 v187, v174, v101
	v_add_u32_e32 v174, v186, v114
	v_add_u32_e32 v176, v187, v114
	ds_read_b64_tr_b16 v[174:175], v174
	ds_read_b64_tr_b16 v[176:177], v176
	v_add_u32_e32 v178, v186, v115
	v_add_u32_e32 v180, v187, v115
	ds_read_b64_tr_b16 v[178:179], v178
	ds_read_b64_tr_b16 v[180:181], v180
	v_add_u32_e32 v182, v186, v116
	v_add_u32_e32 v184, v187, v116
	ds_read_b64_tr_b16 v[182:183], v182
	ds_read_b64_tr_b16 v[184:185], v184
	v_add_u32_e32 v186, v186, v117
	v_add_u32_e32 v188, v187, v117
	ds_read_b64_tr_b16 v[186:187], v186
	ds_read_b64_tr_b16 v[188:189], v188
	s_waitcnt lgkmcnt(0)
	ds_bpermute_b32 v220, v98, v219
	v_cvt_pk_bf16_f32 v190, v81, v83
	v_cvt_pk_bf16_f32 v191, v89, v155
	v_cvt_pk_bf16_f32 v192, v157, v192
	v_cvt_pk_bf16_f32 v193, v193, v194
	v_cvt_pk_bf16_f32 v194, v195, v196
	v_cvt_pk_bf16_f32 v195, v197, v198
	v_cvt_pk_bf16_f32 v196, v199, v200
	v_cvt_pk_bf16_f32 v197, v201, v202
	v_cvt_pk_bf16_f32 v198, v203, v204
	v_cvt_pk_bf16_f32 v199, v205, v206
	v_cvt_pk_bf16_f32 v200, v207, v208
	v_cvt_pk_bf16_f32 v201, v209, v210
	v_cvt_pk_bf16_f32 v202, v211, v212
	v_cvt_pk_bf16_f32 v203, v213, v214
	v_cvt_pk_bf16_f32 v204, v215, v216
	v_cvt_pk_bf16_f32 v205, v217, v218
	v_mfma_f32_16x16x32_bf16 v[32:35], v[32:35], v[190:193], 0
	s_andn2_b64 vcc, exec, s[26:27]
	v_mfma_f32_16x16x32_bf16 v[36:39], v[36:39], v[190:193], 0
	v_mfma_f32_16x16x32_bf16 v[40:43], v[40:43], v[190:193], 0
	v_mfma_f32_16x16x32_bf16 v[44:47], v[44:47], v[190:193], 0
	v_mfma_f32_16x16x32_bf16 v[32:35], v[48:51], v[194:197], v[32:35]
	v_mfma_f32_16x16x32_bf16 v[36:39], v[52:55], v[194:197], v[36:39]
	v_mfma_f32_16x16x32_bf16 v[40:43], v[56:59], v[194:197], v[40:43]
	v_mfma_f32_16x16x32_bf16 v[44:47], v[60:63], v[194:197], v[44:47]
	v_mfma_f32_16x16x32_bf16 v[32:35], v[158:161], v[198:201], v[32:35]
	v_mfma_f32_16x16x32_bf16 v[36:39], v[162:165], v[198:201], v[36:39]
	v_mfma_f32_16x16x32_bf16 v[48:51], v[166:169], v[198:201], v[40:43]
	v_mfma_f32_16x16x32_bf16 v[52:55], v[170:173], v[198:201], v[44:47]
	v_mfma_f32_16x16x32_bf16 v[44:47], v[174:177], v[202:205], v[32:35]
	v_mfma_f32_16x16x32_bf16 v[40:43], v[178:181], v[202:205], v[36:39]
	v_mfma_f32_16x16x32_bf16 v[36:39], v[182:185], v[202:205], v[48:51]
	v_mfma_f32_16x16x32_bf16 v[32:35], v[186:189], v[202:205], v[52:55]
	s_waitcnt lgkmcnt(0)
	s_nop 1
	v_add_f32_e32 v48, v219, v220
	s_cbranch_vccnz .LBB0_889
	ds_write_b128 v118, v[44:47]
	ds_write_b128 v118, v[40:43] offset:1024
	ds_write_b128 v118, v[36:39] offset:2048
	ds_write_b128 v118, v[32:35] offset:3072
	ds_write_b32 v119, v48 offset:4096

.LBB0_972:
	v_lshl_add_u32 v150, s38, 8, v131
	v_ashrrev_i32_e32 v151, 31, v150
	v_lshl_or_b32 v148, s0, 8, v153
	v_lshlrev_b64 v[160:161], 11, v[150:151]
	v_ashrrev_i32_e32 v149, 31, v148
	v_lshl_add_u64 v[160:161], s[14:15], 0, v[160:161]
	v_lshl_add_u64 v[164:165], v[148:149], 1, v[160:161]
	v_mov_b32_e32 v232, v164
	v_mov_b32_e32 v233, v165
	global_load_dwordx4 v[188:191], v[232:233], off
	global_load_dwordx4 v[192:195], v[232:233], off offset:256
	s_mov_b64 s[100:101], 0x8000
	v_lshl_add_u64 v[230:231], v[232:233], 0, s[100:101]
	global_load_dwordx4 v[196:199], v[230:231], off
	global_load_dwordx4 v[200:203], v[230:231], off offset:256
	s_mov_b64 s[100:101], 0x10000
	v_lshl_add_u64 v[230:231], v[232:233], 0, s[100:101]
	global_load_dwordx4 v[204:207], v[230:231], off
	global_load_dwordx4 v[208:211], v[230:231], off offset:256
	s_mov_b64 s[100:101], 0x18000
	v_lshl_add_u64 v[230:231], v[232:233], 0, s[100:101]
	global_load_dwordx4 v[212:215], v[230:231], off
	global_load_dwordx4 v[216:219], v[230:231], off offset:256
	v_and_b32_e32 v170, 64, v158
	v_add_u32_e32 v170, 64, v170
	v_xor_b32_e32 v171, 32, v158
	s_lshl_b32 s38, s0, 2
	s_ashr_i32 s39, s38, 31
	s_waitcnt vmcnt(7)
	v_lshlrev_b32_e32 v159, 16, v188
	v_and_b32_e32 v160, 0xffff0000, v188
	v_lshlrev_b32_e32 v166, 16, v189
	v_and_b32_e32 v161, 0xffff0000, v189
	v_lshlrev_b32_e32 v167, 16, v190
	v_and_b32_e32 v162, 0xffff0000, v190
	v_lshlrev_b32_e32 v168, 16, v191
	v_and_b32_e32 v163, 0xffff0000, v191
	v_add_f32_e32 v159, v124, v159
	v_add_f32_e32 v169, v125, v160
	v_add_f32_e32 v126, v126, v166
	v_add_f32_e32 v127, v127, v161
	v_add_f32_e32 v166, v120, v167
	v_add_f32_e32 v121, v121, v162
	v_add_f32_e32 v167, v122, v168
	v_add_f32_e32 v168, v123, v163
	v_cvt_pk_bf16_f32 v122, v159, v169
	v_cvt_pk_bf16_f32 v123, v126, v127
	v_cvt_pk_bf16_f32 v124, v166, v121
	v_cvt_pk_bf16_f32 v125, v167, v168
	v_mul_f32_e32 v169, v169, v169
	v_mul_f32_e32 v127, v127, v127
	v_mul_f32_e32 v121, v121, v121
	v_mul_f32_e32 v168, v168, v168
	v_fmac_f32_e32 v169, v159, v159
	v_fmac_f32_e32 v127, v126, v126
	v_fmac_f32_e32 v121, v166, v166
	v_fmac_f32_e32 v168, v167, v167
	v_add_f32_e32 v126, v169, v127
	v_add_f32_e32 v121, v121, v168
	v_add_f32_e32 v121, v126, v121
	v_xor_b32_e32 v120, 16, v158
	v_cmp_lt_i32_e32 vcc, v120, v170
	global_store_dwordx4 v[164:165], v[122:125], off
	s_waitcnt vmcnt(7)
	v_lshlrev_b32_e32 v126, 16, v192
	v_and_b32_e32 v127, 0xffff0000, v192
	v_lshlrev_b32_e32 v159, 16, v193
	v_and_b32_e32 v160, 0xffff0000, v193
	v_lshlrev_b32_e32 v161, 16, v194
	v_and_b32_e32 v162, 0xffff0000, v194
	v_lshlrev_b32_e32 v166, 16, v195
	v_and_b32_e32 v163, 0xffff0000, v195
	v_add_f32_e32 v117, v117, v127
	v_add_f32_e32 v119, v119, v160
	v_add_f32_e32 v127, v113, v162
	v_add_f32_e32 v115, v115, v163
	v_add_f32_e32 v116, v116, v126
	v_add_f32_e32 v118, v118, v159
	v_add_f32_e32 v126, v112, v161
	v_add_f32_e32 v159, v114, v166
	v_mul_f32_e32 v112, v117, v117
	v_mul_f32_e32 v113, v119, v119
	v_mul_f32_e32 v114, v127, v127
	v_mul_f32_e32 v160, v115, v115
	v_fmac_f32_e32 v112, v116, v116
	v_fmac_f32_e32 v113, v118, v118
	v_fmac_f32_e32 v114, v126, v126
	v_fmac_f32_e32 v160, v159, v159
	v_add_f32_e32 v112, v112, v113
	v_add_f32_e32 v113, v114, v160
	v_cndmask_b32_e32 v120, v158, v120, vcc
	v_add_f32_e32 v112, v112, v113
	v_lshlrev_b32_e32 v120, 2, v120
	v_add_f32_e32 v112, v121, v112
	v_mov_b32_e32 v113, v112
	s_nop 1
	v_permlane16_swap_b32_e32 v113, v112
	v_cmp_lt_i32_e32 vcc, v171, v170
	v_cvt_pk_bf16_f32 v116, v116, v117
	v_cvt_pk_bf16_f32 v117, v118, v119
	v_cvt_pk_bf16_f32 v118, v126, v127
	s_waitcnt lgkmcnt(0)
	v_add_f32_e32 v112, v112, v113
	v_cvt_pk_bf16_f32 v119, v159, v115
	v_cndmask_b32_e32 v114, v158, v171, vcc
	v_lshlrev_b32_e32 v114, 2, v114
	v_mov_b32_e32 v113, v112
	s_nop 1
	v_permlane32_swap_b32_e32 v113, v112
	global_store_dwordx4 v[164:165], v[116:119], off offset:256
	s_and_saveexec_b64 s[40:41], s[4:5]
	s_cbranch_execz .LBB0_974
	v_lshlrev_b64 v[116:117], 6, v[150:151]
	v_lshl_add_u64 v[116:117], s[18:19], 0, v[116:117]
	v_lshl_add_u64 v[116:117], s[38:39], 2, v[116:117]
	s_lshl_b32 s0, s56, 2
	v_lshl_add_u64 v[116:117], v[116:117], 0, s[0:1]
	s_waitcnt lgkmcnt(0)
	v_add_f32_e32 v112, v112, v113
	global_store_dword v[116:117], v112, off
.LBB0_974:
	s_or_b64 exec, exec, s[40:41]
	v_or_b32_e32 v112, 16, v150
	s_waitcnt lgkmcnt(0)
	v_ashrrev_i32_e32 v113, 31, v112
	v_lshlrev_b64 v[116:117], 11, v[112:113]
	v_lshl_add_u64 v[116:117], s[14:15], 0, v[116:117]
	v_lshl_add_u64 v[122:123], v[148:149], 1, v[116:117]
	s_mov_b64 s[100:101], 0x40000
	v_lshl_add_u64 v[230:231], v[232:233], 0, s[100:101]
	global_load_dwordx4 v[188:191], v[230:231], off
	global_load_dwordx4 v[192:195], v[230:231], off offset:256
	s_waitcnt vmcnt(9)
	v_lshlrev_b32_e32 v115, 16, v196
	v_and_b32_e32 v116, 0xffff0000, v196
	v_lshlrev_b32_e32 v121, 16, v197
	v_and_b32_e32 v117, 0xffff0000, v197
	v_lshlrev_b32_e32 v124, 16, v198
	v_and_b32_e32 v118, 0xffff0000, v198
	v_lshlrev_b32_e32 v125, 16, v199
	v_and_b32_e32 v119, 0xffff0000, v199
	v_add_f32_e32 v115, v108, v115
	v_add_f32_e32 v116, v109, v116
	v_add_f32_e32 v121, v110, v121
	v_add_f32_e32 v117, v111, v117
	v_add_f32_e32 v124, v104, v124
	v_add_f32_e32 v118, v105, v118
	v_add_f32_e32 v125, v106, v125
	v_add_f32_e32 v119, v107, v119
	v_cvt_pk_bf16_f32 v104, v115, v116
	v_cvt_pk_bf16_f32 v105, v121, v117
	v_cvt_pk_bf16_f32 v106, v124, v118
	v_cvt_pk_bf16_f32 v107, v125, v119
	v_mul_f32_e32 v116, v116, v116
	v_mul_f32_e32 v117, v117, v117
	v_mul_f32_e32 v118, v118, v118
	v_mul_f32_e32 v119, v119, v119
	v_fmac_f32_e32 v116, v115, v115
	v_fmac_f32_e32 v117, v121, v121
	v_fmac_f32_e32 v118, v124, v124
	v_fmac_f32_e32 v119, v125, v125
	v_add_f32_e32 v115, v116, v117
	v_add_f32_e32 v116, v118, v119
	v_add_f32_e32 v115, v115, v116
	global_store_dwordx4 v[122:123], v[104:107], off
	s_waitcnt vmcnt(9)
	v_lshlrev_b32_e32 v116, 16, v200
	v_and_b32_e32 v108, 0xffff0000, v200
	v_lshlrev_b32_e32 v117, 16, v201
	v_and_b32_e32 v109, 0xffff0000, v201
	v_lshlrev_b32_e32 v118, 16, v202
	v_and_b32_e32 v110, 0xffff0000, v202
	v_lshlrev_b32_e32 v119, 16, v203
	v_and_b32_e32 v111, 0xffff0000, v203
	v_add_f32_e32 v101, v101, v108
	v_add_f32_e32 v103, v103, v109
	v_add_f32_e32 v109, v97, v110
	v_add_f32_e32 v111, v99, v111
	v_add_f32_e32 v100, v100, v116
	v_add_f32_e32 v102, v102, v117
	v_add_f32_e32 v108, v96, v118
	v_add_f32_e32 v110, v98, v119
	v_mul_f32_e32 v96, v101, v101
	v_mul_f32_e32 v97, v103, v103
	v_mul_f32_e32 v98, v109, v109
	v_mul_f32_e32 v99, v111, v111
	v_fmac_f32_e32 v96, v100, v100
	v_fmac_f32_e32 v97, v102, v102
	v_fmac_f32_e32 v98, v108, v108
	v_fmac_f32_e32 v99, v110, v110
	v_add_f32_e32 v96, v96, v97
	v_add_f32_e32 v97, v98, v99
	v_add_f32_e32 v96, v96, v97
	v_add_f32_e32 v96, v115, v96
	v_mov_b32_e32 v97, v96
	s_nop 1
	v_permlane16_swap_b32_e32 v97, v96
	v_cvt_pk_bf16_f32 v98, v100, v101
	v_cvt_pk_bf16_f32 v99, v102, v103
	v_cvt_pk_bf16_f32 v100, v108, v109
	v_cvt_pk_bf16_f32 v101, v110, v111
	s_waitcnt lgkmcnt(0)
	v_add_f32_e32 v96, v96, v97
	v_mov_b32_e32 v97, v96
	s_nop 1
	v_permlane32_swap_b32_e32 v97, v96
	global_store_dwordx4 v[122:123], v[98:101], off offset:256
	s_and_saveexec_b64 s[40:41], s[4:5]
	s_cbranch_execz .LBB0_976
	v_lshlrev_b64 v[98:99], 6, v[112:113]
	v_lshl_add_u64 v[98:99], s[18:19], 0, v[98:99]
	v_lshl_add_u64 v[98:99], s[38:39], 2, v[98:99]
	s_lshl_b32 s0, s56, 2
	v_lshl_add_u64 v[98:99], v[98:99], 0, s[0:1]
	s_waitcnt lgkmcnt(0)
	v_add_f32_e32 v96, v96, v97
	global_store_dword v[98:99], v96, off
.LBB0_976:
	s_or_b64 exec, exec, s[40:41]
	v_or_b32_e32 v96, 32, v150
	s_waitcnt lgkmcnt(0)
	v_ashrrev_i32_e32 v97, 31, v96
	v_lshlrev_b64 v[98:99], 11, v[96:97]
	v_lshl_add_u64 v[98:99], s[14:15], 0, v[98:99]
	v_lshl_add_u64 v[102:103], v[148:149], 1, v[98:99]
	s_mov_b64 s[100:101], 0x48000
	v_lshl_add_u64 v[230:231], v[232:233], 0, s[100:101]
	global_load_dwordx4 v[196:199], v[230:231], off
	global_load_dwordx4 v[200:203], v[230:231], off offset:256
	s_waitcnt vmcnt(11)
	v_lshlrev_b32_e32 v104, 16, v204
	v_and_b32_e32 v98, 0xffff0000, v204
	v_lshlrev_b32_e32 v105, 16, v205
	v_and_b32_e32 v99, 0xffff0000, v205
	v_lshlrev_b32_e32 v106, 16, v206
	v_and_b32_e32 v100, 0xffff0000, v206
	v_lshlrev_b32_e32 v107, 16, v207
	v_and_b32_e32 v101, 0xffff0000, v207
	v_add_f32_e32 v104, v92, v104
	v_add_f32_e32 v98, v93, v98
	v_add_f32_e32 v105, v94, v105
	v_add_f32_e32 v99, v95, v99
	v_add_f32_e32 v106, v88, v106
	v_add_f32_e32 v100, v89, v100
	v_add_f32_e32 v107, v90, v107
	v_add_f32_e32 v101, v91, v101
	v_cvt_pk_bf16_f32 v88, v104, v98
	v_cvt_pk_bf16_f32 v89, v105, v99
	v_cvt_pk_bf16_f32 v90, v106, v100
	v_cvt_pk_bf16_f32 v91, v107, v101
	v_mul_f32_e32 v98, v98, v98
	v_mul_f32_e32 v99, v99, v99
	v_mul_f32_e32 v100, v100, v100
	v_mul_f32_e32 v101, v101, v101
	v_fmac_f32_e32 v98, v104, v104
	v_fmac_f32_e32 v99, v105, v105
	v_fmac_f32_e32 v100, v106, v106
	v_fmac_f32_e32 v101, v107, v107
	v_add_f32_e32 v98, v98, v99
	v_add_f32_e32 v99, v100, v101
	v_add_f32_e32 v98, v98, v99
	global_store_dwordx4 v[102:103], v[88:91], off
	s_waitcnt vmcnt(11)
	v_lshlrev_b32_e32 v99, 16, v208
	v_and_b32_e32 v92, 0xffff0000, v208
	v_lshlrev_b32_e32 v100, 16, v209
	v_and_b32_e32 v93, 0xffff0000, v209
	v_lshlrev_b32_e32 v101, 16, v210
	v_and_b32_e32 v94, 0xffff0000, v210
	v_lshlrev_b32_e32 v104, 16, v211
	v_and_b32_e32 v95, 0xffff0000, v211
	v_add_f32_e32 v85, v85, v92
	v_add_f32_e32 v87, v87, v93
	v_add_f32_e32 v93, v81, v94
	v_add_f32_e32 v95, v83, v95
	v_add_f32_e32 v84, v84, v99
	v_add_f32_e32 v86, v86, v100
	v_add_f32_e32 v92, v80, v101
	v_add_f32_e32 v94, v82, v104
	v_mul_f32_e32 v80, v85, v85
	v_mul_f32_e32 v81, v87, v87
	v_mul_f32_e32 v82, v93, v93
	v_mul_f32_e32 v83, v95, v95
	v_fmac_f32_e32 v80, v84, v84
	v_fmac_f32_e32 v81, v86, v86
	v_fmac_f32_e32 v82, v92, v92
	v_fmac_f32_e32 v83, v94, v94
	v_add_f32_e32 v80, v80, v81
	v_add_f32_e32 v81, v82, v83
	v_add_f32_e32 v80, v80, v81
	v_add_f32_e32 v80, v98, v80
	v_mov_b32_e32 v81, v80
	s_nop 1
	v_permlane16_swap_b32_e32 v81, v80
	v_cvt_pk_bf16_f32 v82, v84, v85
	v_cvt_pk_bf16_f32 v83, v86, v87
	v_cvt_pk_bf16_f32 v84, v92, v93
	v_cvt_pk_bf16_f32 v85, v94, v95
	s_waitcnt lgkmcnt(0)
	v_add_f32_e32 v80, v80, v81
	v_mov_b32_e32 v81, v80
	s_nop 1
	v_permlane32_swap_b32_e32 v81, v80
	global_store_dwordx4 v[102:103], v[82:85], off offset:256
	s_and_saveexec_b64 s[40:41], s[4:5]
	s_cbranch_execz .LBB0_978
	v_lshlrev_b64 v[82:83], 6, v[96:97]
	v_lshl_add_u64 v[82:83], s[18:19], 0, v[82:83]
	v_lshl_add_u64 v[82:83], s[38:39], 2, v[82:83]
	s_lshl_b32 s0, s56, 2
	v_lshl_add_u64 v[82:83], v[82:83], 0, s[0:1]
	s_waitcnt lgkmcnt(0)
	v_add_f32_e32 v80, v80, v81
	global_store_dword v[82:83], v80, off
.LBB0_978:
	s_or_b64 exec, exec, s[40:41]
	v_or_b32_e32 v80, 48, v150
	s_waitcnt lgkmcnt(0)
	v_ashrrev_i32_e32 v81, 31, v80
	v_lshlrev_b64 v[82:83], 11, v[80:81]
	v_lshl_add_u64 v[82:83], s[14:15], 0, v[82:83]
	v_lshl_add_u64 v[86:87], v[148:149], 1, v[82:83]
	s_mov_b64 s[100:101], 0x50000
	v_lshl_add_u64 v[230:231], v[232:233], 0, s[100:101]
	global_load_dwordx4 v[204:207], v[230:231], off
	global_load_dwordx4 v[208:211], v[230:231], off offset:256
	s_waitcnt vmcnt(13)
	v_lshlrev_b32_e32 v88, 16, v212
	v_and_b32_e32 v82, 0xffff0000, v212
	v_lshlrev_b32_e32 v89, 16, v213
	v_and_b32_e32 v83, 0xffff0000, v213
	v_lshlrev_b32_e32 v90, 16, v214
	v_and_b32_e32 v84, 0xffff0000, v214
	v_lshlrev_b32_e32 v91, 16, v215
	v_and_b32_e32 v85, 0xffff0000, v215
	v_add_f32_e32 v88, v76, v88
	v_add_f32_e32 v82, v77, v82
	v_add_f32_e32 v89, v78, v89
	v_add_f32_e32 v83, v79, v83
	v_add_f32_e32 v90, v72, v90
	v_add_f32_e32 v84, v73, v84
	v_add_f32_e32 v91, v74, v91
	v_add_f32_e32 v85, v75, v85
	v_cvt_pk_bf16_f32 v72, v88, v82
	v_cvt_pk_bf16_f32 v73, v89, v83
	v_cvt_pk_bf16_f32 v74, v90, v84
	v_cvt_pk_bf16_f32 v75, v91, v85
	v_mul_f32_e32 v82, v82, v82
	v_mul_f32_e32 v83, v83, v83
	v_mul_f32_e32 v84, v84, v84
	v_mul_f32_e32 v85, v85, v85
	v_fmac_f32_e32 v82, v88, v88
	v_fmac_f32_e32 v83, v89, v89
	v_fmac_f32_e32 v84, v90, v90
	v_fmac_f32_e32 v85, v91, v91
	v_add_f32_e32 v82, v82, v83
	v_add_f32_e32 v83, v84, v85
	v_add_f32_e32 v82, v82, v83
	global_store_dwordx4 v[86:87], v[72:75], off
	s_waitcnt vmcnt(13)
	v_lshlrev_b32_e32 v83, 16, v216
	v_and_b32_e32 v76, 0xffff0000, v216
	v_lshlrev_b32_e32 v84, 16, v217
	v_and_b32_e32 v77, 0xffff0000, v217
	v_lshlrev_b32_e32 v85, 16, v218
	v_and_b32_e32 v78, 0xffff0000, v218
	v_lshlrev_b32_e32 v88, 16, v219
	v_and_b32_e32 v79, 0xffff0000, v219
	v_add_f32_e32 v69, v69, v76
	v_add_f32_e32 v71, v71, v77
	v_add_f32_e32 v77, v65, v78
	v_add_f32_e32 v79, v67, v79
	v_add_f32_e32 v68, v68, v83
	v_add_f32_e32 v70, v70, v84
	v_add_f32_e32 v76, v64, v85
	v_add_f32_e32 v78, v66, v88
	v_mul_f32_e32 v64, v69, v69
	v_mul_f32_e32 v65, v71, v71
	v_mul_f32_e32 v66, v77, v77
	v_mul_f32_e32 v67, v79, v79
	v_fmac_f32_e32 v64, v68, v68
	v_fmac_f32_e32 v65, v70, v70
	v_fmac_f32_e32 v66, v76, v76
	v_fmac_f32_e32 v67, v78, v78
	v_add_f32_e32 v64, v64, v65
	v_add_f32_e32 v65, v66, v67
	v_add_f32_e32 v64, v64, v65
	v_add_f32_e32 v64, v82, v64
	v_mov_b32_e32 v65, v64
	s_nop 1
	v_permlane16_swap_b32_e32 v65, v64
	v_cvt_pk_bf16_f32 v66, v68, v69
	v_cvt_pk_bf16_f32 v67, v70, v71
	v_cvt_pk_bf16_f32 v68, v76, v77
	v_cvt_pk_bf16_f32 v69, v78, v79
	s_waitcnt lgkmcnt(0)
	v_add_f32_e32 v64, v64, v65
	v_mov_b32_e32 v65, v64
	s_nop 1
	v_permlane32_swap_b32_e32 v65, v64
	global_store_dwordx4 v[86:87], v[66:69], off offset:256
	s_and_saveexec_b64 s[40:41], s[4:5]
	s_cbranch_execz .LBB0_980
	v_lshlrev_b64 v[66:67], 6, v[80:81]
	v_lshl_add_u64 v[66:67], s[18:19], 0, v[66:67]
	v_lshl_add_u64 v[66:67], s[38:39], 2, v[66:67]
	s_lshl_b32 s0, s56, 2
	v_lshl_add_u64 v[66:67], v[66:67], 0, s[0:1]
	s_waitcnt lgkmcnt(0)
	v_add_f32_e32 v64, v64, v65
	global_store_dword v[66:67], v64, off
.LBB0_980:
	s_or_b64 exec, exec, s[40:41]
	v_add_u32_e32 v64, 0x80, v150
	s_waitcnt lgkmcnt(0)
	v_ashrrev_i32_e32 v65, 31, v64
	v_lshlrev_b64 v[66:67], 11, v[64:65]
	v_lshl_add_u64 v[66:67], s[14:15], 0, v[66:67]
	v_lshl_add_u64 v[70:71], v[148:149], 1, v[66:67]
	s_mov_b64 s[100:101], 0x58000
	v_lshl_add_u64 v[230:231], v[232:233], 0, s[100:101]
	global_load_dwordx4 v[212:215], v[230:231], off
	global_load_dwordx4 v[216:219], v[230:231], off offset:256
	s_waitcnt vmcnt(13)
	v_lshlrev_b32_e32 v72, 16, v188
	v_and_b32_e32 v66, 0xffff0000, v188
	v_lshlrev_b32_e32 v73, 16, v189
	v_and_b32_e32 v67, 0xffff0000, v189
	v_lshlrev_b32_e32 v74, 16, v190
	v_and_b32_e32 v68, 0xffff0000, v190
	v_lshlrev_b32_e32 v75, 16, v191
	v_and_b32_e32 v69, 0xffff0000, v191
	v_add_f32_e32 v72, v60, v72
	v_add_f32_e32 v66, v61, v66
	v_add_f32_e32 v73, v62, v73
	v_add_f32_e32 v67, v63, v67
	v_add_f32_e32 v74, v56, v74
	v_add_f32_e32 v68, v57, v68
	v_add_f32_e32 v75, v58, v75
	v_add_f32_e32 v69, v59, v69
	v_cvt_pk_bf16_f32 v56, v72, v66
	v_cvt_pk_bf16_f32 v57, v73, v67
	v_cvt_pk_bf16_f32 v58, v74, v68
	v_cvt_pk_bf16_f32 v59, v75, v69
	v_mul_f32_e32 v66, v66, v66
	v_mul_f32_e32 v67, v67, v67
	v_mul_f32_e32 v68, v68, v68
	v_mul_f32_e32 v69, v69, v69
	v_fmac_f32_e32 v66, v72, v72
	v_fmac_f32_e32 v67, v73, v73
	v_fmac_f32_e32 v68, v74, v74
	v_fmac_f32_e32 v69, v75, v75
	v_add_f32_e32 v66, v66, v67
	v_add_f32_e32 v67, v68, v69
	v_add_f32_e32 v66, v66, v67
	global_store_dwordx4 v[70:71], v[56:59], off
	s_waitcnt vmcnt(13)
	v_lshlrev_b32_e32 v67, 16, v192
	v_and_b32_e32 v60, 0xffff0000, v192
	v_lshlrev_b32_e32 v68, 16, v193
	v_and_b32_e32 v61, 0xffff0000, v193
	v_lshlrev_b32_e32 v69, 16, v194
	v_and_b32_e32 v62, 0xffff0000, v194
	v_lshlrev_b32_e32 v72, 16, v195
	v_and_b32_e32 v63, 0xffff0000, v195
	v_add_f32_e32 v53, v53, v60
	v_add_f32_e32 v55, v55, v61
	v_add_f32_e32 v61, v49, v62
	v_add_f32_e32 v63, v51, v63
	v_add_f32_e32 v52, v52, v67
	v_add_f32_e32 v54, v54, v68
	v_add_f32_e32 v60, v48, v69
	v_add_f32_e32 v62, v50, v72
	v_mul_f32_e32 v48, v53, v53
	v_mul_f32_e32 v49, v55, v55
	v_mul_f32_e32 v50, v61, v61
	v_mul_f32_e32 v51, v63, v63
	v_fmac_f32_e32 v48, v52, v52
	v_fmac_f32_e32 v49, v54, v54
	v_fmac_f32_e32 v50, v60, v60
	v_fmac_f32_e32 v51, v62, v62
	v_add_f32_e32 v48, v48, v49
	v_add_f32_e32 v49, v50, v51
	v_add_f32_e32 v48, v48, v49
	v_add_f32_e32 v48, v66, v48
	v_mov_b32_e32 v49, v48
	s_nop 1
	v_permlane16_swap_b32_e32 v49, v48
	v_cvt_pk_bf16_f32 v50, v52, v53
	v_cvt_pk_bf16_f32 v51, v54, v55
	v_cvt_pk_bf16_f32 v52, v60, v61
	v_cvt_pk_bf16_f32 v53, v62, v63
	s_waitcnt lgkmcnt(0)
	v_add_f32_e32 v48, v48, v49
	v_mov_b32_e32 v49, v48
	s_nop 1
	v_permlane32_swap_b32_e32 v49, v48
	global_store_dwordx4 v[70:71], v[50:53], off offset:256
	s_and_saveexec_b64 s[40:41], s[4:5]
	s_cbranch_execz .LBB0_982
	v_lshlrev_b64 v[50:51], 6, v[64:65]
	v_lshl_add_u64 v[50:51], s[18:19], 0, v[50:51]
	v_lshl_add_u64 v[50:51], s[38:39], 2, v[50:51]
	s_lshl_b32 s0, s56, 2
	v_lshl_add_u64 v[50:51], v[50:51], 0, s[0:1]
	s_waitcnt lgkmcnt(0)
	v_add_f32_e32 v48, v48, v49
	global_store_dword v[50:51], v48, off
.LBB0_982:
	s_or_b64 exec, exec, s[40:41]
	v_add_u32_e32 v48, 0x90, v150
	s_waitcnt lgkmcnt(0)
	v_ashrrev_i32_e32 v49, 31, v48
	v_lshlrev_b64 v[50:51], 11, v[48:49]
	v_lshl_add_u64 v[50:51], s[14:15], 0, v[50:51]
	v_lshl_add_u64 v[54:55], v[148:149], 1, v[50:51]
	s_waitcnt vmcnt(11)
	v_lshlrev_b32_e32 v56, 16, v196
	v_and_b32_e32 v50, 0xffff0000, v196
	v_lshlrev_b32_e32 v57, 16, v197
	v_and_b32_e32 v51, 0xffff0000, v197
	v_lshlrev_b32_e32 v58, 16, v198
	v_and_b32_e32 v52, 0xffff0000, v198
	v_lshlrev_b32_e32 v59, 16, v199
	v_and_b32_e32 v53, 0xffff0000, v199
	v_add_f32_e32 v56, v44, v56
	v_add_f32_e32 v50, v45, v50
	v_add_f32_e32 v57, v46, v57
	v_add_f32_e32 v51, v47, v51
	v_add_f32_e32 v58, v40, v58
	v_add_f32_e32 v52, v41, v52
	v_add_f32_e32 v59, v42, v59
	v_add_f32_e32 v53, v43, v53
	v_cvt_pk_bf16_f32 v40, v56, v50
	v_cvt_pk_bf16_f32 v41, v57, v51
	v_cvt_pk_bf16_f32 v42, v58, v52
	v_cvt_pk_bf16_f32 v43, v59, v53
	v_mul_f32_e32 v50, v50, v50
	v_mul_f32_e32 v51, v51, v51
	v_mul_f32_e32 v52, v52, v52
	v_mul_f32_e32 v53, v53, v53
	v_fmac_f32_e32 v50, v56, v56
	v_fmac_f32_e32 v51, v57, v57
	v_fmac_f32_e32 v52, v58, v58
	v_fmac_f32_e32 v53, v59, v59
	v_add_f32_e32 v50, v50, v51
	v_add_f32_e32 v51, v52, v53
	v_add_f32_e32 v50, v50, v51
	global_store_dwordx4 v[54:55], v[40:43], off
	s_waitcnt vmcnt(11)
	v_lshlrev_b32_e32 v51, 16, v200
	v_and_b32_e32 v44, 0xffff0000, v200
	v_lshlrev_b32_e32 v52, 16, v201
	v_and_b32_e32 v45, 0xffff0000, v201
	v_lshlrev_b32_e32 v53, 16, v202
	v_and_b32_e32 v46, 0xffff0000, v202
	v_lshlrev_b32_e32 v56, 16, v203
	v_and_b32_e32 v47, 0xffff0000, v203
	v_add_f32_e32 v37, v37, v44
	v_add_f32_e32 v39, v39, v45
	v_add_f32_e32 v45, v33, v46
	v_add_f32_e32 v47, v35, v47
	v_add_f32_e32 v36, v36, v51
	v_add_f32_e32 v38, v38, v52
	v_add_f32_e32 v44, v32, v53
	v_add_f32_e32 v46, v34, v56
	v_mul_f32_e32 v32, v37, v37
	v_mul_f32_e32 v33, v39, v39
	v_mul_f32_e32 v34, v45, v45
	v_mul_f32_e32 v35, v47, v47
	v_fmac_f32_e32 v32, v36, v36
	v_fmac_f32_e32 v33, v38, v38
	v_fmac_f32_e32 v34, v44, v44
	v_fmac_f32_e32 v35, v46, v46
	v_add_f32_e32 v32, v32, v33
	v_add_f32_e32 v33, v34, v35
	v_add_f32_e32 v32, v32, v33
	v_add_f32_e32 v32, v50, v32
	v_mov_b32_e32 v33, v32
	s_nop 1
	v_permlane16_swap_b32_e32 v33, v32
	v_cvt_pk_bf16_f32 v34, v36, v37
	v_cvt_pk_bf16_f32 v35, v38, v39
	v_cvt_pk_bf16_f32 v36, v44, v45
	v_cvt_pk_bf16_f32 v37, v46, v47
	s_waitcnt lgkmcnt(0)
	v_add_f32_e32 v32, v32, v33
	v_mov_b32_e32 v33, v32
	s_nop 1
	v_permlane32_swap_b32_e32 v33, v32
	global_store_dwordx4 v[54:55], v[34:37], off offset:256
	s_and_saveexec_b64 s[40:41], s[4:5]
	s_cbranch_execz .LBB0_984
	v_lshlrev_b64 v[34:35], 6, v[48:49]
	v_lshl_add_u64 v[34:35], s[18:19], 0, v[34:35]
	v_lshl_add_u64 v[34:35], s[38:39], 2, v[34:35]
	s_lshl_b32 s0, s56, 2
	v_lshl_add_u64 v[34:35], v[34:35], 0, s[0:1]
	s_waitcnt lgkmcnt(0)
	v_add_f32_e32 v32, v32, v33
	global_store_dword v[34:35], v32, off
.LBB0_984:
	s_or_b64 exec, exec, s[40:41]
	v_add_u32_e32 v32, 0xa0, v150
	s_waitcnt lgkmcnt(0)
	v_ashrrev_i32_e32 v33, 31, v32
	v_lshlrev_b64 v[34:35], 11, v[32:33]
	v_lshl_add_u64 v[34:35], s[14:15], 0, v[34:35]
	v_lshl_add_u64 v[38:39], v[148:149], 1, v[34:35]
	s_waitcnt vmcnt(9)
	v_lshlrev_b32_e32 v40, 16, v204
	v_and_b32_e32 v34, 0xffff0000, v204
	v_lshlrev_b32_e32 v41, 16, v205
	v_and_b32_e32 v35, 0xffff0000, v205
	v_lshlrev_b32_e32 v42, 16, v206
	v_and_b32_e32 v36, 0xffff0000, v206
	v_lshlrev_b32_e32 v43, 16, v207
	v_and_b32_e32 v37, 0xffff0000, v207
	v_add_f32_e32 v40, v28, v40
	v_add_f32_e32 v34, v29, v34
	v_add_f32_e32 v41, v30, v41
	v_add_f32_e32 v35, v31, v35
	v_add_f32_e32 v42, v24, v42
	v_add_f32_e32 v36, v25, v36
	v_add_f32_e32 v43, v26, v43
	v_add_f32_e32 v37, v27, v37
	v_cvt_pk_bf16_f32 v24, v40, v34
	v_cvt_pk_bf16_f32 v25, v41, v35
	v_cvt_pk_bf16_f32 v26, v42, v36
	v_cvt_pk_bf16_f32 v27, v43, v37
	v_mul_f32_e32 v34, v34, v34
	v_mul_f32_e32 v35, v35, v35
	v_mul_f32_e32 v36, v36, v36
	v_mul_f32_e32 v37, v37, v37
	v_fmac_f32_e32 v34, v40, v40
	v_fmac_f32_e32 v35, v41, v41
	v_fmac_f32_e32 v36, v42, v42
	v_fmac_f32_e32 v37, v43, v43
	v_add_f32_e32 v34, v34, v35
	v_add_f32_e32 v35, v36, v37
	v_add_f32_e32 v34, v34, v35
	global_store_dwordx4 v[38:39], v[24:27], off
	s_waitcnt vmcnt(9)
	v_lshlrev_b32_e32 v35, 16, v208
	v_and_b32_e32 v28, 0xffff0000, v208
	v_lshlrev_b32_e32 v36, 16, v209
	v_and_b32_e32 v29, 0xffff0000, v209
	v_lshlrev_b32_e32 v37, 16, v210
	v_and_b32_e32 v30, 0xffff0000, v210
	v_lshlrev_b32_e32 v40, 16, v211
	v_and_b32_e32 v31, 0xffff0000, v211
	v_add_f32_e32 v21, v21, v28
	v_add_f32_e32 v23, v23, v29
	v_add_f32_e32 v29, v17, v30
	v_add_f32_e32 v31, v19, v31
	v_add_f32_e32 v20, v20, v35
	v_add_f32_e32 v22, v22, v36
	v_add_f32_e32 v28, v16, v37
	v_add_f32_e32 v30, v18, v40
	v_mul_f32_e32 v16, v21, v21
	v_mul_f32_e32 v17, v23, v23
	v_mul_f32_e32 v18, v29, v29
	v_mul_f32_e32 v19, v31, v31
	v_fmac_f32_e32 v16, v20, v20
	v_fmac_f32_e32 v17, v22, v22
	v_fmac_f32_e32 v18, v28, v28
	v_fmac_f32_e32 v19, v30, v30
	v_add_f32_e32 v16, v16, v17
	v_add_f32_e32 v17, v18, v19
	v_add_f32_e32 v16, v16, v17
	v_add_f32_e32 v16, v34, v16
	v_mov_b32_e32 v17, v16
	s_nop 1
	v_permlane16_swap_b32_e32 v17, v16
	v_cvt_pk_bf16_f32 v18, v20, v21
	v_cvt_pk_bf16_f32 v19, v22, v23
	v_cvt_pk_bf16_f32 v20, v28, v29
	v_cvt_pk_bf16_f32 v21, v30, v31
	s_waitcnt lgkmcnt(0)
	v_add_f32_e32 v16, v16, v17
	v_mov_b32_e32 v17, v16
	s_nop 1
	v_permlane32_swap_b32_e32 v17, v16
	global_store_dwordx4 v[38:39], v[18:21], off offset:256
	s_and_saveexec_b64 s[40:41], s[4:5]
	s_cbranch_execz .LBB0_986
	v_lshlrev_b64 v[18:19], 6, v[32:33]
	v_lshl_add_u64 v[18:19], s[18:19], 0, v[18:19]
	v_lshl_add_u64 v[18:19], s[38:39], 2, v[18:19]
	s_lshl_b32 s0, s56, 2
	v_lshl_add_u64 v[18:19], v[18:19], 0, s[0:1]
	s_waitcnt lgkmcnt(0)
	v_add_f32_e32 v16, v16, v17
	global_store_dword v[18:19], v16, off
.LBB0_986:
	s_or_b64 exec, exec, s[40:41]
	v_add_u32_e32 v16, 0xb0, v150
	s_waitcnt lgkmcnt(0)
	v_ashrrev_i32_e32 v17, 31, v16
	v_lshlrev_b64 v[18:19], 11, v[16:17]
	v_lshl_add_u64 v[18:19], s[14:15], 0, v[18:19]
	v_lshl_add_u64 v[22:23], v[148:149], 1, v[18:19]
	s_waitcnt vmcnt(7)
	v_lshlrev_b32_e32 v24, 16, v212
	v_and_b32_e32 v18, 0xffff0000, v212
	v_lshlrev_b32_e32 v25, 16, v213
	v_and_b32_e32 v19, 0xffff0000, v213
	v_lshlrev_b32_e32 v26, 16, v214
	v_and_b32_e32 v20, 0xffff0000, v214
	v_lshlrev_b32_e32 v27, 16, v215
	v_and_b32_e32 v21, 0xffff0000, v215
	v_add_f32_e32 v24, v12, v24
	v_add_f32_e32 v18, v13, v18
	v_add_f32_e32 v25, v14, v25
	v_add_f32_e32 v19, v15, v19
	v_add_f32_e32 v26, v8, v26
	v_add_f32_e32 v20, v9, v20
	v_add_f32_e32 v27, v10, v27
	v_add_f32_e32 v21, v11, v21
	v_cvt_pk_bf16_f32 v8, v24, v18
	v_cvt_pk_bf16_f32 v9, v25, v19
	v_cvt_pk_bf16_f32 v10, v26, v20
	v_cvt_pk_bf16_f32 v11, v27, v21
	v_mul_f32_e32 v18, v18, v18
	v_mul_f32_e32 v19, v19, v19
	v_mul_f32_e32 v20, v20, v20
	v_mul_f32_e32 v21, v21, v21
	v_fmac_f32_e32 v18, v24, v24
	v_fmac_f32_e32 v19, v25, v25
	v_fmac_f32_e32 v20, v26, v26
	v_fmac_f32_e32 v21, v27, v27
	v_add_f32_e32 v18, v18, v19
	v_add_f32_e32 v19, v20, v21
	v_add_f32_e32 v18, v18, v19
	global_store_dwordx4 v[22:23], v[8:11], off
	s_waitcnt vmcnt(7)
	v_lshlrev_b32_e32 v19, 16, v216
	v_and_b32_e32 v12, 0xffff0000, v216
	v_lshlrev_b32_e32 v20, 16, v217
	v_and_b32_e32 v13, 0xffff0000, v217
	v_lshlrev_b32_e32 v21, 16, v218
	v_and_b32_e32 v14, 0xffff0000, v218
	v_lshlrev_b32_e32 v24, 16, v219
	v_and_b32_e32 v15, 0xffff0000, v219
	v_add_f32_e32 v5, v5, v12
	v_add_f32_e32 v7, v7, v13
	v_add_f32_e32 v13, v1, v14
	v_add_f32_e32 v15, v3, v15
	v_add_f32_e32 v4, v4, v19
	v_add_f32_e32 v6, v6, v20
	v_add_f32_e32 v12, v0, v21
	v_add_f32_e32 v14, v2, v24
	v_mul_f32_e32 v0, v5, v5
	v_mul_f32_e32 v1, v7, v7
	v_mul_f32_e32 v2, v13, v13
	v_mul_f32_e32 v3, v15, v15
	v_fmac_f32_e32 v0, v4, v4
	v_fmac_f32_e32 v1, v6, v6
	v_fmac_f32_e32 v2, v12, v12
	v_fmac_f32_e32 v3, v14, v14
	v_add_f32_e32 v0, v0, v1
	v_add_f32_e32 v1, v2, v3
	v_add_f32_e32 v0, v0, v1
	v_add_f32_e32 v0, v18, v0
	v_mov_b32_e32 v1, v0
	s_nop 1
	v_permlane16_swap_b32_e32 v1, v0
	v_cvt_pk_bf16_f32 v2, v4, v5
	v_cvt_pk_bf16_f32 v3, v6, v7
	v_cvt_pk_bf16_f32 v4, v12, v13
	v_cvt_pk_bf16_f32 v5, v14, v15
	s_waitcnt lgkmcnt(0)
	v_add_f32_e32 v0, v0, v1
	v_mov_b32_e32 v1, v0
	s_nop 1
	v_permlane32_swap_b32_e32 v1, v0
	global_store_dwordx4 v[22:23], v[2:5], off offset:256
	s_and_saveexec_b64 s[40:41], s[4:5]
	s_cbranch_execz .LBB0_988
	v_lshlrev_b64 v[2:3], 6, v[16:17]
	v_lshl_add_u64 v[2:3], s[18:19], 0, v[2:3]
	v_lshl_add_u64 v[2:3], s[38:39], 2, v[2:3]
	s_lshl_b32 s0, s56, 2
	v_lshl_add_u64 v[2:3], v[2:3], 0, s[0:1]
	s_waitcnt lgkmcnt(0)
	v_add_f32_e32 v0, v0, v1
	global_store_dword v[2:3], v0, off

.LBB0_1148:
	v_lshl_add_u32 v150, s12, 8, v131
	v_ashrrev_i32_e32 v151, 31, v150
	v_lshl_or_b32 v148, s8, 8, v153
	v_lshlrev_b64 v[160:161], 11, v[150:151]
	v_ashrrev_i32_e32 v149, 31, v148
	v_lshl_add_u64 v[160:161], s[14:15], 0, v[160:161]
	v_lshl_add_u64 v[164:165], v[148:149], 1, v[160:161]
	v_mov_b32_e32 v232, v164
	v_mov_b32_e32 v233, v165
	global_load_dwordx4 v[188:191], v[232:233], off
	global_load_dwordx4 v[192:195], v[232:233], off offset:256
	s_mov_b64 s[100:101], 0x8000
	v_lshl_add_u64 v[230:231], v[232:233], 0, s[100:101]
	global_load_dwordx4 v[196:199], v[230:231], off
	global_load_dwordx4 v[200:203], v[230:231], off offset:256
	s_mov_b64 s[100:101], 0x10000
	v_lshl_add_u64 v[230:231], v[232:233], 0, s[100:101]
	global_load_dwordx4 v[204:207], v[230:231], off
	global_load_dwordx4 v[208:211], v[230:231], off offset:256
	s_mov_b64 s[100:101], 0x18000
	v_lshl_add_u64 v[230:231], v[232:233], 0, s[100:101]
	global_load_dwordx4 v[212:215], v[230:231], off
	global_load_dwordx4 v[216:219], v[230:231], off offset:256
	v_and_b32_e32 v170, 64, v158
	v_add_u32_e32 v170, 64, v170
	v_xor_b32_e32 v171, 32, v158
	s_lshl_b32 s30, s8, 2
	s_ashr_i32 s31, s30, 31
	s_waitcnt vmcnt(7)
	v_lshlrev_b32_e32 v159, 16, v188
	v_and_b32_e32 v160, 0xffff0000, v188
	v_lshlrev_b32_e32 v166, 16, v189
	v_and_b32_e32 v161, 0xffff0000, v189
	v_lshlrev_b32_e32 v167, 16, v190
	v_and_b32_e32 v162, 0xffff0000, v190
	v_lshlrev_b32_e32 v168, 16, v191
	v_and_b32_e32 v163, 0xffff0000, v191
	v_add_f32_e32 v159, v124, v159
	v_add_f32_e32 v169, v125, v160
	v_add_f32_e32 v126, v126, v166
	v_add_f32_e32 v127, v127, v161
	v_add_f32_e32 v166, v120, v167
	v_add_f32_e32 v121, v121, v162
	v_add_f32_e32 v167, v122, v168
	v_add_f32_e32 v168, v123, v163
	v_cvt_pk_bf16_f32 v122, v159, v169
	v_cvt_pk_bf16_f32 v123, v126, v127
	v_cvt_pk_bf16_f32 v124, v166, v121
	v_cvt_pk_bf16_f32 v125, v167, v168
	v_mul_f32_e32 v169, v169, v169
	v_mul_f32_e32 v127, v127, v127
	v_mul_f32_e32 v121, v121, v121
	v_mul_f32_e32 v168, v168, v168
	v_fmac_f32_e32 v169, v159, v159
	v_fmac_f32_e32 v127, v126, v126
	v_fmac_f32_e32 v121, v166, v166
	v_fmac_f32_e32 v168, v167, v167
	v_add_f32_e32 v126, v169, v127
	v_add_f32_e32 v121, v121, v168
	v_add_f32_e32 v121, v126, v121
	v_xor_b32_e32 v120, 16, v158
	v_cmp_lt_i32_e32 vcc, v120, v170
	global_store_dwordx4 v[164:165], v[122:125], off
	s_waitcnt vmcnt(7)
	v_lshlrev_b32_e32 v126, 16, v192
	v_and_b32_e32 v127, 0xffff0000, v192
	v_lshlrev_b32_e32 v159, 16, v193
	v_and_b32_e32 v160, 0xffff0000, v193
	v_lshlrev_b32_e32 v161, 16, v194
	v_and_b32_e32 v162, 0xffff0000, v194
	v_lshlrev_b32_e32 v166, 16, v195
	v_and_b32_e32 v163, 0xffff0000, v195
	v_add_f32_e32 v117, v117, v127
	v_add_f32_e32 v119, v119, v160
	v_add_f32_e32 v127, v113, v162
	v_add_f32_e32 v115, v115, v163
	v_add_f32_e32 v116, v116, v126
	v_add_f32_e32 v118, v118, v159
	v_add_f32_e32 v126, v112, v161
	v_add_f32_e32 v159, v114, v166
	v_mul_f32_e32 v112, v117, v117
	v_mul_f32_e32 v113, v119, v119
	v_mul_f32_e32 v114, v127, v127
	v_mul_f32_e32 v160, v115, v115
	v_fmac_f32_e32 v112, v116, v116
	v_fmac_f32_e32 v113, v118, v118
	v_fmac_f32_e32 v114, v126, v126
	v_fmac_f32_e32 v160, v159, v159
	v_add_f32_e32 v112, v112, v113
	v_add_f32_e32 v113, v114, v160
	v_cndmask_b32_e32 v120, v158, v120, vcc
	v_add_f32_e32 v112, v112, v113
	v_lshlrev_b32_e32 v120, 2, v120
	v_add_f32_e32 v112, v121, v112
	v_mov_b32_e32 v113, v112
	s_nop 1
	v_permlane16_swap_b32_e32 v113, v112
	v_cmp_lt_i32_e32 vcc, v171, v170
	v_cvt_pk_bf16_f32 v116, v116, v117
	v_cvt_pk_bf16_f32 v117, v118, v119
	v_cvt_pk_bf16_f32 v118, v126, v127
	s_waitcnt lgkmcnt(0)
	v_add_f32_e32 v112, v112, v113
	v_cvt_pk_bf16_f32 v119, v159, v115
	v_cndmask_b32_e32 v114, v158, v171, vcc
	v_lshlrev_b32_e32 v114, 2, v114
	v_mov_b32_e32 v113, v112
	s_nop 1
	v_permlane32_swap_b32_e32 v113, v112
	global_store_dwordx4 v[164:165], v[116:119], off offset:256
	s_and_saveexec_b64 s[36:37], s[4:5]
	s_cbranch_execz .LBB0_1150
	v_lshlrev_b64 v[116:117], 6, v[150:151]
	v_lshl_add_u64 v[116:117], s[18:19], 0, v[116:117]
	v_lshl_add_u64 v[116:117], s[30:31], 2, v[116:117]
	s_lshl_b32 s8, s50, 2
	v_lshl_add_u64 v[116:117], v[116:117], 0, s[8:9]
	s_waitcnt lgkmcnt(0)
	v_add_f32_e32 v112, v112, v113
	global_store_dword v[116:117], v112, off
.LBB0_1150:
	s_or_b64 exec, exec, s[36:37]
	v_or_b32_e32 v112, 16, v150
	s_waitcnt lgkmcnt(0)
	v_ashrrev_i32_e32 v113, 31, v112
	v_lshlrev_b64 v[116:117], 11, v[112:113]
	v_lshl_add_u64 v[116:117], s[14:15], 0, v[116:117]
	v_lshl_add_u64 v[122:123], v[148:149], 1, v[116:117]
	s_mov_b64 s[100:101], 0x40000
	v_lshl_add_u64 v[230:231], v[232:233], 0, s[100:101]
	global_load_dwordx4 v[188:191], v[230:231], off
	global_load_dwordx4 v[192:195], v[230:231], off offset:256
	s_waitcnt vmcnt(9)
	v_lshlrev_b32_e32 v115, 16, v196
	v_and_b32_e32 v116, 0xffff0000, v196
	v_lshlrev_b32_e32 v121, 16, v197
	v_and_b32_e32 v117, 0xffff0000, v197
	v_lshlrev_b32_e32 v124, 16, v198
	v_and_b32_e32 v118, 0xffff0000, v198
	v_lshlrev_b32_e32 v125, 16, v199
	v_and_b32_e32 v119, 0xffff0000, v199
	v_add_f32_e32 v115, v108, v115
	v_add_f32_e32 v116, v109, v116
	v_add_f32_e32 v121, v110, v121
	v_add_f32_e32 v117, v111, v117
	v_add_f32_e32 v124, v104, v124
	v_add_f32_e32 v118, v105, v118
	v_add_f32_e32 v125, v106, v125
	v_add_f32_e32 v119, v107, v119
	v_cvt_pk_bf16_f32 v104, v115, v116
	v_cvt_pk_bf16_f32 v105, v121, v117
	v_cvt_pk_bf16_f32 v106, v124, v118
	v_cvt_pk_bf16_f32 v107, v125, v119
	v_mul_f32_e32 v116, v116, v116
	v_mul_f32_e32 v117, v117, v117
	v_mul_f32_e32 v118, v118, v118
	v_mul_f32_e32 v119, v119, v119
	v_fmac_f32_e32 v116, v115, v115
	v_fmac_f32_e32 v117, v121, v121
	v_fmac_f32_e32 v118, v124, v124
	v_fmac_f32_e32 v119, v125, v125
	v_add_f32_e32 v115, v116, v117
	v_add_f32_e32 v116, v118, v119
	v_add_f32_e32 v115, v115, v116
	global_store_dwordx4 v[122:123], v[104:107], off
	s_waitcnt vmcnt(9)
	v_lshlrev_b32_e32 v116, 16, v200
	v_and_b32_e32 v108, 0xffff0000, v200
	v_lshlrev_b32_e32 v117, 16, v201
	v_and_b32_e32 v109, 0xffff0000, v201
	v_lshlrev_b32_e32 v118, 16, v202
	v_and_b32_e32 v110, 0xffff0000, v202
	v_lshlrev_b32_e32 v119, 16, v203
	v_and_b32_e32 v111, 0xffff0000, v203
	v_add_f32_e32 v101, v101, v108
	v_add_f32_e32 v103, v103, v109
	v_add_f32_e32 v109, v97, v110
	v_add_f32_e32 v111, v99, v111
	v_add_f32_e32 v100, v100, v116
	v_add_f32_e32 v102, v102, v117
	v_add_f32_e32 v108, v96, v118
	v_add_f32_e32 v110, v98, v119
	v_mul_f32_e32 v96, v101, v101
	v_mul_f32_e32 v97, v103, v103
	v_mul_f32_e32 v98, v109, v109
	v_mul_f32_e32 v99, v111, v111
	v_fmac_f32_e32 v96, v100, v100
	v_fmac_f32_e32 v97, v102, v102
	v_fmac_f32_e32 v98, v108, v108
	v_fmac_f32_e32 v99, v110, v110
	v_add_f32_e32 v96, v96, v97
	v_add_f32_e32 v97, v98, v99
	v_add_f32_e32 v96, v96, v97
	v_add_f32_e32 v96, v115, v96
	v_mov_b32_e32 v97, v96
	s_nop 1
	v_permlane16_swap_b32_e32 v97, v96
	v_cvt_pk_bf16_f32 v98, v100, v101
	v_cvt_pk_bf16_f32 v99, v102, v103
	v_cvt_pk_bf16_f32 v100, v108, v109
	v_cvt_pk_bf16_f32 v101, v110, v111
	s_waitcnt lgkmcnt(0)
	v_add_f32_e32 v96, v96, v97
	v_mov_b32_e32 v97, v96
	s_nop 1
	v_permlane32_swap_b32_e32 v97, v96
	global_store_dwordx4 v[122:123], v[98:101], off offset:256
	s_and_saveexec_b64 s[36:37], s[4:5]
	s_cbranch_execz .LBB0_1152
	v_lshlrev_b64 v[98:99], 6, v[112:113]
	v_lshl_add_u64 v[98:99], s[18:19], 0, v[98:99]
	v_lshl_add_u64 v[98:99], s[30:31], 2, v[98:99]
	s_lshl_b32 s8, s50, 2
	v_lshl_add_u64 v[98:99], v[98:99], 0, s[8:9]
	s_waitcnt lgkmcnt(0)
	v_add_f32_e32 v96, v96, v97
	global_store_dword v[98:99], v96, off
.LBB0_1152:
	s_or_b64 exec, exec, s[36:37]
	v_or_b32_e32 v96, 32, v150
	s_waitcnt lgkmcnt(0)
	v_ashrrev_i32_e32 v97, 31, v96
	v_lshlrev_b64 v[98:99], 11, v[96:97]
	v_lshl_add_u64 v[98:99], s[14:15], 0, v[98:99]
	v_lshl_add_u64 v[102:103], v[148:149], 1, v[98:99]
	s_mov_b64 s[100:101], 0x48000
	v_lshl_add_u64 v[230:231], v[232:233], 0, s[100:101]
	global_load_dwordx4 v[196:199], v[230:231], off
	global_load_dwordx4 v[200:203], v[230:231], off offset:256
	s_waitcnt vmcnt(11)
	v_lshlrev_b32_e32 v104, 16, v204
	v_and_b32_e32 v98, 0xffff0000, v204
	v_lshlrev_b32_e32 v105, 16, v205
	v_and_b32_e32 v99, 0xffff0000, v205
	v_lshlrev_b32_e32 v106, 16, v206
	v_and_b32_e32 v100, 0xffff0000, v206
	v_lshlrev_b32_e32 v107, 16, v207
	v_and_b32_e32 v101, 0xffff0000, v207
	v_add_f32_e32 v104, v92, v104
	v_add_f32_e32 v98, v93, v98
	v_add_f32_e32 v105, v94, v105
	v_add_f32_e32 v99, v95, v99
	v_add_f32_e32 v106, v88, v106
	v_add_f32_e32 v100, v89, v100
	v_add_f32_e32 v107, v90, v107
	v_add_f32_e32 v101, v91, v101
	v_cvt_pk_bf16_f32 v88, v104, v98
	v_cvt_pk_bf16_f32 v89, v105, v99
	v_cvt_pk_bf16_f32 v90, v106, v100
	v_cvt_pk_bf16_f32 v91, v107, v101
	v_mul_f32_e32 v98, v98, v98
	v_mul_f32_e32 v99, v99, v99
	v_mul_f32_e32 v100, v100, v100
	v_mul_f32_e32 v101, v101, v101
	v_fmac_f32_e32 v98, v104, v104
	v_fmac_f32_e32 v99, v105, v105
	v_fmac_f32_e32 v100, v106, v106
	v_fmac_f32_e32 v101, v107, v107
	v_add_f32_e32 v98, v98, v99
	v_add_f32_e32 v99, v100, v101
	v_add_f32_e32 v98, v98, v99
	global_store_dwordx4 v[102:103], v[88:91], off
	s_waitcnt vmcnt(11)
	v_lshlrev_b32_e32 v99, 16, v208
	v_and_b32_e32 v92, 0xffff0000, v208
	v_lshlrev_b32_e32 v100, 16, v209
	v_and_b32_e32 v93, 0xffff0000, v209
	v_lshlrev_b32_e32 v101, 16, v210
	v_and_b32_e32 v94, 0xffff0000, v210
	v_lshlrev_b32_e32 v104, 16, v211
	v_and_b32_e32 v95, 0xffff0000, v211
	v_add_f32_e32 v85, v85, v92
	v_add_f32_e32 v87, v87, v93
	v_add_f32_e32 v93, v81, v94
	v_add_f32_e32 v95, v83, v95
	v_add_f32_e32 v84, v84, v99
	v_add_f32_e32 v86, v86, v100
	v_add_f32_e32 v92, v80, v101
	v_add_f32_e32 v94, v82, v104
	v_mul_f32_e32 v80, v85, v85
	v_mul_f32_e32 v81, v87, v87
	v_mul_f32_e32 v82, v93, v93
	v_mul_f32_e32 v83, v95, v95
	v_fmac_f32_e32 v80, v84, v84
	v_fmac_f32_e32 v81, v86, v86
	v_fmac_f32_e32 v82, v92, v92
	v_fmac_f32_e32 v83, v94, v94
	v_add_f32_e32 v80, v80, v81
	v_add_f32_e32 v81, v82, v83
	v_add_f32_e32 v80, v80, v81
	v_add_f32_e32 v80, v98, v80
	v_mov_b32_e32 v81, v80
	s_nop 1
	v_permlane16_swap_b32_e32 v81, v80
	v_cvt_pk_bf16_f32 v82, v84, v85
	v_cvt_pk_bf16_f32 v83, v86, v87
	v_cvt_pk_bf16_f32 v84, v92, v93
	v_cvt_pk_bf16_f32 v85, v94, v95
	s_waitcnt lgkmcnt(0)
	v_add_f32_e32 v80, v80, v81
	v_mov_b32_e32 v81, v80
	s_nop 1
	v_permlane32_swap_b32_e32 v81, v80
	global_store_dwordx4 v[102:103], v[82:85], off offset:256
	s_and_saveexec_b64 s[36:37], s[4:5]
	s_cbranch_execz .LBB0_1154
	v_lshlrev_b64 v[82:83], 6, v[96:97]
	v_lshl_add_u64 v[82:83], s[18:19], 0, v[82:83]
	v_lshl_add_u64 v[82:83], s[30:31], 2, v[82:83]
	s_lshl_b32 s8, s50, 2
	v_lshl_add_u64 v[82:83], v[82:83], 0, s[8:9]
	s_waitcnt lgkmcnt(0)
	v_add_f32_e32 v80, v80, v81
	global_store_dword v[82:83], v80, off
.LBB0_1154:
	s_or_b64 exec, exec, s[36:37]
	v_or_b32_e32 v80, 48, v150
	s_waitcnt lgkmcnt(0)
	v_ashrrev_i32_e32 v81, 31, v80
	v_lshlrev_b64 v[82:83], 11, v[80:81]
	v_lshl_add_u64 v[82:83], s[14:15], 0, v[82:83]
	v_lshl_add_u64 v[86:87], v[148:149], 1, v[82:83]
	s_mov_b64 s[100:101], 0x50000
	v_lshl_add_u64 v[230:231], v[232:233], 0, s[100:101]
	global_load_dwordx4 v[204:207], v[230:231], off
	global_load_dwordx4 v[208:211], v[230:231], off offset:256
	s_waitcnt vmcnt(13)
	v_lshlrev_b32_e32 v88, 16, v212
	v_and_b32_e32 v82, 0xffff0000, v212
	v_lshlrev_b32_e32 v89, 16, v213
	v_and_b32_e32 v83, 0xffff0000, v213
	v_lshlrev_b32_e32 v90, 16, v214
	v_and_b32_e32 v84, 0xffff0000, v214
	v_lshlrev_b32_e32 v91, 16, v215
	v_and_b32_e32 v85, 0xffff0000, v215
	v_add_f32_e32 v88, v76, v88
	v_add_f32_e32 v82, v77, v82
	v_add_f32_e32 v89, v78, v89
	v_add_f32_e32 v83, v79, v83
	v_add_f32_e32 v90, v72, v90
	v_add_f32_e32 v84, v73, v84
	v_add_f32_e32 v91, v74, v91
	v_add_f32_e32 v85, v75, v85
	v_cvt_pk_bf16_f32 v72, v88, v82
	v_cvt_pk_bf16_f32 v73, v89, v83
	v_cvt_pk_bf16_f32 v74, v90, v84
	v_cvt_pk_bf16_f32 v75, v91, v85
	v_mul_f32_e32 v82, v82, v82
	v_mul_f32_e32 v83, v83, v83
	v_mul_f32_e32 v84, v84, v84
	v_mul_f32_e32 v85, v85, v85
	v_fmac_f32_e32 v82, v88, v88
	v_fmac_f32_e32 v83, v89, v89
	v_fmac_f32_e32 v84, v90, v90
	v_fmac_f32_e32 v85, v91, v91
	v_add_f32_e32 v82, v82, v83
	v_add_f32_e32 v83, v84, v85
	v_add_f32_e32 v82, v82, v83
	global_store_dwordx4 v[86:87], v[72:75], off
	s_waitcnt vmcnt(13)
	v_lshlrev_b32_e32 v83, 16, v216
	v_and_b32_e32 v76, 0xffff0000, v216
	v_lshlrev_b32_e32 v84, 16, v217
	v_and_b32_e32 v77, 0xffff0000, v217
	v_lshlrev_b32_e32 v85, 16, v218
	v_and_b32_e32 v78, 0xffff0000, v218
	v_lshlrev_b32_e32 v88, 16, v219
	v_and_b32_e32 v79, 0xffff0000, v219
	v_add_f32_e32 v69, v69, v76
	v_add_f32_e32 v71, v71, v77
	v_add_f32_e32 v77, v65, v78
	v_add_f32_e32 v79, v67, v79
	v_add_f32_e32 v68, v68, v83
	v_add_f32_e32 v70, v70, v84
	v_add_f32_e32 v76, v64, v85
	v_add_f32_e32 v78, v66, v88
	v_mul_f32_e32 v64, v69, v69
	v_mul_f32_e32 v65, v71, v71
	v_mul_f32_e32 v66, v77, v77
	v_mul_f32_e32 v67, v79, v79
	v_fmac_f32_e32 v64, v68, v68
	v_fmac_f32_e32 v65, v70, v70
	v_fmac_f32_e32 v66, v76, v76
	v_fmac_f32_e32 v67, v78, v78
	v_add_f32_e32 v64, v64, v65
	v_add_f32_e32 v65, v66, v67
	v_add_f32_e32 v64, v64, v65
	v_add_f32_e32 v64, v82, v64
	v_mov_b32_e32 v65, v64
	s_nop 1
	v_permlane16_swap_b32_e32 v65, v64
	v_cvt_pk_bf16_f32 v66, v68, v69
	v_cvt_pk_bf16_f32 v67, v70, v71
	v_cvt_pk_bf16_f32 v68, v76, v77
	v_cvt_pk_bf16_f32 v69, v78, v79
	s_waitcnt lgkmcnt(0)
	v_add_f32_e32 v64, v64, v65
	v_mov_b32_e32 v65, v64
	s_nop 1
	v_permlane32_swap_b32_e32 v65, v64
	global_store_dwordx4 v[86:87], v[66:69], off offset:256
	s_and_saveexec_b64 s[36:37], s[4:5]
	s_cbranch_execz .LBB0_1156
	v_lshlrev_b64 v[66:67], 6, v[80:81]
	v_lshl_add_u64 v[66:67], s[18:19], 0, v[66:67]
	v_lshl_add_u64 v[66:67], s[30:31], 2, v[66:67]
	s_lshl_b32 s8, s50, 2
	v_lshl_add_u64 v[66:67], v[66:67], 0, s[8:9]
	s_waitcnt lgkmcnt(0)
	v_add_f32_e32 v64, v64, v65
	global_store_dword v[66:67], v64, off
.LBB0_1156:
	s_or_b64 exec, exec, s[36:37]
	v_add_u32_e32 v64, 0x80, v150
	s_waitcnt lgkmcnt(0)
	v_ashrrev_i32_e32 v65, 31, v64
	v_lshlrev_b64 v[66:67], 11, v[64:65]
	v_lshl_add_u64 v[66:67], s[14:15], 0, v[66:67]
	v_lshl_add_u64 v[70:71], v[148:149], 1, v[66:67]
	s_mov_b64 s[100:101], 0x58000
	v_lshl_add_u64 v[230:231], v[232:233], 0, s[100:101]
	global_load_dwordx4 v[212:215], v[230:231], off
	global_load_dwordx4 v[216:219], v[230:231], off offset:256
	s_waitcnt vmcnt(13)
	v_lshlrev_b32_e32 v72, 16, v188
	v_and_b32_e32 v66, 0xffff0000, v188
	v_lshlrev_b32_e32 v73, 16, v189
	v_and_b32_e32 v67, 0xffff0000, v189
	v_lshlrev_b32_e32 v74, 16, v190
	v_and_b32_e32 v68, 0xffff0000, v190
	v_lshlrev_b32_e32 v75, 16, v191
	v_and_b32_e32 v69, 0xffff0000, v191
	v_add_f32_e32 v72, v60, v72
	v_add_f32_e32 v66, v61, v66
	v_add_f32_e32 v73, v62, v73
	v_add_f32_e32 v67, v63, v67
	v_add_f32_e32 v74, v56, v74
	v_add_f32_e32 v68, v57, v68
	v_add_f32_e32 v75, v58, v75
	v_add_f32_e32 v69, v59, v69
	v_cvt_pk_bf16_f32 v56, v72, v66
	v_cvt_pk_bf16_f32 v57, v73, v67
	v_cvt_pk_bf16_f32 v58, v74, v68
	v_cvt_pk_bf16_f32 v59, v75, v69
	v_mul_f32_e32 v66, v66, v66
	v_mul_f32_e32 v67, v67, v67
	v_mul_f32_e32 v68, v68, v68
	v_mul_f32_e32 v69, v69, v69
	v_fmac_f32_e32 v66, v72, v72
	v_fmac_f32_e32 v67, v73, v73
	v_fmac_f32_e32 v68, v74, v74
	v_fmac_f32_e32 v69, v75, v75
	v_add_f32_e32 v66, v66, v67
	v_add_f32_e32 v67, v68, v69
	v_add_f32_e32 v66, v66, v67
	global_store_dwordx4 v[70:71], v[56:59], off
	s_waitcnt vmcnt(13)
	v_lshlrev_b32_e32 v67, 16, v192
	v_and_b32_e32 v60, 0xffff0000, v192
	v_lshlrev_b32_e32 v68, 16, v193
	v_and_b32_e32 v61, 0xffff0000, v193
	v_lshlrev_b32_e32 v69, 16, v194
	v_and_b32_e32 v62, 0xffff0000, v194
	v_lshlrev_b32_e32 v72, 16, v195
	v_and_b32_e32 v63, 0xffff0000, v195
	v_add_f32_e32 v53, v53, v60
	v_add_f32_e32 v55, v55, v61
	v_add_f32_e32 v61, v49, v62
	v_add_f32_e32 v63, v51, v63
	v_add_f32_e32 v52, v52, v67
	v_add_f32_e32 v54, v54, v68
	v_add_f32_e32 v60, v48, v69
	v_add_f32_e32 v62, v50, v72
	v_mul_f32_e32 v48, v53, v53
	v_mul_f32_e32 v49, v55, v55
	v_mul_f32_e32 v50, v61, v61
	v_mul_f32_e32 v51, v63, v63
	v_fmac_f32_e32 v48, v52, v52
	v_fmac_f32_e32 v49, v54, v54
	v_fmac_f32_e32 v50, v60, v60
	v_fmac_f32_e32 v51, v62, v62
	v_add_f32_e32 v48, v48, v49
	v_add_f32_e32 v49, v50, v51
	v_add_f32_e32 v48, v48, v49
	v_add_f32_e32 v48, v66, v48
	v_mov_b32_e32 v49, v48
	s_nop 1
	v_permlane16_swap_b32_e32 v49, v48
	v_cvt_pk_bf16_f32 v50, v52, v53
	v_cvt_pk_bf16_f32 v51, v54, v55
	v_cvt_pk_bf16_f32 v52, v60, v61
	v_cvt_pk_bf16_f32 v53, v62, v63
	s_waitcnt lgkmcnt(0)
	v_add_f32_e32 v48, v48, v49
	v_mov_b32_e32 v49, v48
	s_nop 1
	v_permlane32_swap_b32_e32 v49, v48
	global_store_dwordx4 v[70:71], v[50:53], off offset:256
	s_and_saveexec_b64 s[36:37], s[4:5]
	s_cbranch_execz .LBB0_1158
	v_lshlrev_b64 v[50:51], 6, v[64:65]
	v_lshl_add_u64 v[50:51], s[18:19], 0, v[50:51]
	v_lshl_add_u64 v[50:51], s[30:31], 2, v[50:51]
	s_lshl_b32 s8, s50, 2
	v_lshl_add_u64 v[50:51], v[50:51], 0, s[8:9]
	s_waitcnt lgkmcnt(0)
	v_add_f32_e32 v48, v48, v49
	global_store_dword v[50:51], v48, off
.LBB0_1158:
	s_or_b64 exec, exec, s[36:37]
	v_add_u32_e32 v48, 0x90, v150
	s_waitcnt lgkmcnt(0)
	v_ashrrev_i32_e32 v49, 31, v48
	v_lshlrev_b64 v[50:51], 11, v[48:49]
	v_lshl_add_u64 v[50:51], s[14:15], 0, v[50:51]
	v_lshl_add_u64 v[54:55], v[148:149], 1, v[50:51]
	s_waitcnt vmcnt(11)
	v_lshlrev_b32_e32 v56, 16, v196
	v_and_b32_e32 v50, 0xffff0000, v196
	v_lshlrev_b32_e32 v57, 16, v197
	v_and_b32_e32 v51, 0xffff0000, v197
	v_lshlrev_b32_e32 v58, 16, v198
	v_and_b32_e32 v52, 0xffff0000, v198
	v_lshlrev_b32_e32 v59, 16, v199
	v_and_b32_e32 v53, 0xffff0000, v199
	v_add_f32_e32 v56, v44, v56
	v_add_f32_e32 v50, v45, v50
	v_add_f32_e32 v57, v46, v57
	v_add_f32_e32 v51, v47, v51
	v_add_f32_e32 v58, v40, v58
	v_add_f32_e32 v52, v41, v52
	v_add_f32_e32 v59, v42, v59
	v_add_f32_e32 v53, v43, v53
	v_cvt_pk_bf16_f32 v40, v56, v50
	v_cvt_pk_bf16_f32 v41, v57, v51
	v_cvt_pk_bf16_f32 v42, v58, v52
	v_cvt_pk_bf16_f32 v43, v59, v53
	v_mul_f32_e32 v50, v50, v50
	v_mul_f32_e32 v51, v51, v51
	v_mul_f32_e32 v52, v52, v52
	v_mul_f32_e32 v53, v53, v53
	v_fmac_f32_e32 v50, v56, v56
	v_fmac_f32_e32 v51, v57, v57
	v_fmac_f32_e32 v52, v58, v58
	v_fmac_f32_e32 v53, v59, v59
	v_add_f32_e32 v50, v50, v51
	v_add_f32_e32 v51, v52, v53
	v_add_f32_e32 v50, v50, v51
	global_store_dwordx4 v[54:55], v[40:43], off
	s_waitcnt vmcnt(11)
	v_lshlrev_b32_e32 v51, 16, v200
	v_and_b32_e32 v44, 0xffff0000, v200
	v_lshlrev_b32_e32 v52, 16, v201
	v_and_b32_e32 v45, 0xffff0000, v201
	v_lshlrev_b32_e32 v53, 16, v202
	v_and_b32_e32 v46, 0xffff0000, v202
	v_lshlrev_b32_e32 v56, 16, v203
	v_and_b32_e32 v47, 0xffff0000, v203
	v_add_f32_e32 v37, v37, v44
	v_add_f32_e32 v39, v39, v45
	v_add_f32_e32 v45, v33, v46
	v_add_f32_e32 v47, v35, v47
	v_add_f32_e32 v36, v36, v51
	v_add_f32_e32 v38, v38, v52
	v_add_f32_e32 v44, v32, v53
	v_add_f32_e32 v46, v34, v56
	v_mul_f32_e32 v32, v37, v37
	v_mul_f32_e32 v33, v39, v39
	v_mul_f32_e32 v34, v45, v45
	v_mul_f32_e32 v35, v47, v47
	v_fmac_f32_e32 v32, v36, v36
	v_fmac_f32_e32 v33, v38, v38
	v_fmac_f32_e32 v34, v44, v44
	v_fmac_f32_e32 v35, v46, v46
	v_add_f32_e32 v32, v32, v33
	v_add_f32_e32 v33, v34, v35
	v_add_f32_e32 v32, v32, v33
	v_add_f32_e32 v32, v50, v32
	v_mov_b32_e32 v33, v32
	s_nop 1
	v_permlane16_swap_b32_e32 v33, v32
	v_cvt_pk_bf16_f32 v34, v36, v37
	v_cvt_pk_bf16_f32 v35, v38, v39
	v_cvt_pk_bf16_f32 v36, v44, v45
	v_cvt_pk_bf16_f32 v37, v46, v47
	s_waitcnt lgkmcnt(0)
	v_add_f32_e32 v32, v32, v33
	v_mov_b32_e32 v33, v32
	s_nop 1
	v_permlane32_swap_b32_e32 v33, v32
	global_store_dwordx4 v[54:55], v[34:37], off offset:256
	s_and_saveexec_b64 s[36:37], s[4:5]
	s_cbranch_execz .LBB0_1160
	v_lshlrev_b64 v[34:35], 6, v[48:49]
	v_lshl_add_u64 v[34:35], s[18:19], 0, v[34:35]
	v_lshl_add_u64 v[34:35], s[30:31], 2, v[34:35]
	s_lshl_b32 s8, s50, 2
	v_lshl_add_u64 v[34:35], v[34:35], 0, s[8:9]
	s_waitcnt lgkmcnt(0)
	v_add_f32_e32 v32, v32, v33
	global_store_dword v[34:35], v32, off
.LBB0_1160:
	s_or_b64 exec, exec, s[36:37]
	v_add_u32_e32 v32, 0xa0, v150
	s_waitcnt lgkmcnt(0)
	v_ashrrev_i32_e32 v33, 31, v32
	v_lshlrev_b64 v[34:35], 11, v[32:33]
	v_lshl_add_u64 v[34:35], s[14:15], 0, v[34:35]
	v_lshl_add_u64 v[38:39], v[148:149], 1, v[34:35]
	s_waitcnt vmcnt(9)
	v_lshlrev_b32_e32 v40, 16, v204
	v_and_b32_e32 v34, 0xffff0000, v204
	v_lshlrev_b32_e32 v41, 16, v205
	v_and_b32_e32 v35, 0xffff0000, v205
	v_lshlrev_b32_e32 v42, 16, v206
	v_and_b32_e32 v36, 0xffff0000, v206
	v_lshlrev_b32_e32 v43, 16, v207
	v_and_b32_e32 v37, 0xffff0000, v207
	v_add_f32_e32 v40, v28, v40
	v_add_f32_e32 v34, v29, v34
	v_add_f32_e32 v41, v30, v41
	v_add_f32_e32 v35, v31, v35
	v_add_f32_e32 v42, v24, v42
	v_add_f32_e32 v36, v25, v36
	v_add_f32_e32 v43, v26, v43
	v_add_f32_e32 v37, v27, v37
	v_cvt_pk_bf16_f32 v24, v40, v34
	v_cvt_pk_bf16_f32 v25, v41, v35
	v_cvt_pk_bf16_f32 v26, v42, v36
	v_cvt_pk_bf16_f32 v27, v43, v37
	v_mul_f32_e32 v34, v34, v34
	v_mul_f32_e32 v35, v35, v35
	v_mul_f32_e32 v36, v36, v36
	v_mul_f32_e32 v37, v37, v37
	v_fmac_f32_e32 v34, v40, v40
	v_fmac_f32_e32 v35, v41, v41
	v_fmac_f32_e32 v36, v42, v42
	v_fmac_f32_e32 v37, v43, v43
	v_add_f32_e32 v34, v34, v35
	v_add_f32_e32 v35, v36, v37
	v_add_f32_e32 v34, v34, v35
	global_store_dwordx4 v[38:39], v[24:27], off
	s_waitcnt vmcnt(9)
	v_lshlrev_b32_e32 v35, 16, v208
	v_and_b32_e32 v28, 0xffff0000, v208
	v_lshlrev_b32_e32 v36, 16, v209
	v_and_b32_e32 v29, 0xffff0000, v209
	v_lshlrev_b32_e32 v37, 16, v210
	v_and_b32_e32 v30, 0xffff0000, v210
	v_lshlrev_b32_e32 v40, 16, v211
	v_and_b32_e32 v31, 0xffff0000, v211
	v_add_f32_e32 v21, v21, v28
	v_add_f32_e32 v23, v23, v29
	v_add_f32_e32 v29, v17, v30
	v_add_f32_e32 v31, v19, v31
	v_add_f32_e32 v20, v20, v35
	v_add_f32_e32 v22, v22, v36
	v_add_f32_e32 v28, v16, v37
	v_add_f32_e32 v30, v18, v40
	v_mul_f32_e32 v16, v21, v21
	v_mul_f32_e32 v17, v23, v23
	v_mul_f32_e32 v18, v29, v29
	v_mul_f32_e32 v19, v31, v31
	v_fmac_f32_e32 v16, v20, v20
	v_fmac_f32_e32 v17, v22, v22
	v_fmac_f32_e32 v18, v28, v28
	v_fmac_f32_e32 v19, v30, v30
	v_add_f32_e32 v16, v16, v17
	v_add_f32_e32 v17, v18, v19
	v_add_f32_e32 v16, v16, v17
	v_add_f32_e32 v16, v34, v16
	v_mov_b32_e32 v17, v16
	s_nop 1
	v_permlane16_swap_b32_e32 v17, v16
	v_cvt_pk_bf16_f32 v18, v20, v21
	v_cvt_pk_bf16_f32 v19, v22, v23
	v_cvt_pk_bf16_f32 v20, v28, v29
	v_cvt_pk_bf16_f32 v21, v30, v31
	s_waitcnt lgkmcnt(0)
	v_add_f32_e32 v16, v16, v17
	v_mov_b32_e32 v17, v16
	s_nop 1
	v_permlane32_swap_b32_e32 v17, v16
	global_store_dwordx4 v[38:39], v[18:21], off offset:256
	s_and_saveexec_b64 s[36:37], s[4:5]
	s_cbranch_execz .LBB0_1162
	v_lshlrev_b64 v[18:19], 6, v[32:33]
	v_lshl_add_u64 v[18:19], s[18:19], 0, v[18:19]
	v_lshl_add_u64 v[18:19], s[30:31], 2, v[18:19]
	s_lshl_b32 s8, s50, 2
	v_lshl_add_u64 v[18:19], v[18:19], 0, s[8:9]
	s_waitcnt lgkmcnt(0)
	v_add_f32_e32 v16, v16, v17
	global_store_dword v[18:19], v16, off
.LBB0_1162:
	s_or_b64 exec, exec, s[36:37]
	v_add_u32_e32 v16, 0xb0, v150
	s_waitcnt lgkmcnt(0)
	v_ashrrev_i32_e32 v17, 31, v16
	v_lshlrev_b64 v[18:19], 11, v[16:17]
	v_lshl_add_u64 v[18:19], s[14:15], 0, v[18:19]
	v_lshl_add_u64 v[22:23], v[148:149], 1, v[18:19]
	s_waitcnt vmcnt(7)
	v_lshlrev_b32_e32 v24, 16, v212
	v_and_b32_e32 v18, 0xffff0000, v212
	v_lshlrev_b32_e32 v25, 16, v213
	v_and_b32_e32 v19, 0xffff0000, v213
	v_lshlrev_b32_e32 v26, 16, v214
	v_and_b32_e32 v20, 0xffff0000, v214
	v_lshlrev_b32_e32 v27, 16, v215
	v_and_b32_e32 v21, 0xffff0000, v215
	v_add_f32_e32 v24, v12, v24
	v_add_f32_e32 v18, v13, v18
	v_add_f32_e32 v25, v14, v25
	v_add_f32_e32 v19, v15, v19
	v_add_f32_e32 v26, v8, v26
	v_add_f32_e32 v20, v9, v20
	v_add_f32_e32 v27, v10, v27
	v_add_f32_e32 v21, v11, v21
	v_cvt_pk_bf16_f32 v8, v24, v18
	v_cvt_pk_bf16_f32 v9, v25, v19
	v_cvt_pk_bf16_f32 v10, v26, v20
	v_cvt_pk_bf16_f32 v11, v27, v21
	v_mul_f32_e32 v18, v18, v18
	v_mul_f32_e32 v19, v19, v19
	v_mul_f32_e32 v20, v20, v20
	v_mul_f32_e32 v21, v21, v21
	v_fmac_f32_e32 v18, v24, v24
	v_fmac_f32_e32 v19, v25, v25
	v_fmac_f32_e32 v20, v26, v26
	v_fmac_f32_e32 v21, v27, v27
	v_add_f32_e32 v18, v18, v19
	v_add_f32_e32 v19, v20, v21
	v_add_f32_e32 v18, v18, v19
	global_store_dwordx4 v[22:23], v[8:11], off
	s_waitcnt vmcnt(7)
	v_lshlrev_b32_e32 v19, 16, v216
	v_and_b32_e32 v12, 0xffff0000, v216
	v_lshlrev_b32_e32 v20, 16, v217
	v_and_b32_e32 v13, 0xffff0000, v217
	v_lshlrev_b32_e32 v21, 16, v218
	v_and_b32_e32 v14, 0xffff0000, v218
	v_lshlrev_b32_e32 v24, 16, v219
	v_and_b32_e32 v15, 0xffff0000, v219
	v_add_f32_e32 v5, v5, v12
	v_add_f32_e32 v7, v7, v13
	v_add_f32_e32 v13, v1, v14
	v_add_f32_e32 v15, v3, v15
	v_add_f32_e32 v4, v4, v19
	v_add_f32_e32 v6, v6, v20
	v_add_f32_e32 v12, v0, v21
	v_add_f32_e32 v14, v2, v24
	v_mul_f32_e32 v0, v5, v5
	v_mul_f32_e32 v1, v7, v7
	v_mul_f32_e32 v2, v13, v13
	v_mul_f32_e32 v3, v15, v15
	v_fmac_f32_e32 v0, v4, v4
	v_fmac_f32_e32 v1, v6, v6
	v_fmac_f32_e32 v2, v12, v12
	v_fmac_f32_e32 v3, v14, v14
	v_add_f32_e32 v0, v0, v1
	v_add_f32_e32 v1, v2, v3
	v_add_f32_e32 v0, v0, v1
	v_add_f32_e32 v0, v18, v0
	v_mov_b32_e32 v1, v0
	s_nop 1
	v_permlane16_swap_b32_e32 v1, v0
	v_cvt_pk_bf16_f32 v2, v4, v5
	v_cvt_pk_bf16_f32 v3, v6, v7
	v_cvt_pk_bf16_f32 v4, v12, v13
	v_cvt_pk_bf16_f32 v5, v14, v15
	s_waitcnt lgkmcnt(0)
	v_add_f32_e32 v0, v0, v1
	v_mov_b32_e32 v1, v0
	s_nop 1
	v_permlane32_swap_b32_e32 v1, v0
	global_store_dwordx4 v[22:23], v[2:5], off offset:256
	s_and_saveexec_b64 s[36:37], s[4:5]
	s_cbranch_execz .LBB0_1164
	v_lshlrev_b64 v[2:3], 6, v[16:17]
	v_lshl_add_u64 v[2:3], s[18:19], 0, v[2:3]
	v_lshl_add_u64 v[2:3], s[30:31], 2, v[2:3]
	s_lshl_b32 s8, s50, 2
	v_lshl_add_u64 v[2:3], v[2:3], 0, s[8:9]
	s_waitcnt lgkmcnt(0)
	v_add_f32_e32 v0, v0, v1
	global_store_dword v[2:3], v0, off

.LBB0_1560:
	v_lshl_add_u32 v148, s38, 8, v150
	v_ashrrev_i32_e32 v149, 31, v148
	v_lshl_or_b32 v146, s0, 8, v152
	v_lshlrev_b64 v[158:159], 11, v[148:149]
	v_ashrrev_i32_e32 v147, 31, v146
	v_lshl_add_u64 v[158:159], s[14:15], 0, v[158:159]
	v_lshl_add_u64 v[162:163], v[146:147], 1, v[158:159]
	v_mov_b32_e32 v232, v162
	v_mov_b32_e32 v233, v163
	global_load_dwordx4 v[188:191], v[232:233], off
	global_load_dwordx4 v[192:195], v[232:233], off offset:256
	s_mov_b64 s[100:101], 0x8000
	v_lshl_add_u64 v[230:231], v[232:233], 0, s[100:101]
	global_load_dwordx4 v[196:199], v[230:231], off
	global_load_dwordx4 v[200:203], v[230:231], off offset:256
	s_mov_b64 s[100:101], 0x10000
	v_lshl_add_u64 v[230:231], v[232:233], 0, s[100:101]
	global_load_dwordx4 v[204:207], v[230:231], off
	global_load_dwordx4 v[208:211], v[230:231], off offset:256
	s_mov_b64 s[100:101], 0x18000
	v_lshl_add_u64 v[230:231], v[232:233], 0, s[100:101]
	global_load_dwordx4 v[212:215], v[230:231], off
	global_load_dwordx4 v[216:219], v[230:231], off offset:256
	v_and_b32_e32 v169, 64, v157
	v_add_u32_e32 v169, 64, v169
	v_xor_b32_e32 v170, 32, v157
	s_lshl_b32 s38, s0, 2
	s_ashr_i32 s39, s38, 31
	s_waitcnt vmcnt(7)
	v_lshlrev_b32_e32 v164, 16, v188
	v_and_b32_e32 v158, 0xffff0000, v188
	v_lshlrev_b32_e32 v165, 16, v189
	v_and_b32_e32 v159, 0xffff0000, v189
	v_lshlrev_b32_e32 v166, 16, v190
	v_and_b32_e32 v160, 0xffff0000, v190
	v_lshlrev_b32_e32 v167, 16, v191
	v_and_b32_e32 v161, 0xffff0000, v191
	v_add_f32_e32 v164, v124, v164
	v_add_f32_e32 v168, v125, v158
	v_add_f32_e32 v126, v126, v165
	v_add_f32_e32 v127, v127, v159
	v_add_f32_e32 v165, v120, v166
	v_add_f32_e32 v121, v121, v160
	v_add_f32_e32 v166, v122, v167
	v_add_f32_e32 v167, v123, v161
	v_cvt_pk_bf16_f32 v122, v164, v168
	v_cvt_pk_bf16_f32 v123, v126, v127
	v_cvt_pk_bf16_f32 v124, v165, v121
	v_cvt_pk_bf16_f32 v125, v166, v167
	v_mul_f32_e32 v168, v168, v168
	v_mul_f32_e32 v127, v127, v127
	v_mul_f32_e32 v121, v121, v121
	v_mul_f32_e32 v167, v167, v167
	v_fmac_f32_e32 v168, v164, v164
	v_fmac_f32_e32 v127, v126, v126
	v_fmac_f32_e32 v121, v165, v165
	v_fmac_f32_e32 v167, v166, v166
	v_add_f32_e32 v126, v168, v127
	v_add_f32_e32 v121, v121, v167
	v_add_f32_e32 v121, v126, v121
	v_xor_b32_e32 v120, 16, v157
	v_cmp_lt_i32_e32 vcc, v120, v169
	global_store_dwordx4 v[162:163], v[122:125], off
	s_waitcnt vmcnt(7)
	v_lshlrev_b32_e32 v126, 16, v192
	v_and_b32_e32 v127, 0xffff0000, v192
	v_lshlrev_b32_e32 v158, 16, v193
	v_and_b32_e32 v159, 0xffff0000, v193
	v_lshlrev_b32_e32 v164, 16, v194
	v_and_b32_e32 v160, 0xffff0000, v194
	v_lshlrev_b32_e32 v165, 16, v195
	v_and_b32_e32 v161, 0xffff0000, v195
	v_add_f32_e32 v117, v117, v127
	v_add_f32_e32 v119, v119, v159
	v_add_f32_e32 v127, v113, v160
	v_add_f32_e32 v115, v115, v161
	v_add_f32_e32 v116, v116, v126
	v_add_f32_e32 v118, v118, v158
	v_add_f32_e32 v126, v112, v164
	v_add_f32_e32 v158, v114, v165
	v_mul_f32_e32 v112, v117, v117
	v_mul_f32_e32 v113, v119, v119
	v_mul_f32_e32 v114, v127, v127
	v_mul_f32_e32 v159, v115, v115
	v_fmac_f32_e32 v112, v116, v116
	v_fmac_f32_e32 v113, v118, v118
	v_fmac_f32_e32 v114, v126, v126
	v_fmac_f32_e32 v159, v158, v158
	v_add_f32_e32 v112, v112, v113
	v_add_f32_e32 v113, v114, v159
	v_cndmask_b32_e32 v120, v157, v120, vcc
	v_add_f32_e32 v112, v112, v113
	v_lshlrev_b32_e32 v120, 2, v120
	v_add_f32_e32 v112, v121, v112
	v_mov_b32_e32 v113, v112
	s_nop 1
	v_permlane16_swap_b32_e32 v113, v112
	v_cmp_lt_i32_e32 vcc, v170, v169
	v_cvt_pk_bf16_f32 v116, v116, v117
	v_cvt_pk_bf16_f32 v117, v118, v119
	v_cvt_pk_bf16_f32 v118, v126, v127
	s_waitcnt lgkmcnt(0)
	v_add_f32_e32 v112, v112, v113
	v_cvt_pk_bf16_f32 v119, v158, v115
	v_cndmask_b32_e32 v114, v157, v170, vcc
	v_lshlrev_b32_e32 v114, 2, v114
	v_mov_b32_e32 v113, v112
	s_nop 1
	v_permlane32_swap_b32_e32 v113, v112
	global_store_dwordx4 v[162:163], v[116:119], off offset:256
	s_and_saveexec_b64 s[40:41], s[4:5]
	s_cbranch_execz .LBB0_1562
	v_lshlrev_b64 v[116:117], 6, v[148:149]
	v_lshl_add_u64 v[116:117], s[18:19], 0, v[116:117]
	v_lshl_add_u64 v[116:117], s[38:39], 2, v[116:117]
	s_lshl_b32 s0, s52, 2
	v_lshl_add_u64 v[116:117], v[116:117], 0, s[0:1]
	s_waitcnt lgkmcnt(0)
	v_add_f32_e32 v112, v112, v113
	global_store_dword v[116:117], v112, off
.LBB0_1562:
	s_or_b64 exec, exec, s[40:41]
	v_or_b32_e32 v112, 16, v148
	s_waitcnt lgkmcnt(0)
	v_ashrrev_i32_e32 v113, 31, v112
	v_lshlrev_b64 v[116:117], 11, v[112:113]
	v_lshl_add_u64 v[116:117], s[14:15], 0, v[116:117]
	v_lshl_add_u64 v[122:123], v[146:147], 1, v[116:117]
	s_mov_b64 s[100:101], 0x40000
	v_lshl_add_u64 v[230:231], v[232:233], 0, s[100:101]
	global_load_dwordx4 v[188:191], v[230:231], off
	global_load_dwordx4 v[192:195], v[230:231], off offset:256
	s_waitcnt vmcnt(9)
	v_lshlrev_b32_e32 v115, 16, v196
	v_and_b32_e32 v116, 0xffff0000, v196
	v_lshlrev_b32_e32 v121, 16, v197
	v_and_b32_e32 v117, 0xffff0000, v197
	v_lshlrev_b32_e32 v124, 16, v198
	v_and_b32_e32 v118, 0xffff0000, v198
	v_lshlrev_b32_e32 v125, 16, v199
	v_and_b32_e32 v119, 0xffff0000, v199
	v_add_f32_e32 v115, v108, v115
	v_add_f32_e32 v116, v109, v116
	v_add_f32_e32 v121, v110, v121
	v_add_f32_e32 v117, v111, v117
	v_add_f32_e32 v124, v104, v124
	v_add_f32_e32 v118, v105, v118
	v_add_f32_e32 v125, v106, v125
	v_add_f32_e32 v119, v107, v119
	v_cvt_pk_bf16_f32 v104, v115, v116
	v_cvt_pk_bf16_f32 v105, v121, v117
	v_cvt_pk_bf16_f32 v106, v124, v118
	v_cvt_pk_bf16_f32 v107, v125, v119
	v_mul_f32_e32 v116, v116, v116
	v_mul_f32_e32 v117, v117, v117
	v_mul_f32_e32 v118, v118, v118
	v_mul_f32_e32 v119, v119, v119
	v_fmac_f32_e32 v116, v115, v115
	v_fmac_f32_e32 v117, v121, v121
	v_fmac_f32_e32 v118, v124, v124
	v_fmac_f32_e32 v119, v125, v125
	v_add_f32_e32 v115, v116, v117
	v_add_f32_e32 v116, v118, v119
	v_add_f32_e32 v115, v115, v116
	global_store_dwordx4 v[122:123], v[104:107], off
	s_waitcnt vmcnt(9)
	v_lshlrev_b32_e32 v116, 16, v200
	v_and_b32_e32 v108, 0xffff0000, v200
	v_lshlrev_b32_e32 v117, 16, v201
	v_and_b32_e32 v109, 0xffff0000, v201
	v_lshlrev_b32_e32 v118, 16, v202
	v_and_b32_e32 v110, 0xffff0000, v202
	v_lshlrev_b32_e32 v119, 16, v203
	v_and_b32_e32 v111, 0xffff0000, v203
	v_add_f32_e32 v101, v101, v108
	v_add_f32_e32 v103, v103, v109
	v_add_f32_e32 v109, v97, v110
	v_add_f32_e32 v111, v99, v111
	v_add_f32_e32 v100, v100, v116
	v_add_f32_e32 v102, v102, v117
	v_add_f32_e32 v108, v96, v118
	v_add_f32_e32 v110, v98, v119
	v_mul_f32_e32 v96, v101, v101
	v_mul_f32_e32 v97, v103, v103
	v_mul_f32_e32 v98, v109, v109
	v_mul_f32_e32 v99, v111, v111
	v_fmac_f32_e32 v96, v100, v100
	v_fmac_f32_e32 v97, v102, v102
	v_fmac_f32_e32 v98, v108, v108
	v_fmac_f32_e32 v99, v110, v110
	v_add_f32_e32 v96, v96, v97
	v_add_f32_e32 v97, v98, v99
	v_add_f32_e32 v96, v96, v97
	v_add_f32_e32 v96, v115, v96
	v_mov_b32_e32 v97, v96
	s_nop 1
	v_permlane16_swap_b32_e32 v97, v96
	v_cvt_pk_bf16_f32 v98, v100, v101
	v_cvt_pk_bf16_f32 v99, v102, v103
	v_cvt_pk_bf16_f32 v100, v108, v109
	v_cvt_pk_bf16_f32 v101, v110, v111
	s_waitcnt lgkmcnt(0)
	v_add_f32_e32 v96, v96, v97
	v_mov_b32_e32 v97, v96
	s_nop 1
	v_permlane32_swap_b32_e32 v97, v96
	global_store_dwordx4 v[122:123], v[98:101], off offset:256
	s_and_saveexec_b64 s[40:41], s[4:5]
	s_cbranch_execz .LBB0_1564
	v_lshlrev_b64 v[98:99], 6, v[112:113]
	v_lshl_add_u64 v[98:99], s[18:19], 0, v[98:99]
	v_lshl_add_u64 v[98:99], s[38:39], 2, v[98:99]
	s_lshl_b32 s0, s52, 2
	v_lshl_add_u64 v[98:99], v[98:99], 0, s[0:1]
	s_waitcnt lgkmcnt(0)
	v_add_f32_e32 v96, v96, v97
	global_store_dword v[98:99], v96, off
.LBB0_1564:
	s_or_b64 exec, exec, s[40:41]
	v_or_b32_e32 v96, 32, v148
	s_waitcnt lgkmcnt(0)
	v_ashrrev_i32_e32 v97, 31, v96
	v_lshlrev_b64 v[98:99], 11, v[96:97]
	v_lshl_add_u64 v[98:99], s[14:15], 0, v[98:99]
	v_lshl_add_u64 v[102:103], v[146:147], 1, v[98:99]
	s_mov_b64 s[100:101], 0x48000
	v_lshl_add_u64 v[230:231], v[232:233], 0, s[100:101]
	global_load_dwordx4 v[196:199], v[230:231], off
	global_load_dwordx4 v[200:203], v[230:231], off offset:256
	s_waitcnt vmcnt(11)
	v_lshlrev_b32_e32 v104, 16, v204
	v_and_b32_e32 v98, 0xffff0000, v204
	v_lshlrev_b32_e32 v105, 16, v205
	v_and_b32_e32 v99, 0xffff0000, v205
	v_lshlrev_b32_e32 v106, 16, v206
	v_and_b32_e32 v100, 0xffff0000, v206
	v_lshlrev_b32_e32 v107, 16, v207
	v_and_b32_e32 v101, 0xffff0000, v207
	v_add_f32_e32 v104, v92, v104
	v_add_f32_e32 v98, v93, v98
	v_add_f32_e32 v105, v94, v105
	v_add_f32_e32 v99, v95, v99
	v_add_f32_e32 v106, v88, v106
	v_add_f32_e32 v100, v89, v100
	v_add_f32_e32 v107, v90, v107
	v_add_f32_e32 v101, v91, v101
	v_cvt_pk_bf16_f32 v88, v104, v98
	v_cvt_pk_bf16_f32 v89, v105, v99
	v_cvt_pk_bf16_f32 v90, v106, v100
	v_cvt_pk_bf16_f32 v91, v107, v101
	v_mul_f32_e32 v98, v98, v98
	v_mul_f32_e32 v99, v99, v99
	v_mul_f32_e32 v100, v100, v100
	v_mul_f32_e32 v101, v101, v101
	v_fmac_f32_e32 v98, v104, v104
	v_fmac_f32_e32 v99, v105, v105
	v_fmac_f32_e32 v100, v106, v106
	v_fmac_f32_e32 v101, v107, v107
	v_add_f32_e32 v98, v98, v99
	v_add_f32_e32 v99, v100, v101
	v_add_f32_e32 v98, v98, v99
	global_store_dwordx4 v[102:103], v[88:91], off
	s_waitcnt vmcnt(11)
	v_lshlrev_b32_e32 v99, 16, v208
	v_and_b32_e32 v92, 0xffff0000, v208
	v_lshlrev_b32_e32 v100, 16, v209
	v_and_b32_e32 v93, 0xffff0000, v209
	v_lshlrev_b32_e32 v101, 16, v210
	v_and_b32_e32 v94, 0xffff0000, v210
	v_lshlrev_b32_e32 v104, 16, v211
	v_and_b32_e32 v95, 0xffff0000, v211
	v_add_f32_e32 v85, v85, v92
	v_add_f32_e32 v87, v87, v93
	v_add_f32_e32 v93, v81, v94
	v_add_f32_e32 v95, v83, v95
	v_add_f32_e32 v84, v84, v99
	v_add_f32_e32 v86, v86, v100
	v_add_f32_e32 v92, v80, v101
	v_add_f32_e32 v94, v82, v104
	v_mul_f32_e32 v80, v85, v85
	v_mul_f32_e32 v81, v87, v87
	v_mul_f32_e32 v82, v93, v93
	v_mul_f32_e32 v83, v95, v95
	v_fmac_f32_e32 v80, v84, v84
	v_fmac_f32_e32 v81, v86, v86
	v_fmac_f32_e32 v82, v92, v92
	v_fmac_f32_e32 v83, v94, v94
	v_add_f32_e32 v80, v80, v81
	v_add_f32_e32 v81, v82, v83
	v_add_f32_e32 v80, v80, v81
	v_add_f32_e32 v80, v98, v80
	v_mov_b32_e32 v81, v80
	s_nop 1
	v_permlane16_swap_b32_e32 v81, v80
	v_cvt_pk_bf16_f32 v82, v84, v85
	v_cvt_pk_bf16_f32 v83, v86, v87
	v_cvt_pk_bf16_f32 v84, v92, v93
	v_cvt_pk_bf16_f32 v85, v94, v95
	s_waitcnt lgkmcnt(0)
	v_add_f32_e32 v80, v80, v81
	v_mov_b32_e32 v81, v80
	s_nop 1
	v_permlane32_swap_b32_e32 v81, v80
	global_store_dwordx4 v[102:103], v[82:85], off offset:256
	s_and_saveexec_b64 s[40:41], s[4:5]
	s_cbranch_execz .LBB0_1566
	v_lshlrev_b64 v[82:83], 6, v[96:97]
	v_lshl_add_u64 v[82:83], s[18:19], 0, v[82:83]
	v_lshl_add_u64 v[82:83], s[38:39], 2, v[82:83]
	s_lshl_b32 s0, s52, 2
	v_lshl_add_u64 v[82:83], v[82:83], 0, s[0:1]
	s_waitcnt lgkmcnt(0)
	v_add_f32_e32 v80, v80, v81
	global_store_dword v[82:83], v80, off
.LBB0_1566:
	s_or_b64 exec, exec, s[40:41]
	v_or_b32_e32 v80, 48, v148
	s_waitcnt lgkmcnt(0)
	v_ashrrev_i32_e32 v81, 31, v80
	v_lshlrev_b64 v[82:83], 11, v[80:81]
	v_lshl_add_u64 v[82:83], s[14:15], 0, v[82:83]
	v_lshl_add_u64 v[86:87], v[146:147], 1, v[82:83]
	s_mov_b64 s[100:101], 0x50000
	v_lshl_add_u64 v[230:231], v[232:233], 0, s[100:101]
	global_load_dwordx4 v[204:207], v[230:231], off
	global_load_dwordx4 v[208:211], v[230:231], off offset:256
	s_waitcnt vmcnt(13)
	v_lshlrev_b32_e32 v88, 16, v212
	v_and_b32_e32 v82, 0xffff0000, v212
	v_lshlrev_b32_e32 v89, 16, v213
	v_and_b32_e32 v83, 0xffff0000, v213
	v_lshlrev_b32_e32 v90, 16, v214
	v_and_b32_e32 v84, 0xffff0000, v214
	v_lshlrev_b32_e32 v91, 16, v215
	v_and_b32_e32 v85, 0xffff0000, v215
	v_add_f32_e32 v88, v76, v88
	v_add_f32_e32 v82, v77, v82
	v_add_f32_e32 v89, v78, v89
	v_add_f32_e32 v83, v79, v83
	v_add_f32_e32 v90, v72, v90
	v_add_f32_e32 v84, v73, v84
	v_add_f32_e32 v91, v74, v91
	v_add_f32_e32 v85, v75, v85
	v_cvt_pk_bf16_f32 v72, v88, v82
	v_cvt_pk_bf16_f32 v73, v89, v83
	v_cvt_pk_bf16_f32 v74, v90, v84
	v_cvt_pk_bf16_f32 v75, v91, v85
	v_mul_f32_e32 v82, v82, v82
	v_mul_f32_e32 v83, v83, v83
	v_mul_f32_e32 v84, v84, v84
	v_mul_f32_e32 v85, v85, v85
	v_fmac_f32_e32 v82, v88, v88
	v_fmac_f32_e32 v83, v89, v89
	v_fmac_f32_e32 v84, v90, v90
	v_fmac_f32_e32 v85, v91, v91
	v_add_f32_e32 v82, v82, v83
	v_add_f32_e32 v83, v84, v85
	v_add_f32_e32 v82, v82, v83
	global_store_dwordx4 v[86:87], v[72:75], off
	s_waitcnt vmcnt(13)
	v_lshlrev_b32_e32 v83, 16, v216
	v_and_b32_e32 v76, 0xffff0000, v216
	v_lshlrev_b32_e32 v84, 16, v217
	v_and_b32_e32 v77, 0xffff0000, v217
	v_lshlrev_b32_e32 v85, 16, v218
	v_and_b32_e32 v78, 0xffff0000, v218
	v_lshlrev_b32_e32 v88, 16, v219
	v_and_b32_e32 v79, 0xffff0000, v219
	v_add_f32_e32 v69, v69, v76
	v_add_f32_e32 v71, v71, v77
	v_add_f32_e32 v77, v65, v78
	v_add_f32_e32 v79, v67, v79
	v_add_f32_e32 v68, v68, v83
	v_add_f32_e32 v70, v70, v84
	v_add_f32_e32 v76, v64, v85
	v_add_f32_e32 v78, v66, v88
	v_mul_f32_e32 v64, v69, v69
	v_mul_f32_e32 v65, v71, v71
	v_mul_f32_e32 v66, v77, v77
	v_mul_f32_e32 v67, v79, v79
	v_fmac_f32_e32 v64, v68, v68
	v_fmac_f32_e32 v65, v70, v70
	v_fmac_f32_e32 v66, v76, v76
	v_fmac_f32_e32 v67, v78, v78
	v_add_f32_e32 v64, v64, v65
	v_add_f32_e32 v65, v66, v67
	v_add_f32_e32 v64, v64, v65
	v_add_f32_e32 v64, v82, v64
	v_mov_b32_e32 v65, v64
	s_nop 1
	v_permlane16_swap_b32_e32 v65, v64
	v_cvt_pk_bf16_f32 v66, v68, v69
	v_cvt_pk_bf16_f32 v67, v70, v71
	v_cvt_pk_bf16_f32 v68, v76, v77
	v_cvt_pk_bf16_f32 v69, v78, v79
	s_waitcnt lgkmcnt(0)
	v_add_f32_e32 v64, v64, v65
	v_mov_b32_e32 v65, v64
	s_nop 1
	v_permlane32_swap_b32_e32 v65, v64
	global_store_dwordx4 v[86:87], v[66:69], off offset:256
	s_and_saveexec_b64 s[40:41], s[4:5]
	s_cbranch_execz .LBB0_1568
	v_lshlrev_b64 v[66:67], 6, v[80:81]
	v_lshl_add_u64 v[66:67], s[18:19], 0, v[66:67]
	v_lshl_add_u64 v[66:67], s[38:39], 2, v[66:67]
	s_lshl_b32 s0, s52, 2
	v_lshl_add_u64 v[66:67], v[66:67], 0, s[0:1]
	s_waitcnt lgkmcnt(0)
	v_add_f32_e32 v64, v64, v65
	global_store_dword v[66:67], v64, off
.LBB0_1568:
	s_or_b64 exec, exec, s[40:41]
	v_add_u32_e32 v64, 0x80, v148
	s_waitcnt lgkmcnt(0)
	v_ashrrev_i32_e32 v65, 31, v64
	v_lshlrev_b64 v[66:67], 11, v[64:65]
	v_lshl_add_u64 v[66:67], s[14:15], 0, v[66:67]
	v_lshl_add_u64 v[70:71], v[146:147], 1, v[66:67]
	s_mov_b64 s[100:101], 0x58000
	v_lshl_add_u64 v[230:231], v[232:233], 0, s[100:101]
	global_load_dwordx4 v[212:215], v[230:231], off
	global_load_dwordx4 v[216:219], v[230:231], off offset:256
	s_waitcnt vmcnt(13)
	v_lshlrev_b32_e32 v72, 16, v188
	v_and_b32_e32 v66, 0xffff0000, v188
	v_lshlrev_b32_e32 v73, 16, v189
	v_and_b32_e32 v67, 0xffff0000, v189
	v_lshlrev_b32_e32 v74, 16, v190
	v_and_b32_e32 v68, 0xffff0000, v190
	v_lshlrev_b32_e32 v75, 16, v191
	v_and_b32_e32 v69, 0xffff0000, v191
	v_add_f32_e32 v72, v60, v72
	v_add_f32_e32 v66, v61, v66
	v_add_f32_e32 v73, v62, v73
	v_add_f32_e32 v67, v63, v67
	v_add_f32_e32 v74, v56, v74
	v_add_f32_e32 v68, v57, v68
	v_add_f32_e32 v75, v58, v75
	v_add_f32_e32 v69, v59, v69
	v_cvt_pk_bf16_f32 v56, v72, v66
	v_cvt_pk_bf16_f32 v57, v73, v67
	v_cvt_pk_bf16_f32 v58, v74, v68
	v_cvt_pk_bf16_f32 v59, v75, v69
	v_mul_f32_e32 v66, v66, v66
	v_mul_f32_e32 v67, v67, v67
	v_mul_f32_e32 v68, v68, v68
	v_mul_f32_e32 v69, v69, v69
	v_fmac_f32_e32 v66, v72, v72
	v_fmac_f32_e32 v67, v73, v73
	v_fmac_f32_e32 v68, v74, v74
	v_fmac_f32_e32 v69, v75, v75
	v_add_f32_e32 v66, v66, v67
	v_add_f32_e32 v67, v68, v69
	v_add_f32_e32 v66, v66, v67
	global_store_dwordx4 v[70:71], v[56:59], off
	s_waitcnt vmcnt(13)
	v_lshlrev_b32_e32 v67, 16, v192
	v_and_b32_e32 v60, 0xffff0000, v192
	v_lshlrev_b32_e32 v68, 16, v193
	v_and_b32_e32 v61, 0xffff0000, v193
	v_lshlrev_b32_e32 v69, 16, v194
	v_and_b32_e32 v62, 0xffff0000, v194
	v_lshlrev_b32_e32 v72, 16, v195
	v_and_b32_e32 v63, 0xffff0000, v195
	v_add_f32_e32 v53, v53, v60
	v_add_f32_e32 v55, v55, v61
	v_add_f32_e32 v61, v49, v62
	v_add_f32_e32 v63, v51, v63
	v_add_f32_e32 v52, v52, v67
	v_add_f32_e32 v54, v54, v68
	v_add_f32_e32 v60, v48, v69
	v_add_f32_e32 v62, v50, v72
	v_mul_f32_e32 v48, v53, v53
	v_mul_f32_e32 v49, v55, v55
	v_mul_f32_e32 v50, v61, v61
	v_mul_f32_e32 v51, v63, v63
	v_fmac_f32_e32 v48, v52, v52
	v_fmac_f32_e32 v49, v54, v54
	v_fmac_f32_e32 v50, v60, v60
	v_fmac_f32_e32 v51, v62, v62
	v_add_f32_e32 v48, v48, v49
	v_add_f32_e32 v49, v50, v51
	v_add_f32_e32 v48, v48, v49
	v_add_f32_e32 v48, v66, v48
	v_mov_b32_e32 v49, v48
	s_nop 1
	v_permlane16_swap_b32_e32 v49, v48
	v_cvt_pk_bf16_f32 v50, v52, v53
	v_cvt_pk_bf16_f32 v51, v54, v55
	v_cvt_pk_bf16_f32 v52, v60, v61
	v_cvt_pk_bf16_f32 v53, v62, v63
	s_waitcnt lgkmcnt(0)
	v_add_f32_e32 v48, v48, v49
	v_mov_b32_e32 v49, v48
	s_nop 1
	v_permlane32_swap_b32_e32 v49, v48
	global_store_dwordx4 v[70:71], v[50:53], off offset:256
	s_and_saveexec_b64 s[40:41], s[4:5]
	s_cbranch_execz .LBB0_1570
	v_lshlrev_b64 v[50:51], 6, v[64:65]
	v_lshl_add_u64 v[50:51], s[18:19], 0, v[50:51]
	v_lshl_add_u64 v[50:51], s[38:39], 2, v[50:51]
	s_lshl_b32 s0, s52, 2
	v_lshl_add_u64 v[50:51], v[50:51], 0, s[0:1]
	s_waitcnt lgkmcnt(0)
	v_add_f32_e32 v48, v48, v49
	global_store_dword v[50:51], v48, off
.LBB0_1570:
	s_or_b64 exec, exec, s[40:41]
	v_add_u32_e32 v48, 0x90, v148
	s_waitcnt lgkmcnt(0)
	v_ashrrev_i32_e32 v49, 31, v48
	v_lshlrev_b64 v[50:51], 11, v[48:49]
	v_lshl_add_u64 v[50:51], s[14:15], 0, v[50:51]
	v_lshl_add_u64 v[54:55], v[146:147], 1, v[50:51]
	s_waitcnt vmcnt(11)
	v_lshlrev_b32_e32 v56, 16, v196
	v_and_b32_e32 v50, 0xffff0000, v196
	v_lshlrev_b32_e32 v57, 16, v197
	v_and_b32_e32 v51, 0xffff0000, v197
	v_lshlrev_b32_e32 v58, 16, v198
	v_and_b32_e32 v52, 0xffff0000, v198
	v_lshlrev_b32_e32 v59, 16, v199
	v_and_b32_e32 v53, 0xffff0000, v199
	v_add_f32_e32 v56, v44, v56
	v_add_f32_e32 v50, v45, v50
	v_add_f32_e32 v57, v46, v57
	v_add_f32_e32 v51, v47, v51
	v_add_f32_e32 v58, v40, v58
	v_add_f32_e32 v52, v41, v52
	v_add_f32_e32 v59, v42, v59
	v_add_f32_e32 v53, v43, v53
	v_cvt_pk_bf16_f32 v40, v56, v50
	v_cvt_pk_bf16_f32 v41, v57, v51
	v_cvt_pk_bf16_f32 v42, v58, v52
	v_cvt_pk_bf16_f32 v43, v59, v53
	v_mul_f32_e32 v50, v50, v50
	v_mul_f32_e32 v51, v51, v51
	v_mul_f32_e32 v52, v52, v52
	v_mul_f32_e32 v53, v53, v53
	v_fmac_f32_e32 v50, v56, v56
	v_fmac_f32_e32 v51, v57, v57
	v_fmac_f32_e32 v52, v58, v58
	v_fmac_f32_e32 v53, v59, v59
	v_add_f32_e32 v50, v50, v51
	v_add_f32_e32 v51, v52, v53
	v_add_f32_e32 v50, v50, v51
	global_store_dwordx4 v[54:55], v[40:43], off
	s_waitcnt vmcnt(11)
	v_lshlrev_b32_e32 v51, 16, v200
	v_and_b32_e32 v44, 0xffff0000, v200
	v_lshlrev_b32_e32 v52, 16, v201
	v_and_b32_e32 v45, 0xffff0000, v201
	v_lshlrev_b32_e32 v53, 16, v202
	v_and_b32_e32 v46, 0xffff0000, v202
	v_lshlrev_b32_e32 v56, 16, v203
	v_and_b32_e32 v47, 0xffff0000, v203
	v_add_f32_e32 v37, v37, v44
	v_add_f32_e32 v39, v39, v45
	v_add_f32_e32 v45, v33, v46
	v_add_f32_e32 v47, v35, v47
	v_add_f32_e32 v36, v36, v51
	v_add_f32_e32 v38, v38, v52
	v_add_f32_e32 v44, v32, v53
	v_add_f32_e32 v46, v34, v56
	v_mul_f32_e32 v32, v37, v37
	v_mul_f32_e32 v33, v39, v39
	v_mul_f32_e32 v34, v45, v45
	v_mul_f32_e32 v35, v47, v47
	v_fmac_f32_e32 v32, v36, v36
	v_fmac_f32_e32 v33, v38, v38
	v_fmac_f32_e32 v34, v44, v44
	v_fmac_f32_e32 v35, v46, v46
	v_add_f32_e32 v32, v32, v33
	v_add_f32_e32 v33, v34, v35
	v_add_f32_e32 v32, v32, v33
	v_add_f32_e32 v32, v50, v32
	v_mov_b32_e32 v33, v32
	s_nop 1
	v_permlane16_swap_b32_e32 v33, v32
	v_cvt_pk_bf16_f32 v34, v36, v37
	v_cvt_pk_bf16_f32 v35, v38, v39
	v_cvt_pk_bf16_f32 v36, v44, v45
	v_cvt_pk_bf16_f32 v37, v46, v47
	s_waitcnt lgkmcnt(0)
	v_add_f32_e32 v32, v32, v33
	v_mov_b32_e32 v33, v32
	s_nop 1
	v_permlane32_swap_b32_e32 v33, v32
	global_store_dwordx4 v[54:55], v[34:37], off offset:256
	s_and_saveexec_b64 s[40:41], s[4:5]
	s_cbranch_execz .LBB0_1572
	v_lshlrev_b64 v[34:35], 6, v[48:49]
	v_lshl_add_u64 v[34:35], s[18:19], 0, v[34:35]
	v_lshl_add_u64 v[34:35], s[38:39], 2, v[34:35]
	s_lshl_b32 s0, s52, 2
	v_lshl_add_u64 v[34:35], v[34:35], 0, s[0:1]
	s_waitcnt lgkmcnt(0)
	v_add_f32_e32 v32, v32, v33
	global_store_dword v[34:35], v32, off
.LBB0_1572:
	s_or_b64 exec, exec, s[40:41]
	v_add_u32_e32 v32, 0xa0, v148
	s_waitcnt lgkmcnt(0)
	v_ashrrev_i32_e32 v33, 31, v32
	v_lshlrev_b64 v[34:35], 11, v[32:33]
	v_lshl_add_u64 v[34:35], s[14:15], 0, v[34:35]
	v_lshl_add_u64 v[38:39], v[146:147], 1, v[34:35]
	s_waitcnt vmcnt(9)
	v_lshlrev_b32_e32 v40, 16, v204
	v_and_b32_e32 v34, 0xffff0000, v204
	v_lshlrev_b32_e32 v41, 16, v205
	v_and_b32_e32 v35, 0xffff0000, v205
	v_lshlrev_b32_e32 v42, 16, v206
	v_and_b32_e32 v36, 0xffff0000, v206
	v_lshlrev_b32_e32 v43, 16, v207
	v_and_b32_e32 v37, 0xffff0000, v207
	v_add_f32_e32 v40, v28, v40
	v_add_f32_e32 v34, v29, v34
	v_add_f32_e32 v41, v30, v41
	v_add_f32_e32 v35, v31, v35
	v_add_f32_e32 v42, v24, v42
	v_add_f32_e32 v36, v25, v36
	v_add_f32_e32 v43, v26, v43
	v_add_f32_e32 v37, v27, v37
	v_cvt_pk_bf16_f32 v24, v40, v34
	v_cvt_pk_bf16_f32 v25, v41, v35
	v_cvt_pk_bf16_f32 v26, v42, v36
	v_cvt_pk_bf16_f32 v27, v43, v37
	v_mul_f32_e32 v34, v34, v34
	v_mul_f32_e32 v35, v35, v35
	v_mul_f32_e32 v36, v36, v36
	v_mul_f32_e32 v37, v37, v37
	v_fmac_f32_e32 v34, v40, v40
	v_fmac_f32_e32 v35, v41, v41
	v_fmac_f32_e32 v36, v42, v42
	v_fmac_f32_e32 v37, v43, v43
	v_add_f32_e32 v34, v34, v35
	v_add_f32_e32 v35, v36, v37
	v_add_f32_e32 v34, v34, v35
	global_store_dwordx4 v[38:39], v[24:27], off
	s_waitcnt vmcnt(9)
	v_lshlrev_b32_e32 v35, 16, v208
	v_and_b32_e32 v28, 0xffff0000, v208
	v_lshlrev_b32_e32 v36, 16, v209
	v_and_b32_e32 v29, 0xffff0000, v209
	v_lshlrev_b32_e32 v37, 16, v210
	v_and_b32_e32 v30, 0xffff0000, v210
	v_lshlrev_b32_e32 v40, 16, v211
	v_and_b32_e32 v31, 0xffff0000, v211
	v_add_f32_e32 v21, v21, v28
	v_add_f32_e32 v23, v23, v29
	v_add_f32_e32 v29, v17, v30
	v_add_f32_e32 v31, v19, v31
	v_add_f32_e32 v20, v20, v35
	v_add_f32_e32 v22, v22, v36
	v_add_f32_e32 v28, v16, v37
	v_add_f32_e32 v30, v18, v40
	v_mul_f32_e32 v16, v21, v21
	v_mul_f32_e32 v17, v23, v23
	v_mul_f32_e32 v18, v29, v29
	v_mul_f32_e32 v19, v31, v31
	v_fmac_f32_e32 v16, v20, v20
	v_fmac_f32_e32 v17, v22, v22
	v_fmac_f32_e32 v18, v28, v28
	v_fmac_f32_e32 v19, v30, v30
	v_add_f32_e32 v16, v16, v17
	v_add_f32_e32 v17, v18, v19
	v_add_f32_e32 v16, v16, v17
	v_add_f32_e32 v16, v34, v16
	v_mov_b32_e32 v17, v16
	s_nop 1
	v_permlane16_swap_b32_e32 v17, v16
	v_cvt_pk_bf16_f32 v18, v20, v21
	v_cvt_pk_bf16_f32 v19, v22, v23
	v_cvt_pk_bf16_f32 v20, v28, v29
	v_cvt_pk_bf16_f32 v21, v30, v31
	s_waitcnt lgkmcnt(0)
	v_add_f32_e32 v16, v16, v17
	v_mov_b32_e32 v17, v16
	s_nop 1
	v_permlane32_swap_b32_e32 v17, v16
	global_store_dwordx4 v[38:39], v[18:21], off offset:256
	s_and_saveexec_b64 s[40:41], s[4:5]
	s_cbranch_execz .LBB0_1574
	v_lshlrev_b64 v[18:19], 6, v[32:33]
	v_lshl_add_u64 v[18:19], s[18:19], 0, v[18:19]
	v_lshl_add_u64 v[18:19], s[38:39], 2, v[18:19]
	s_lshl_b32 s0, s52, 2
	v_lshl_add_u64 v[18:19], v[18:19], 0, s[0:1]
	s_waitcnt lgkmcnt(0)
	v_add_f32_e32 v16, v16, v17
	global_store_dword v[18:19], v16, off
.LBB0_1574:
	s_or_b64 exec, exec, s[40:41]
	v_add_u32_e32 v16, 0xb0, v148
	s_waitcnt lgkmcnt(0)
	v_ashrrev_i32_e32 v17, 31, v16
	v_lshlrev_b64 v[18:19], 11, v[16:17]
	v_lshl_add_u64 v[18:19], s[14:15], 0, v[18:19]
	v_lshl_add_u64 v[22:23], v[146:147], 1, v[18:19]
	s_waitcnt vmcnt(7)
	v_lshlrev_b32_e32 v24, 16, v212
	v_and_b32_e32 v18, 0xffff0000, v212
	v_lshlrev_b32_e32 v25, 16, v213
	v_and_b32_e32 v19, 0xffff0000, v213
	v_lshlrev_b32_e32 v26, 16, v214
	v_and_b32_e32 v20, 0xffff0000, v214
	v_lshlrev_b32_e32 v27, 16, v215
	v_and_b32_e32 v21, 0xffff0000, v215
	v_add_f32_e32 v24, v12, v24
	v_add_f32_e32 v18, v13, v18
	v_add_f32_e32 v25, v14, v25
	v_add_f32_e32 v19, v15, v19
	v_add_f32_e32 v26, v8, v26
	v_add_f32_e32 v20, v9, v20
	v_add_f32_e32 v27, v10, v27
	v_add_f32_e32 v21, v11, v21
	v_cvt_pk_bf16_f32 v8, v24, v18
	v_cvt_pk_bf16_f32 v9, v25, v19
	v_cvt_pk_bf16_f32 v10, v26, v20
	v_cvt_pk_bf16_f32 v11, v27, v21
	v_mul_f32_e32 v18, v18, v18
	v_mul_f32_e32 v19, v19, v19
	v_mul_f32_e32 v20, v20, v20
	v_mul_f32_e32 v21, v21, v21
	v_fmac_f32_e32 v18, v24, v24
	v_fmac_f32_e32 v19, v25, v25
	v_fmac_f32_e32 v20, v26, v26
	v_fmac_f32_e32 v21, v27, v27
	v_add_f32_e32 v18, v18, v19
	v_add_f32_e32 v19, v20, v21
	v_add_f32_e32 v18, v18, v19
	global_store_dwordx4 v[22:23], v[8:11], off
	s_waitcnt vmcnt(7)
	v_lshlrev_b32_e32 v19, 16, v216
	v_and_b32_e32 v12, 0xffff0000, v216
	v_lshlrev_b32_e32 v20, 16, v217
	v_and_b32_e32 v13, 0xffff0000, v217
	v_lshlrev_b32_e32 v21, 16, v218
	v_and_b32_e32 v14, 0xffff0000, v218
	v_lshlrev_b32_e32 v24, 16, v219
	v_and_b32_e32 v15, 0xffff0000, v219
	v_add_f32_e32 v5, v5, v12
	v_add_f32_e32 v7, v7, v13
	v_add_f32_e32 v13, v1, v14
	v_add_f32_e32 v15, v3, v15
	v_add_f32_e32 v4, v4, v19
	v_add_f32_e32 v6, v6, v20
	v_add_f32_e32 v12, v0, v21
	v_add_f32_e32 v14, v2, v24
	v_mul_f32_e32 v0, v5, v5
	v_mul_f32_e32 v1, v7, v7
	v_mul_f32_e32 v2, v13, v13
	v_mul_f32_e32 v3, v15, v15
	v_fmac_f32_e32 v0, v4, v4
	v_fmac_f32_e32 v1, v6, v6
	v_fmac_f32_e32 v2, v12, v12
	v_fmac_f32_e32 v3, v14, v14
	v_add_f32_e32 v0, v0, v1
	v_add_f32_e32 v1, v2, v3
	v_add_f32_e32 v0, v0, v1
	v_add_f32_e32 v0, v18, v0
	v_mov_b32_e32 v1, v0
	s_nop 1
	v_permlane16_swap_b32_e32 v1, v0
	v_cvt_pk_bf16_f32 v2, v4, v5
	v_cvt_pk_bf16_f32 v3, v6, v7
	v_cvt_pk_bf16_f32 v4, v12, v13
	v_cvt_pk_bf16_f32 v5, v14, v15
	s_waitcnt lgkmcnt(0)
	v_add_f32_e32 v0, v0, v1
	v_mov_b32_e32 v1, v0
	s_nop 1
	v_permlane32_swap_b32_e32 v1, v0
	global_store_dwordx4 v[22:23], v[2:5], off offset:256
	s_and_saveexec_b64 s[40:41], s[4:5]
	s_cbranch_execz .LBB0_1576
	v_lshlrev_b64 v[2:3], 6, v[16:17]
	v_lshl_add_u64 v[2:3], s[18:19], 0, v[2:3]
	v_lshl_add_u64 v[2:3], s[38:39], 2, v[2:3]
	s_lshl_b32 s0, s52, 2
	v_lshl_add_u64 v[2:3], v[2:3], 0, s[0:1]
	s_waitcnt lgkmcnt(0)
	v_add_f32_e32 v0, v0, v1
	global_store_dword v[2:3], v0, off

.LBB0_1736:
	v_lshl_add_u32 v148, s12, 8, v150
	v_ashrrev_i32_e32 v149, 31, v148
	v_lshl_or_b32 v146, s8, 8, v152
	v_lshlrev_b64 v[158:159], 11, v[148:149]
	v_ashrrev_i32_e32 v147, 31, v146
	v_lshl_add_u64 v[158:159], s[14:15], 0, v[158:159]
	v_lshl_add_u64 v[162:163], v[146:147], 1, v[158:159]
	v_mov_b32_e32 v232, v162
	v_mov_b32_e32 v233, v163
	global_load_dwordx4 v[188:191], v[232:233], off
	global_load_dwordx4 v[192:195], v[232:233], off offset:256
	s_mov_b64 s[100:101], 0x8000
	v_lshl_add_u64 v[230:231], v[232:233], 0, s[100:101]
	global_load_dwordx4 v[196:199], v[230:231], off
	global_load_dwordx4 v[200:203], v[230:231], off offset:256
	s_mov_b64 s[100:101], 0x10000
	v_lshl_add_u64 v[230:231], v[232:233], 0, s[100:101]
	global_load_dwordx4 v[204:207], v[230:231], off
	global_load_dwordx4 v[208:211], v[230:231], off offset:256
	s_mov_b64 s[100:101], 0x18000
	v_lshl_add_u64 v[230:231], v[232:233], 0, s[100:101]
	global_load_dwordx4 v[212:215], v[230:231], off
	global_load_dwordx4 v[216:219], v[230:231], off offset:256
	v_and_b32_e32 v169, 64, v157
	v_add_u32_e32 v169, 64, v169
	v_xor_b32_e32 v170, 32, v157
	s_lshl_b32 s30, s8, 2
	s_ashr_i32 s31, s30, 31
	s_waitcnt vmcnt(7)
	v_lshlrev_b32_e32 v164, 16, v188
	v_and_b32_e32 v158, 0xffff0000, v188
	v_lshlrev_b32_e32 v165, 16, v189
	v_and_b32_e32 v159, 0xffff0000, v189
	v_lshlrev_b32_e32 v166, 16, v190
	v_and_b32_e32 v160, 0xffff0000, v190
	v_lshlrev_b32_e32 v167, 16, v191
	v_and_b32_e32 v161, 0xffff0000, v191
	v_add_f32_e32 v164, v124, v164
	v_add_f32_e32 v168, v125, v158
	v_add_f32_e32 v126, v126, v165
	v_add_f32_e32 v127, v127, v159
	v_add_f32_e32 v165, v120, v166
	v_add_f32_e32 v121, v121, v160
	v_add_f32_e32 v166, v122, v167
	v_add_f32_e32 v167, v123, v161
	v_cvt_pk_bf16_f32 v122, v164, v168
	v_cvt_pk_bf16_f32 v123, v126, v127
	v_cvt_pk_bf16_f32 v124, v165, v121
	v_cvt_pk_bf16_f32 v125, v166, v167
	v_mul_f32_e32 v168, v168, v168
	v_mul_f32_e32 v127, v127, v127
	v_mul_f32_e32 v121, v121, v121
	v_mul_f32_e32 v167, v167, v167
	v_fmac_f32_e32 v168, v164, v164
	v_fmac_f32_e32 v127, v126, v126
	v_fmac_f32_e32 v121, v165, v165
	v_fmac_f32_e32 v167, v166, v166
	v_add_f32_e32 v126, v168, v127
	v_add_f32_e32 v121, v121, v167
	v_add_f32_e32 v121, v126, v121
	v_xor_b32_e32 v120, 16, v157
	v_cmp_lt_i32_e32 vcc, v120, v169
	global_store_dwordx4 v[162:163], v[122:125], off
	s_waitcnt vmcnt(7)
	v_lshlrev_b32_e32 v126, 16, v192
	v_and_b32_e32 v127, 0xffff0000, v192
	v_lshlrev_b32_e32 v158, 16, v193
	v_and_b32_e32 v159, 0xffff0000, v193
	v_lshlrev_b32_e32 v164, 16, v194
	v_and_b32_e32 v160, 0xffff0000, v194
	v_lshlrev_b32_e32 v165, 16, v195
	v_and_b32_e32 v161, 0xffff0000, v195
	v_add_f32_e32 v117, v117, v127
	v_add_f32_e32 v119, v119, v159
	v_add_f32_e32 v127, v113, v160
	v_add_f32_e32 v115, v115, v161
	v_add_f32_e32 v116, v116, v126
	v_add_f32_e32 v118, v118, v158
	v_add_f32_e32 v126, v112, v164
	v_add_f32_e32 v158, v114, v165
	v_mul_f32_e32 v112, v117, v117
	v_mul_f32_e32 v113, v119, v119
	v_mul_f32_e32 v114, v127, v127
	v_mul_f32_e32 v159, v115, v115
	v_fmac_f32_e32 v112, v116, v116
	v_fmac_f32_e32 v113, v118, v118
	v_fmac_f32_e32 v114, v126, v126
	v_fmac_f32_e32 v159, v158, v158
	v_add_f32_e32 v112, v112, v113
	v_add_f32_e32 v113, v114, v159
	v_cndmask_b32_e32 v120, v157, v120, vcc
	v_add_f32_e32 v112, v112, v113
	v_lshlrev_b32_e32 v120, 2, v120
	v_add_f32_e32 v112, v121, v112
	v_mov_b32_e32 v113, v112
	s_nop 1
	v_permlane16_swap_b32_e32 v113, v112
	v_cmp_lt_i32_e32 vcc, v170, v169
	v_cvt_pk_bf16_f32 v116, v116, v117
	v_cvt_pk_bf16_f32 v117, v118, v119
	v_cvt_pk_bf16_f32 v118, v126, v127
	s_waitcnt lgkmcnt(0)
	v_add_f32_e32 v112, v112, v113
	v_cvt_pk_bf16_f32 v119, v158, v115
	v_cndmask_b32_e32 v114, v157, v170, vcc
	v_lshlrev_b32_e32 v114, 2, v114
	v_mov_b32_e32 v113, v112
	s_nop 1
	v_permlane32_swap_b32_e32 v113, v112
	global_store_dwordx4 v[162:163], v[116:119], off offset:256
	s_and_saveexec_b64 s[36:37], s[4:5]
	s_cbranch_execz .LBB0_1738
	v_lshlrev_b64 v[116:117], 6, v[148:149]
	v_lshl_add_u64 v[116:117], s[18:19], 0, v[116:117]
	v_lshl_add_u64 v[116:117], s[30:31], 2, v[116:117]
	s_lshl_b32 s8, s46, 2
	v_lshl_add_u64 v[116:117], v[116:117], 0, s[8:9]
	s_waitcnt lgkmcnt(0)
	v_add_f32_e32 v112, v112, v113
	global_store_dword v[116:117], v112, off
.LBB0_1738:
	s_or_b64 exec, exec, s[36:37]
	v_or_b32_e32 v112, 16, v148
	s_waitcnt lgkmcnt(0)
	v_ashrrev_i32_e32 v113, 31, v112
	v_lshlrev_b64 v[116:117], 11, v[112:113]
	v_lshl_add_u64 v[116:117], s[14:15], 0, v[116:117]
	v_lshl_add_u64 v[122:123], v[146:147], 1, v[116:117]
	s_mov_b64 s[100:101], 0x40000
	v_lshl_add_u64 v[230:231], v[232:233], 0, s[100:101]
	global_load_dwordx4 v[188:191], v[230:231], off
	global_load_dwordx4 v[192:195], v[230:231], off offset:256
	s_waitcnt vmcnt(9)
	v_lshlrev_b32_e32 v115, 16, v196
	v_and_b32_e32 v116, 0xffff0000, v196
	v_lshlrev_b32_e32 v121, 16, v197
	v_and_b32_e32 v117, 0xffff0000, v197
	v_lshlrev_b32_e32 v124, 16, v198
	v_and_b32_e32 v118, 0xffff0000, v198
	v_lshlrev_b32_e32 v125, 16, v199
	v_and_b32_e32 v119, 0xffff0000, v199
	v_add_f32_e32 v115, v108, v115
	v_add_f32_e32 v116, v109, v116
	v_add_f32_e32 v121, v110, v121
	v_add_f32_e32 v117, v111, v117
	v_add_f32_e32 v124, v104, v124
	v_add_f32_e32 v118, v105, v118
	v_add_f32_e32 v125, v106, v125
	v_add_f32_e32 v119, v107, v119
	v_cvt_pk_bf16_f32 v104, v115, v116
	v_cvt_pk_bf16_f32 v105, v121, v117
	v_cvt_pk_bf16_f32 v106, v124, v118
	v_cvt_pk_bf16_f32 v107, v125, v119
	v_mul_f32_e32 v116, v116, v116
	v_mul_f32_e32 v117, v117, v117
	v_mul_f32_e32 v118, v118, v118
	v_mul_f32_e32 v119, v119, v119
	v_fmac_f32_e32 v116, v115, v115
	v_fmac_f32_e32 v117, v121, v121
	v_fmac_f32_e32 v118, v124, v124
	v_fmac_f32_e32 v119, v125, v125
	v_add_f32_e32 v115, v116, v117
	v_add_f32_e32 v116, v118, v119
	v_add_f32_e32 v115, v115, v116
	global_store_dwordx4 v[122:123], v[104:107], off
	s_waitcnt vmcnt(9)
	v_lshlrev_b32_e32 v116, 16, v200
	v_and_b32_e32 v108, 0xffff0000, v200
	v_lshlrev_b32_e32 v117, 16, v201
	v_and_b32_e32 v109, 0xffff0000, v201
	v_lshlrev_b32_e32 v118, 16, v202
	v_and_b32_e32 v110, 0xffff0000, v202
	v_lshlrev_b32_e32 v119, 16, v203
	v_and_b32_e32 v111, 0xffff0000, v203
	v_add_f32_e32 v101, v101, v108
	v_add_f32_e32 v103, v103, v109
	v_add_f32_e32 v109, v97, v110
	v_add_f32_e32 v111, v99, v111
	v_add_f32_e32 v100, v100, v116
	v_add_f32_e32 v102, v102, v117
	v_add_f32_e32 v108, v96, v118
	v_add_f32_e32 v110, v98, v119
	v_mul_f32_e32 v96, v101, v101
	v_mul_f32_e32 v97, v103, v103
	v_mul_f32_e32 v98, v109, v109
	v_mul_f32_e32 v99, v111, v111
	v_fmac_f32_e32 v96, v100, v100
	v_fmac_f32_e32 v97, v102, v102
	v_fmac_f32_e32 v98, v108, v108
	v_fmac_f32_e32 v99, v110, v110
	v_add_f32_e32 v96, v96, v97
	v_add_f32_e32 v97, v98, v99
	v_add_f32_e32 v96, v96, v97
	v_add_f32_e32 v96, v115, v96
	v_mov_b32_e32 v97, v96
	s_nop 1
	v_permlane16_swap_b32_e32 v97, v96
	v_cvt_pk_bf16_f32 v98, v100, v101
	v_cvt_pk_bf16_f32 v99, v102, v103
	v_cvt_pk_bf16_f32 v100, v108, v109
	v_cvt_pk_bf16_f32 v101, v110, v111
	s_waitcnt lgkmcnt(0)
	v_add_f32_e32 v96, v96, v97
	v_mov_b32_e32 v97, v96
	s_nop 1
	v_permlane32_swap_b32_e32 v97, v96
	global_store_dwordx4 v[122:123], v[98:101], off offset:256
	s_and_saveexec_b64 s[36:37], s[4:5]
	s_cbranch_execz .LBB0_1740
	v_lshlrev_b64 v[98:99], 6, v[112:113]
	v_lshl_add_u64 v[98:99], s[18:19], 0, v[98:99]
	v_lshl_add_u64 v[98:99], s[30:31], 2, v[98:99]
	s_lshl_b32 s8, s46, 2
	v_lshl_add_u64 v[98:99], v[98:99], 0, s[8:9]
	s_waitcnt lgkmcnt(0)
	v_add_f32_e32 v96, v96, v97
	global_store_dword v[98:99], v96, off
.LBB0_1740:
	s_or_b64 exec, exec, s[36:37]
	v_or_b32_e32 v96, 32, v148
	s_waitcnt lgkmcnt(0)
	v_ashrrev_i32_e32 v97, 31, v96
	v_lshlrev_b64 v[98:99], 11, v[96:97]
	v_lshl_add_u64 v[98:99], s[14:15], 0, v[98:99]
	v_lshl_add_u64 v[102:103], v[146:147], 1, v[98:99]
	s_mov_b64 s[100:101], 0x48000
	v_lshl_add_u64 v[230:231], v[232:233], 0, s[100:101]
	global_load_dwordx4 v[196:199], v[230:231], off
	global_load_dwordx4 v[200:203], v[230:231], off offset:256
	s_waitcnt vmcnt(11)
	v_lshlrev_b32_e32 v104, 16, v204
	v_and_b32_e32 v98, 0xffff0000, v204
	v_lshlrev_b32_e32 v105, 16, v205
	v_and_b32_e32 v99, 0xffff0000, v205
	v_lshlrev_b32_e32 v106, 16, v206
	v_and_b32_e32 v100, 0xffff0000, v206
	v_lshlrev_b32_e32 v107, 16, v207
	v_and_b32_e32 v101, 0xffff0000, v207
	v_add_f32_e32 v104, v92, v104
	v_add_f32_e32 v98, v93, v98
	v_add_f32_e32 v105, v94, v105
	v_add_f32_e32 v99, v95, v99
	v_add_f32_e32 v106, v88, v106
	v_add_f32_e32 v100, v89, v100
	v_add_f32_e32 v107, v90, v107
	v_add_f32_e32 v101, v91, v101
	v_cvt_pk_bf16_f32 v88, v104, v98
	v_cvt_pk_bf16_f32 v89, v105, v99
	v_cvt_pk_bf16_f32 v90, v106, v100
	v_cvt_pk_bf16_f32 v91, v107, v101
	v_mul_f32_e32 v98, v98, v98
	v_mul_f32_e32 v99, v99, v99
	v_mul_f32_e32 v100, v100, v100
	v_mul_f32_e32 v101, v101, v101
	v_fmac_f32_e32 v98, v104, v104
	v_fmac_f32_e32 v99, v105, v105
	v_fmac_f32_e32 v100, v106, v106
	v_fmac_f32_e32 v101, v107, v107
	v_add_f32_e32 v98, v98, v99
	v_add_f32_e32 v99, v100, v101
	v_add_f32_e32 v98, v98, v99
	global_store_dwordx4 v[102:103], v[88:91], off
	s_waitcnt vmcnt(11)
	v_lshlrev_b32_e32 v99, 16, v208
	v_and_b32_e32 v92, 0xffff0000, v208
	v_lshlrev_b32_e32 v100, 16, v209
	v_and_b32_e32 v93, 0xffff0000, v209
	v_lshlrev_b32_e32 v101, 16, v210
	v_and_b32_e32 v94, 0xffff0000, v210
	v_lshlrev_b32_e32 v104, 16, v211
	v_and_b32_e32 v95, 0xffff0000, v211
	v_add_f32_e32 v85, v85, v92
	v_add_f32_e32 v87, v87, v93
	v_add_f32_e32 v93, v81, v94
	v_add_f32_e32 v95, v83, v95
	v_add_f32_e32 v84, v84, v99
	v_add_f32_e32 v86, v86, v100
	v_add_f32_e32 v92, v80, v101
	v_add_f32_e32 v94, v82, v104
	v_mul_f32_e32 v80, v85, v85
	v_mul_f32_e32 v81, v87, v87
	v_mul_f32_e32 v82, v93, v93
	v_mul_f32_e32 v83, v95, v95
	v_fmac_f32_e32 v80, v84, v84
	v_fmac_f32_e32 v81, v86, v86
	v_fmac_f32_e32 v82, v92, v92
	v_fmac_f32_e32 v83, v94, v94
	v_add_f32_e32 v80, v80, v81
	v_add_f32_e32 v81, v82, v83
	v_add_f32_e32 v80, v80, v81
	v_add_f32_e32 v80, v98, v80
	v_mov_b32_e32 v81, v80
	s_nop 1
	v_permlane16_swap_b32_e32 v81, v80
	v_cvt_pk_bf16_f32 v82, v84, v85
	v_cvt_pk_bf16_f32 v83, v86, v87
	v_cvt_pk_bf16_f32 v84, v92, v93
	v_cvt_pk_bf16_f32 v85, v94, v95
	s_waitcnt lgkmcnt(0)
	v_add_f32_e32 v80, v80, v81
	v_mov_b32_e32 v81, v80
	s_nop 1
	v_permlane32_swap_b32_e32 v81, v80
	global_store_dwordx4 v[102:103], v[82:85], off offset:256
	s_and_saveexec_b64 s[36:37], s[4:5]
	s_cbranch_execz .LBB0_1742
	v_lshlrev_b64 v[82:83], 6, v[96:97]
	v_lshl_add_u64 v[82:83], s[18:19], 0, v[82:83]
	v_lshl_add_u64 v[82:83], s[30:31], 2, v[82:83]
	s_lshl_b32 s8, s46, 2
	v_lshl_add_u64 v[82:83], v[82:83], 0, s[8:9]
	s_waitcnt lgkmcnt(0)
	v_add_f32_e32 v80, v80, v81
	global_store_dword v[82:83], v80, off
.LBB0_1742:
	s_or_b64 exec, exec, s[36:37]
	v_or_b32_e32 v80, 48, v148
	s_waitcnt lgkmcnt(0)
	v_ashrrev_i32_e32 v81, 31, v80
	v_lshlrev_b64 v[82:83], 11, v[80:81]
	v_lshl_add_u64 v[82:83], s[14:15], 0, v[82:83]
	v_lshl_add_u64 v[86:87], v[146:147], 1, v[82:83]
	s_mov_b64 s[100:101], 0x50000
	v_lshl_add_u64 v[230:231], v[232:233], 0, s[100:101]
	global_load_dwordx4 v[204:207], v[230:231], off
	global_load_dwordx4 v[208:211], v[230:231], off offset:256
	s_waitcnt vmcnt(13)
	v_lshlrev_b32_e32 v88, 16, v212
	v_and_b32_e32 v82, 0xffff0000, v212
	v_lshlrev_b32_e32 v89, 16, v213
	v_and_b32_e32 v83, 0xffff0000, v213
	v_lshlrev_b32_e32 v90, 16, v214
	v_and_b32_e32 v84, 0xffff0000, v214
	v_lshlrev_b32_e32 v91, 16, v215
	v_and_b32_e32 v85, 0xffff0000, v215
	v_add_f32_e32 v88, v76, v88
	v_add_f32_e32 v82, v77, v82
	v_add_f32_e32 v89, v78, v89
	v_add_f32_e32 v83, v79, v83
	v_add_f32_e32 v90, v72, v90
	v_add_f32_e32 v84, v73, v84
	v_add_f32_e32 v91, v74, v91
	v_add_f32_e32 v85, v75, v85
	v_cvt_pk_bf16_f32 v72, v88, v82
	v_cvt_pk_bf16_f32 v73, v89, v83
	v_cvt_pk_bf16_f32 v74, v90, v84
	v_cvt_pk_bf16_f32 v75, v91, v85
	v_mul_f32_e32 v82, v82, v82
	v_mul_f32_e32 v83, v83, v83
	v_mul_f32_e32 v84, v84, v84
	v_mul_f32_e32 v85, v85, v85
	v_fmac_f32_e32 v82, v88, v88
	v_fmac_f32_e32 v83, v89, v89
	v_fmac_f32_e32 v84, v90, v90
	v_fmac_f32_e32 v85, v91, v91
	v_add_f32_e32 v82, v82, v83
	v_add_f32_e32 v83, v84, v85
	v_add_f32_e32 v82, v82, v83
	global_store_dwordx4 v[86:87], v[72:75], off
	s_waitcnt vmcnt(13)
	v_lshlrev_b32_e32 v83, 16, v216
	v_and_b32_e32 v76, 0xffff0000, v216
	v_lshlrev_b32_e32 v84, 16, v217
	v_and_b32_e32 v77, 0xffff0000, v217
	v_lshlrev_b32_e32 v85, 16, v218
	v_and_b32_e32 v78, 0xffff0000, v218
	v_lshlrev_b32_e32 v88, 16, v219
	v_and_b32_e32 v79, 0xffff0000, v219
	v_add_f32_e32 v69, v69, v76
	v_add_f32_e32 v71, v71, v77
	v_add_f32_e32 v77, v65, v78
	v_add_f32_e32 v79, v67, v79
	v_add_f32_e32 v68, v68, v83
	v_add_f32_e32 v70, v70, v84
	v_add_f32_e32 v76, v64, v85
	v_add_f32_e32 v78, v66, v88
	v_mul_f32_e32 v64, v69, v69
	v_mul_f32_e32 v65, v71, v71
	v_mul_f32_e32 v66, v77, v77
	v_mul_f32_e32 v67, v79, v79
	v_fmac_f32_e32 v64, v68, v68
	v_fmac_f32_e32 v65, v70, v70
	v_fmac_f32_e32 v66, v76, v76
	v_fmac_f32_e32 v67, v78, v78
	v_add_f32_e32 v64, v64, v65
	v_add_f32_e32 v65, v66, v67
	v_add_f32_e32 v64, v64, v65
	v_add_f32_e32 v64, v82, v64
	v_mov_b32_e32 v65, v64
	s_nop 1
	v_permlane16_swap_b32_e32 v65, v64
	v_cvt_pk_bf16_f32 v66, v68, v69
	v_cvt_pk_bf16_f32 v67, v70, v71
	v_cvt_pk_bf16_f32 v68, v76, v77
	v_cvt_pk_bf16_f32 v69, v78, v79
	s_waitcnt lgkmcnt(0)
	v_add_f32_e32 v64, v64, v65
	v_mov_b32_e32 v65, v64
	s_nop 1
	v_permlane32_swap_b32_e32 v65, v64
	global_store_dwordx4 v[86:87], v[66:69], off offset:256
	s_and_saveexec_b64 s[36:37], s[4:5]
	s_cbranch_execz .LBB0_1744
	v_lshlrev_b64 v[66:67], 6, v[80:81]
	v_lshl_add_u64 v[66:67], s[18:19], 0, v[66:67]
	v_lshl_add_u64 v[66:67], s[30:31], 2, v[66:67]
	s_lshl_b32 s8, s46, 2
	v_lshl_add_u64 v[66:67], v[66:67], 0, s[8:9]
	s_waitcnt lgkmcnt(0)
	v_add_f32_e32 v64, v64, v65
	global_store_dword v[66:67], v64, off
.LBB0_1744:
	s_or_b64 exec, exec, s[36:37]
	v_add_u32_e32 v64, 0x80, v148
	s_waitcnt lgkmcnt(0)
	v_ashrrev_i32_e32 v65, 31, v64
	v_lshlrev_b64 v[66:67], 11, v[64:65]
	v_lshl_add_u64 v[66:67], s[14:15], 0, v[66:67]
	v_lshl_add_u64 v[70:71], v[146:147], 1, v[66:67]
	s_mov_b64 s[100:101], 0x58000
	v_lshl_add_u64 v[230:231], v[232:233], 0, s[100:101]
	global_load_dwordx4 v[212:215], v[230:231], off
	global_load_dwordx4 v[216:219], v[230:231], off offset:256
	s_waitcnt vmcnt(13)
	v_lshlrev_b32_e32 v72, 16, v188
	v_and_b32_e32 v66, 0xffff0000, v188
	v_lshlrev_b32_e32 v73, 16, v189
	v_and_b32_e32 v67, 0xffff0000, v189
	v_lshlrev_b32_e32 v74, 16, v190
	v_and_b32_e32 v68, 0xffff0000, v190
	v_lshlrev_b32_e32 v75, 16, v191
	v_and_b32_e32 v69, 0xffff0000, v191
	v_add_f32_e32 v72, v60, v72
	v_add_f32_e32 v66, v61, v66
	v_add_f32_e32 v73, v62, v73
	v_add_f32_e32 v67, v63, v67
	v_add_f32_e32 v74, v56, v74
	v_add_f32_e32 v68, v57, v68
	v_add_f32_e32 v75, v58, v75
	v_add_f32_e32 v69, v59, v69
	v_cvt_pk_bf16_f32 v56, v72, v66
	v_cvt_pk_bf16_f32 v57, v73, v67
	v_cvt_pk_bf16_f32 v58, v74, v68
	v_cvt_pk_bf16_f32 v59, v75, v69
	v_mul_f32_e32 v66, v66, v66
	v_mul_f32_e32 v67, v67, v67
	v_mul_f32_e32 v68, v68, v68
	v_mul_f32_e32 v69, v69, v69
	v_fmac_f32_e32 v66, v72, v72
	v_fmac_f32_e32 v67, v73, v73
	v_fmac_f32_e32 v68, v74, v74
	v_fmac_f32_e32 v69, v75, v75
	v_add_f32_e32 v66, v66, v67
	v_add_f32_e32 v67, v68, v69
	v_add_f32_e32 v66, v66, v67
	global_store_dwordx4 v[70:71], v[56:59], off
	s_waitcnt vmcnt(13)
	v_lshlrev_b32_e32 v67, 16, v192
	v_and_b32_e32 v60, 0xffff0000, v192
	v_lshlrev_b32_e32 v68, 16, v193
	v_and_b32_e32 v61, 0xffff0000, v193
	v_lshlrev_b32_e32 v69, 16, v194
	v_and_b32_e32 v62, 0xffff0000, v194
	v_lshlrev_b32_e32 v72, 16, v195
	v_and_b32_e32 v63, 0xffff0000, v195
	v_add_f32_e32 v53, v53, v60
	v_add_f32_e32 v55, v55, v61
	v_add_f32_e32 v61, v49, v62
	v_add_f32_e32 v63, v51, v63
	v_add_f32_e32 v52, v52, v67
	v_add_f32_e32 v54, v54, v68
	v_add_f32_e32 v60, v48, v69
	v_add_f32_e32 v62, v50, v72
	v_mul_f32_e32 v48, v53, v53
	v_mul_f32_e32 v49, v55, v55
	v_mul_f32_e32 v50, v61, v61
	v_mul_f32_e32 v51, v63, v63
	v_fmac_f32_e32 v48, v52, v52
	v_fmac_f32_e32 v49, v54, v54
	v_fmac_f32_e32 v50, v60, v60
	v_fmac_f32_e32 v51, v62, v62
	v_add_f32_e32 v48, v48, v49
	v_add_f32_e32 v49, v50, v51
	v_add_f32_e32 v48, v48, v49
	v_add_f32_e32 v48, v66, v48
	v_mov_b32_e32 v49, v48
	s_nop 1
	v_permlane16_swap_b32_e32 v49, v48
	v_cvt_pk_bf16_f32 v50, v52, v53
	v_cvt_pk_bf16_f32 v51, v54, v55
	v_cvt_pk_bf16_f32 v52, v60, v61
	v_cvt_pk_bf16_f32 v53, v62, v63
	s_waitcnt lgkmcnt(0)
	v_add_f32_e32 v48, v48, v49
	v_mov_b32_e32 v49, v48
	s_nop 1
	v_permlane32_swap_b32_e32 v49, v48
	global_store_dwordx4 v[70:71], v[50:53], off offset:256
	s_and_saveexec_b64 s[36:37], s[4:5]
	s_cbranch_execz .LBB0_1746
	v_lshlrev_b64 v[50:51], 6, v[64:65]
	v_lshl_add_u64 v[50:51], s[18:19], 0, v[50:51]
	v_lshl_add_u64 v[50:51], s[30:31], 2, v[50:51]
	s_lshl_b32 s8, s46, 2
	v_lshl_add_u64 v[50:51], v[50:51], 0, s[8:9]
	s_waitcnt lgkmcnt(0)
	v_add_f32_e32 v48, v48, v49
	global_store_dword v[50:51], v48, off
.LBB0_1746:
	s_or_b64 exec, exec, s[36:37]
	v_add_u32_e32 v48, 0x90, v148
	s_waitcnt lgkmcnt(0)
	v_ashrrev_i32_e32 v49, 31, v48
	v_lshlrev_b64 v[50:51], 11, v[48:49]
	v_lshl_add_u64 v[50:51], s[14:15], 0, v[50:51]
	v_lshl_add_u64 v[54:55], v[146:147], 1, v[50:51]
	s_waitcnt vmcnt(11)
	v_lshlrev_b32_e32 v56, 16, v196
	v_and_b32_e32 v50, 0xffff0000, v196
	v_lshlrev_b32_e32 v57, 16, v197
	v_and_b32_e32 v51, 0xffff0000, v197
	v_lshlrev_b32_e32 v58, 16, v198
	v_and_b32_e32 v52, 0xffff0000, v198
	v_lshlrev_b32_e32 v59, 16, v199
	v_and_b32_e32 v53, 0xffff0000, v199
	v_add_f32_e32 v56, v44, v56
	v_add_f32_e32 v50, v45, v50
	v_add_f32_e32 v57, v46, v57
	v_add_f32_e32 v51, v47, v51
	v_add_f32_e32 v58, v40, v58
	v_add_f32_e32 v52, v41, v52
	v_add_f32_e32 v59, v42, v59
	v_add_f32_e32 v53, v43, v53
	v_cvt_pk_bf16_f32 v40, v56, v50
	v_cvt_pk_bf16_f32 v41, v57, v51
	v_cvt_pk_bf16_f32 v42, v58, v52
	v_cvt_pk_bf16_f32 v43, v59, v53
	v_mul_f32_e32 v50, v50, v50
	v_mul_f32_e32 v51, v51, v51
	v_mul_f32_e32 v52, v52, v52
	v_mul_f32_e32 v53, v53, v53
	v_fmac_f32_e32 v50, v56, v56
	v_fmac_f32_e32 v51, v57, v57
	v_fmac_f32_e32 v52, v58, v58
	v_fmac_f32_e32 v53, v59, v59
	v_add_f32_e32 v50, v50, v51
	v_add_f32_e32 v51, v52, v53
	v_add_f32_e32 v50, v50, v51
	global_store_dwordx4 v[54:55], v[40:43], off
	s_waitcnt vmcnt(11)
	v_lshlrev_b32_e32 v51, 16, v200
	v_and_b32_e32 v44, 0xffff0000, v200
	v_lshlrev_b32_e32 v52, 16, v201
	v_and_b32_e32 v45, 0xffff0000, v201
	v_lshlrev_b32_e32 v53, 16, v202
	v_and_b32_e32 v46, 0xffff0000, v202
	v_lshlrev_b32_e32 v56, 16, v203
	v_and_b32_e32 v47, 0xffff0000, v203
	v_add_f32_e32 v37, v37, v44
	v_add_f32_e32 v39, v39, v45
	v_add_f32_e32 v45, v33, v46
	v_add_f32_e32 v47, v35, v47
	v_add_f32_e32 v36, v36, v51
	v_add_f32_e32 v38, v38, v52
	v_add_f32_e32 v44, v32, v53
	v_add_f32_e32 v46, v34, v56
	v_mul_f32_e32 v32, v37, v37
	v_mul_f32_e32 v33, v39, v39
	v_mul_f32_e32 v34, v45, v45
	v_mul_f32_e32 v35, v47, v47
	v_fmac_f32_e32 v32, v36, v36
	v_fmac_f32_e32 v33, v38, v38
	v_fmac_f32_e32 v34, v44, v44
	v_fmac_f32_e32 v35, v46, v46
	v_add_f32_e32 v32, v32, v33
	v_add_f32_e32 v33, v34, v35
	v_add_f32_e32 v32, v32, v33
	v_add_f32_e32 v32, v50, v32
	v_mov_b32_e32 v33, v32
	s_nop 1
	v_permlane16_swap_b32_e32 v33, v32
	v_cvt_pk_bf16_f32 v34, v36, v37
	v_cvt_pk_bf16_f32 v35, v38, v39
	v_cvt_pk_bf16_f32 v36, v44, v45
	v_cvt_pk_bf16_f32 v37, v46, v47
	s_waitcnt lgkmcnt(0)
	v_add_f32_e32 v32, v32, v33
	v_mov_b32_e32 v33, v32
	s_nop 1
	v_permlane32_swap_b32_e32 v33, v32
	global_store_dwordx4 v[54:55], v[34:37], off offset:256
	s_and_saveexec_b64 s[36:37], s[4:5]
	s_cbranch_execz .LBB0_1748
	v_lshlrev_b64 v[34:35], 6, v[48:49]
	v_lshl_add_u64 v[34:35], s[18:19], 0, v[34:35]
	v_lshl_add_u64 v[34:35], s[30:31], 2, v[34:35]
	s_lshl_b32 s8, s46, 2
	v_lshl_add_u64 v[34:35], v[34:35], 0, s[8:9]
	s_waitcnt lgkmcnt(0)
	v_add_f32_e32 v32, v32, v33
	global_store_dword v[34:35], v32, off
.LBB0_1748:
	s_or_b64 exec, exec, s[36:37]
	v_add_u32_e32 v32, 0xa0, v148
	s_waitcnt lgkmcnt(0)
	v_ashrrev_i32_e32 v33, 31, v32
	v_lshlrev_b64 v[34:35], 11, v[32:33]
	v_lshl_add_u64 v[34:35], s[14:15], 0, v[34:35]
	v_lshl_add_u64 v[38:39], v[146:147], 1, v[34:35]
	s_waitcnt vmcnt(9)
	v_lshlrev_b32_e32 v40, 16, v204
	v_and_b32_e32 v34, 0xffff0000, v204
	v_lshlrev_b32_e32 v41, 16, v205
	v_and_b32_e32 v35, 0xffff0000, v205
	v_lshlrev_b32_e32 v42, 16, v206
	v_and_b32_e32 v36, 0xffff0000, v206
	v_lshlrev_b32_e32 v43, 16, v207
	v_and_b32_e32 v37, 0xffff0000, v207
	v_add_f32_e32 v40, v28, v40
	v_add_f32_e32 v34, v29, v34
	v_add_f32_e32 v41, v30, v41
	v_add_f32_e32 v35, v31, v35
	v_add_f32_e32 v42, v24, v42
	v_add_f32_e32 v36, v25, v36
	v_add_f32_e32 v43, v26, v43
	v_add_f32_e32 v37, v27, v37
	v_cvt_pk_bf16_f32 v24, v40, v34
	v_cvt_pk_bf16_f32 v25, v41, v35
	v_cvt_pk_bf16_f32 v26, v42, v36
	v_cvt_pk_bf16_f32 v27, v43, v37
	v_mul_f32_e32 v34, v34, v34
	v_mul_f32_e32 v35, v35, v35
	v_mul_f32_e32 v36, v36, v36
	v_mul_f32_e32 v37, v37, v37
	v_fmac_f32_e32 v34, v40, v40
	v_fmac_f32_e32 v35, v41, v41
	v_fmac_f32_e32 v36, v42, v42
	v_fmac_f32_e32 v37, v43, v43
	v_add_f32_e32 v34, v34, v35
	v_add_f32_e32 v35, v36, v37
	v_add_f32_e32 v34, v34, v35
	global_store_dwordx4 v[38:39], v[24:27], off
	s_waitcnt vmcnt(9)
	v_lshlrev_b32_e32 v35, 16, v208
	v_and_b32_e32 v28, 0xffff0000, v208
	v_lshlrev_b32_e32 v36, 16, v209
	v_and_b32_e32 v29, 0xffff0000, v209
	v_lshlrev_b32_e32 v37, 16, v210
	v_and_b32_e32 v30, 0xffff0000, v210
	v_lshlrev_b32_e32 v40, 16, v211
	v_and_b32_e32 v31, 0xffff0000, v211
	v_add_f32_e32 v21, v21, v28
	v_add_f32_e32 v23, v23, v29
	v_add_f32_e32 v29, v17, v30
	v_add_f32_e32 v31, v19, v31
	v_add_f32_e32 v20, v20, v35
	v_add_f32_e32 v22, v22, v36
	v_add_f32_e32 v28, v16, v37
	v_add_f32_e32 v30, v18, v40
	v_mul_f32_e32 v16, v21, v21
	v_mul_f32_e32 v17, v23, v23
	v_mul_f32_e32 v18, v29, v29
	v_mul_f32_e32 v19, v31, v31
	v_fmac_f32_e32 v16, v20, v20
	v_fmac_f32_e32 v17, v22, v22
	v_fmac_f32_e32 v18, v28, v28
	v_fmac_f32_e32 v19, v30, v30
	v_add_f32_e32 v16, v16, v17
	v_add_f32_e32 v17, v18, v19
	v_add_f32_e32 v16, v16, v17
	v_add_f32_e32 v16, v34, v16
	v_mov_b32_e32 v17, v16
	s_nop 1
	v_permlane16_swap_b32_e32 v17, v16
	v_cvt_pk_bf16_f32 v18, v20, v21
	v_cvt_pk_bf16_f32 v19, v22, v23
	v_cvt_pk_bf16_f32 v20, v28, v29
	v_cvt_pk_bf16_f32 v21, v30, v31
	s_waitcnt lgkmcnt(0)
	v_add_f32_e32 v16, v16, v17
	v_mov_b32_e32 v17, v16
	s_nop 1
	v_permlane32_swap_b32_e32 v17, v16
	global_store_dwordx4 v[38:39], v[18:21], off offset:256
	s_and_saveexec_b64 s[36:37], s[4:5]
	s_cbranch_execz .LBB0_1750
	v_lshlrev_b64 v[18:19], 6, v[32:33]
	v_lshl_add_u64 v[18:19], s[18:19], 0, v[18:19]
	v_lshl_add_u64 v[18:19], s[30:31], 2, v[18:19]
	s_lshl_b32 s8, s46, 2
	v_lshl_add_u64 v[18:19], v[18:19], 0, s[8:9]
	s_waitcnt lgkmcnt(0)
	v_add_f32_e32 v16, v16, v17
	global_store_dword v[18:19], v16, off
.LBB0_1750:
	s_or_b64 exec, exec, s[36:37]
	v_add_u32_e32 v16, 0xb0, v148
	s_waitcnt lgkmcnt(0)
	v_ashrrev_i32_e32 v17, 31, v16
	v_lshlrev_b64 v[18:19], 11, v[16:17]
	v_lshl_add_u64 v[18:19], s[14:15], 0, v[18:19]
	v_lshl_add_u64 v[22:23], v[146:147], 1, v[18:19]
	s_waitcnt vmcnt(7)
	v_lshlrev_b32_e32 v24, 16, v212
	v_and_b32_e32 v18, 0xffff0000, v212
	v_lshlrev_b32_e32 v25, 16, v213
	v_and_b32_e32 v19, 0xffff0000, v213
	v_lshlrev_b32_e32 v26, 16, v214
	v_and_b32_e32 v20, 0xffff0000, v214
	v_lshlrev_b32_e32 v27, 16, v215
	v_and_b32_e32 v21, 0xffff0000, v215
	v_add_f32_e32 v24, v12, v24
	v_add_f32_e32 v18, v13, v18
	v_add_f32_e32 v25, v14, v25
	v_add_f32_e32 v19, v15, v19
	v_add_f32_e32 v26, v8, v26
	v_add_f32_e32 v20, v9, v20
	v_add_f32_e32 v27, v10, v27
	v_add_f32_e32 v21, v11, v21
	v_cvt_pk_bf16_f32 v8, v24, v18
	v_cvt_pk_bf16_f32 v9, v25, v19
	v_cvt_pk_bf16_f32 v10, v26, v20
	v_cvt_pk_bf16_f32 v11, v27, v21
	v_mul_f32_e32 v18, v18, v18
	v_mul_f32_e32 v19, v19, v19
	v_mul_f32_e32 v20, v20, v20
	v_mul_f32_e32 v21, v21, v21
	v_fmac_f32_e32 v18, v24, v24
	v_fmac_f32_e32 v19, v25, v25
	v_fmac_f32_e32 v20, v26, v26
	v_fmac_f32_e32 v21, v27, v27
	v_add_f32_e32 v18, v18, v19
	v_add_f32_e32 v19, v20, v21
	v_add_f32_e32 v18, v18, v19
	global_store_dwordx4 v[22:23], v[8:11], off
	s_waitcnt vmcnt(7)
	v_lshlrev_b32_e32 v19, 16, v216
	v_and_b32_e32 v12, 0xffff0000, v216
	v_lshlrev_b32_e32 v20, 16, v217
	v_and_b32_e32 v13, 0xffff0000, v217
	v_lshlrev_b32_e32 v21, 16, v218
	v_and_b32_e32 v14, 0xffff0000, v218
	v_lshlrev_b32_e32 v24, 16, v219
	v_and_b32_e32 v15, 0xffff0000, v219
	v_add_f32_e32 v5, v5, v12
	v_add_f32_e32 v7, v7, v13
	v_add_f32_e32 v13, v1, v14
	v_add_f32_e32 v15, v3, v15
	v_add_f32_e32 v4, v4, v19
	v_add_f32_e32 v6, v6, v20
	v_add_f32_e32 v12, v0, v21
	v_add_f32_e32 v14, v2, v24
	v_mul_f32_e32 v0, v5, v5
	v_mul_f32_e32 v1, v7, v7
	v_mul_f32_e32 v2, v13, v13
	v_mul_f32_e32 v3, v15, v15
	v_fmac_f32_e32 v0, v4, v4
	v_fmac_f32_e32 v1, v6, v6
	v_fmac_f32_e32 v2, v12, v12
	v_fmac_f32_e32 v3, v14, v14
	v_add_f32_e32 v0, v0, v1
	v_add_f32_e32 v1, v2, v3
	v_add_f32_e32 v0, v0, v1
	v_add_f32_e32 v0, v18, v0
	v_mov_b32_e32 v1, v0
	s_nop 1
	v_permlane16_swap_b32_e32 v1, v0
	v_cvt_pk_bf16_f32 v2, v4, v5
	v_cvt_pk_bf16_f32 v3, v6, v7
	v_cvt_pk_bf16_f32 v4, v12, v13
	v_cvt_pk_bf16_f32 v5, v14, v15
	s_waitcnt lgkmcnt(0)
	v_add_f32_e32 v0, v0, v1
	v_mov_b32_e32 v1, v0
	s_nop 1
	v_permlane32_swap_b32_e32 v1, v0
	global_store_dwordx4 v[22:23], v[2:5], off offset:256
	s_and_saveexec_b64 s[36:37], s[4:5]
	s_cbranch_execz .LBB0_1752
	v_lshlrev_b64 v[2:3], 6, v[16:17]
	v_lshl_add_u64 v[2:3], s[18:19], 0, v[2:3]
	v_lshl_add_u64 v[2:3], s[30:31], 2, v[2:3]
	s_lshl_b32 s8, s46, 2
	v_lshl_add_u64 v[2:3], v[2:3], 0, s[8:9]
	s_waitcnt lgkmcnt(0)
	v_add_f32_e32 v0, v0, v1
	global_store_dword v[2:3], v0, off

.LBB0_2004:
	v_lshl_add_u32 v148, s36, 8, v150
	v_ashrrev_i32_e32 v149, 31, v148
	v_lshl_or_b32 v146, s0, 8, v152
	v_lshlrev_b64 v[158:159], 11, v[148:149]
	v_ashrrev_i32_e32 v147, 31, v146
	v_lshl_add_u64 v[158:159], s[14:15], 0, v[158:159]
	v_lshl_add_u64 v[162:163], v[146:147], 1, v[158:159]
	v_mov_b32_e32 v232, v162
	v_mov_b32_e32 v233, v163
	global_load_dwordx4 v[188:191], v[232:233], off
	global_load_dwordx4 v[192:195], v[232:233], off offset:256
	s_mov_b64 s[100:101], 0x8000
	v_lshl_add_u64 v[230:231], v[232:233], 0, s[100:101]
	global_load_dwordx4 v[196:199], v[230:231], off
	global_load_dwordx4 v[200:203], v[230:231], off offset:256
	s_mov_b64 s[100:101], 0x10000
	v_lshl_add_u64 v[230:231], v[232:233], 0, s[100:101]
	global_load_dwordx4 v[204:207], v[230:231], off
	global_load_dwordx4 v[208:211], v[230:231], off offset:256
	s_mov_b64 s[100:101], 0x18000
	v_lshl_add_u64 v[230:231], v[232:233], 0, s[100:101]
	global_load_dwordx4 v[212:215], v[230:231], off
	global_load_dwordx4 v[216:219], v[230:231], off offset:256
	v_and_b32_e32 v168, 64, v156
	v_add_u32_e32 v168, 64, v168
	v_xor_b32_e32 v169, 32, v156
	s_lshl_b32 s36, s0, 2
	s_ashr_i32 s37, s36, 31
	s_waitcnt vmcnt(7)
	v_lshlrev_b32_e32 v157, 16, v188
	v_and_b32_e32 v158, 0xffff0000, v188
	v_lshlrev_b32_e32 v164, 16, v189
	v_and_b32_e32 v159, 0xffff0000, v189
	v_lshlrev_b32_e32 v165, 16, v190
	v_and_b32_e32 v160, 0xffff0000, v190
	v_lshlrev_b32_e32 v166, 16, v191
	v_and_b32_e32 v161, 0xffff0000, v191
	v_add_f32_e32 v157, v124, v157
	v_add_f32_e32 v167, v125, v158
	v_add_f32_e32 v126, v126, v164
	v_add_f32_e32 v127, v127, v159
	v_add_f32_e32 v164, v120, v165
	v_add_f32_e32 v121, v121, v160
	v_add_f32_e32 v165, v122, v166
	v_add_f32_e32 v166, v123, v161
	v_cvt_pk_bf16_f32 v122, v157, v167
	v_cvt_pk_bf16_f32 v123, v126, v127
	v_cvt_pk_bf16_f32 v124, v164, v121
	v_cvt_pk_bf16_f32 v125, v165, v166
	v_mul_f32_e32 v167, v167, v167
	v_mul_f32_e32 v127, v127, v127
	v_mul_f32_e32 v121, v121, v121
	v_mul_f32_e32 v166, v166, v166
	v_fmac_f32_e32 v167, v157, v157
	v_fmac_f32_e32 v127, v126, v126
	v_fmac_f32_e32 v121, v164, v164
	v_fmac_f32_e32 v166, v165, v165
	v_add_f32_e32 v126, v167, v127
	v_add_f32_e32 v121, v121, v166
	v_add_f32_e32 v121, v126, v121
	v_xor_b32_e32 v120, 16, v156
	v_cmp_lt_i32_e32 vcc, v120, v168
	global_store_dwordx4 v[162:163], v[122:125], off
	s_waitcnt vmcnt(7)
	v_lshlrev_b32_e32 v126, 16, v192
	v_and_b32_e32 v127, 0xffff0000, v192
	v_lshlrev_b32_e32 v157, 16, v193
	v_and_b32_e32 v158, 0xffff0000, v193
	v_lshlrev_b32_e32 v159, 16, v194
	v_and_b32_e32 v160, 0xffff0000, v194
	v_lshlrev_b32_e32 v164, 16, v195
	v_and_b32_e32 v161, 0xffff0000, v195
	v_add_f32_e32 v117, v117, v127
	v_add_f32_e32 v119, v119, v158
	v_add_f32_e32 v127, v113, v160
	v_add_f32_e32 v115, v115, v161
	v_add_f32_e32 v116, v116, v126
	v_add_f32_e32 v118, v118, v157
	v_add_f32_e32 v126, v112, v159
	v_add_f32_e32 v157, v114, v164
	v_mul_f32_e32 v112, v117, v117
	v_mul_f32_e32 v113, v119, v119
	v_mul_f32_e32 v114, v127, v127
	v_mul_f32_e32 v158, v115, v115
	v_fmac_f32_e32 v112, v116, v116
	v_fmac_f32_e32 v113, v118, v118
	v_fmac_f32_e32 v114, v126, v126
	v_fmac_f32_e32 v158, v157, v157
	v_add_f32_e32 v112, v112, v113
	v_add_f32_e32 v113, v114, v158
	v_cndmask_b32_e32 v120, v156, v120, vcc
	v_add_f32_e32 v112, v112, v113
	v_lshlrev_b32_e32 v120, 2, v120
	v_add_f32_e32 v112, v121, v112
	v_mov_b32_e32 v113, v112
	s_nop 1
	v_permlane16_swap_b32_e32 v113, v112
	v_cmp_lt_i32_e32 vcc, v169, v168
	v_cvt_pk_bf16_f32 v116, v116, v117
	v_cvt_pk_bf16_f32 v117, v118, v119
	v_cvt_pk_bf16_f32 v118, v126, v127
	s_waitcnt lgkmcnt(0)
	v_add_f32_e32 v112, v112, v113
	v_cvt_pk_bf16_f32 v119, v157, v115
	v_cndmask_b32_e32 v114, v156, v169, vcc
	v_lshlrev_b32_e32 v114, 2, v114
	v_mov_b32_e32 v113, v112
	s_nop 1
	v_permlane32_swap_b32_e32 v113, v112
	global_store_dwordx4 v[162:163], v[116:119], off offset:256
	s_and_saveexec_b64 s[38:39], s[4:5]
	s_cbranch_execz .LBB0_2006
	v_lshlrev_b64 v[116:117], 6, v[148:149]
	v_lshl_add_u64 v[116:117], s[18:19], 0, v[116:117]
	v_lshl_add_u64 v[116:117], s[36:37], 2, v[116:117]
	s_lshl_b32 s0, s50, 2
	v_lshl_add_u64 v[116:117], v[116:117], 0, s[0:1]
	s_waitcnt lgkmcnt(0)
	v_add_f32_e32 v112, v112, v113
	global_store_dword v[116:117], v112, off
.LBB0_2006:
	s_or_b64 exec, exec, s[38:39]
	v_or_b32_e32 v112, 16, v148
	s_waitcnt lgkmcnt(0)
	v_ashrrev_i32_e32 v113, 31, v112
	v_lshlrev_b64 v[116:117], 11, v[112:113]
	v_lshl_add_u64 v[116:117], s[14:15], 0, v[116:117]
	v_lshl_add_u64 v[122:123], v[146:147], 1, v[116:117]
	s_mov_b64 s[100:101], 0x40000
	v_lshl_add_u64 v[230:231], v[232:233], 0, s[100:101]
	global_load_dwordx4 v[188:191], v[230:231], off
	global_load_dwordx4 v[192:195], v[230:231], off offset:256
	s_waitcnt vmcnt(9)
	v_lshlrev_b32_e32 v115, 16, v196
	v_and_b32_e32 v116, 0xffff0000, v196
	v_lshlrev_b32_e32 v121, 16, v197
	v_and_b32_e32 v117, 0xffff0000, v197
	v_lshlrev_b32_e32 v124, 16, v198
	v_and_b32_e32 v118, 0xffff0000, v198
	v_lshlrev_b32_e32 v125, 16, v199
	v_and_b32_e32 v119, 0xffff0000, v199
	v_add_f32_e32 v115, v108, v115
	v_add_f32_e32 v116, v109, v116
	v_add_f32_e32 v121, v110, v121
	v_add_f32_e32 v117, v111, v117
	v_add_f32_e32 v124, v104, v124
	v_add_f32_e32 v118, v105, v118
	v_add_f32_e32 v125, v106, v125
	v_add_f32_e32 v119, v107, v119
	v_cvt_pk_bf16_f32 v104, v115, v116
	v_cvt_pk_bf16_f32 v105, v121, v117
	v_cvt_pk_bf16_f32 v106, v124, v118
	v_cvt_pk_bf16_f32 v107, v125, v119
	v_mul_f32_e32 v116, v116, v116
	v_mul_f32_e32 v117, v117, v117
	v_mul_f32_e32 v118, v118, v118
	v_mul_f32_e32 v119, v119, v119
	v_fmac_f32_e32 v116, v115, v115
	v_fmac_f32_e32 v117, v121, v121
	v_fmac_f32_e32 v118, v124, v124
	v_fmac_f32_e32 v119, v125, v125
	v_add_f32_e32 v115, v116, v117
	v_add_f32_e32 v116, v118, v119
	v_add_f32_e32 v115, v115, v116
	global_store_dwordx4 v[122:123], v[104:107], off
	s_waitcnt vmcnt(9)
	v_lshlrev_b32_e32 v116, 16, v200
	v_and_b32_e32 v108, 0xffff0000, v200
	v_lshlrev_b32_e32 v117, 16, v201
	v_and_b32_e32 v109, 0xffff0000, v201
	v_lshlrev_b32_e32 v118, 16, v202
	v_and_b32_e32 v110, 0xffff0000, v202
	v_lshlrev_b32_e32 v119, 16, v203
	v_and_b32_e32 v111, 0xffff0000, v203
	v_add_f32_e32 v101, v101, v108
	v_add_f32_e32 v103, v103, v109
	v_add_f32_e32 v109, v97, v110
	v_add_f32_e32 v111, v99, v111
	v_add_f32_e32 v100, v100, v116
	v_add_f32_e32 v102, v102, v117
	v_add_f32_e32 v108, v96, v118
	v_add_f32_e32 v110, v98, v119
	v_mul_f32_e32 v96, v101, v101
	v_mul_f32_e32 v97, v103, v103
	v_mul_f32_e32 v98, v109, v109
	v_mul_f32_e32 v99, v111, v111
	v_fmac_f32_e32 v96, v100, v100
	v_fmac_f32_e32 v97, v102, v102
	v_fmac_f32_e32 v98, v108, v108
	v_fmac_f32_e32 v99, v110, v110
	v_add_f32_e32 v96, v96, v97
	v_add_f32_e32 v97, v98, v99
	v_add_f32_e32 v96, v96, v97
	v_add_f32_e32 v96, v115, v96
	v_mov_b32_e32 v97, v96
	s_nop 1
	v_permlane16_swap_b32_e32 v97, v96
	v_cvt_pk_bf16_f32 v98, v100, v101
	v_cvt_pk_bf16_f32 v99, v102, v103
	v_cvt_pk_bf16_f32 v100, v108, v109
	v_cvt_pk_bf16_f32 v101, v110, v111
	s_waitcnt lgkmcnt(0)
	v_add_f32_e32 v96, v96, v97
	v_mov_b32_e32 v97, v96
	s_nop 1
	v_permlane32_swap_b32_e32 v97, v96
	global_store_dwordx4 v[122:123], v[98:101], off offset:256
	s_and_saveexec_b64 s[38:39], s[4:5]
	s_cbranch_execz .LBB0_2008
	v_lshlrev_b64 v[98:99], 6, v[112:113]
	v_lshl_add_u64 v[98:99], s[18:19], 0, v[98:99]
	v_lshl_add_u64 v[98:99], s[36:37], 2, v[98:99]
	s_lshl_b32 s0, s50, 2
	v_lshl_add_u64 v[98:99], v[98:99], 0, s[0:1]
	s_waitcnt lgkmcnt(0)
	v_add_f32_e32 v96, v96, v97
	global_store_dword v[98:99], v96, off
.LBB0_2008:
	s_or_b64 exec, exec, s[38:39]
	v_or_b32_e32 v96, 32, v148
	s_waitcnt lgkmcnt(0)
	v_ashrrev_i32_e32 v97, 31, v96
	v_lshlrev_b64 v[98:99], 11, v[96:97]
	v_lshl_add_u64 v[98:99], s[14:15], 0, v[98:99]
	v_lshl_add_u64 v[102:103], v[146:147], 1, v[98:99]
	s_mov_b64 s[100:101], 0x48000
	v_lshl_add_u64 v[230:231], v[232:233], 0, s[100:101]
	global_load_dwordx4 v[196:199], v[230:231], off
	global_load_dwordx4 v[200:203], v[230:231], off offset:256
	s_waitcnt vmcnt(11)
	v_lshlrev_b32_e32 v104, 16, v204
	v_and_b32_e32 v98, 0xffff0000, v204
	v_lshlrev_b32_e32 v105, 16, v205
	v_and_b32_e32 v99, 0xffff0000, v205
	v_lshlrev_b32_e32 v106, 16, v206
	v_and_b32_e32 v100, 0xffff0000, v206
	v_lshlrev_b32_e32 v107, 16, v207
	v_and_b32_e32 v101, 0xffff0000, v207
	v_add_f32_e32 v104, v92, v104
	v_add_f32_e32 v98, v93, v98
	v_add_f32_e32 v105, v94, v105
	v_add_f32_e32 v99, v95, v99
	v_add_f32_e32 v106, v88, v106
	v_add_f32_e32 v100, v89, v100
	v_add_f32_e32 v107, v90, v107
	v_add_f32_e32 v101, v91, v101
	v_cvt_pk_bf16_f32 v88, v104, v98
	v_cvt_pk_bf16_f32 v89, v105, v99
	v_cvt_pk_bf16_f32 v90, v106, v100
	v_cvt_pk_bf16_f32 v91, v107, v101
	v_mul_f32_e32 v98, v98, v98
	v_mul_f32_e32 v99, v99, v99
	v_mul_f32_e32 v100, v100, v100
	v_mul_f32_e32 v101, v101, v101
	v_fmac_f32_e32 v98, v104, v104
	v_fmac_f32_e32 v99, v105, v105
	v_fmac_f32_e32 v100, v106, v106
	v_fmac_f32_e32 v101, v107, v107
	v_add_f32_e32 v98, v98, v99
	v_add_f32_e32 v99, v100, v101
	v_add_f32_e32 v98, v98, v99
	global_store_dwordx4 v[102:103], v[88:91], off
	s_waitcnt vmcnt(11)
	v_lshlrev_b32_e32 v99, 16, v208
	v_and_b32_e32 v92, 0xffff0000, v208
	v_lshlrev_b32_e32 v100, 16, v209
	v_and_b32_e32 v93, 0xffff0000, v209
	v_lshlrev_b32_e32 v101, 16, v210
	v_and_b32_e32 v94, 0xffff0000, v210
	v_lshlrev_b32_e32 v104, 16, v211
	v_and_b32_e32 v95, 0xffff0000, v211
	v_add_f32_e32 v85, v85, v92
	v_add_f32_e32 v87, v87, v93
	v_add_f32_e32 v93, v81, v94
	v_add_f32_e32 v95, v83, v95
	v_add_f32_e32 v84, v84, v99
	v_add_f32_e32 v86, v86, v100
	v_add_f32_e32 v92, v80, v101
	v_add_f32_e32 v94, v82, v104
	v_mul_f32_e32 v80, v85, v85
	v_mul_f32_e32 v81, v87, v87
	v_mul_f32_e32 v82, v93, v93
	v_mul_f32_e32 v83, v95, v95
	v_fmac_f32_e32 v80, v84, v84
	v_fmac_f32_e32 v81, v86, v86
	v_fmac_f32_e32 v82, v92, v92
	v_fmac_f32_e32 v83, v94, v94
	v_add_f32_e32 v80, v80, v81
	v_add_f32_e32 v81, v82, v83
	v_add_f32_e32 v80, v80, v81
	v_add_f32_e32 v80, v98, v80
	v_mov_b32_e32 v81, v80
	s_nop 1
	v_permlane16_swap_b32_e32 v81, v80
	v_cvt_pk_bf16_f32 v82, v84, v85
	v_cvt_pk_bf16_f32 v83, v86, v87
	v_cvt_pk_bf16_f32 v84, v92, v93
	v_cvt_pk_bf16_f32 v85, v94, v95
	s_waitcnt lgkmcnt(0)
	v_add_f32_e32 v80, v80, v81
	v_mov_b32_e32 v81, v80
	s_nop 1
	v_permlane32_swap_b32_e32 v81, v80
	global_store_dwordx4 v[102:103], v[82:85], off offset:256
	s_and_saveexec_b64 s[38:39], s[4:5]
	s_cbranch_execz .LBB0_2010
	v_lshlrev_b64 v[82:83], 6, v[96:97]
	v_lshl_add_u64 v[82:83], s[18:19], 0, v[82:83]
	v_lshl_add_u64 v[82:83], s[36:37], 2, v[82:83]
	s_lshl_b32 s0, s50, 2
	v_lshl_add_u64 v[82:83], v[82:83], 0, s[0:1]
	s_waitcnt lgkmcnt(0)
	v_add_f32_e32 v80, v80, v81
	global_store_dword v[82:83], v80, off
.LBB0_2010:
	s_or_b64 exec, exec, s[38:39]
	v_or_b32_e32 v80, 48, v148
	s_waitcnt lgkmcnt(0)
	v_ashrrev_i32_e32 v81, 31, v80
	v_lshlrev_b64 v[82:83], 11, v[80:81]
	v_lshl_add_u64 v[82:83], s[14:15], 0, v[82:83]
	v_lshl_add_u64 v[86:87], v[146:147], 1, v[82:83]
	s_mov_b64 s[100:101], 0x50000
	v_lshl_add_u64 v[230:231], v[232:233], 0, s[100:101]
	global_load_dwordx4 v[204:207], v[230:231], off
	global_load_dwordx4 v[208:211], v[230:231], off offset:256
	s_waitcnt vmcnt(13)
	v_lshlrev_b32_e32 v88, 16, v212
	v_and_b32_e32 v82, 0xffff0000, v212
	v_lshlrev_b32_e32 v89, 16, v213
	v_and_b32_e32 v83, 0xffff0000, v213
	v_lshlrev_b32_e32 v90, 16, v214
	v_and_b32_e32 v84, 0xffff0000, v214
	v_lshlrev_b32_e32 v91, 16, v215
	v_and_b32_e32 v85, 0xffff0000, v215
	v_add_f32_e32 v88, v76, v88
	v_add_f32_e32 v82, v77, v82
	v_add_f32_e32 v89, v78, v89
	v_add_f32_e32 v83, v79, v83
	v_add_f32_e32 v90, v72, v90
	v_add_f32_e32 v84, v73, v84
	v_add_f32_e32 v91, v74, v91
	v_add_f32_e32 v85, v75, v85
	v_cvt_pk_bf16_f32 v72, v88, v82
	v_cvt_pk_bf16_f32 v73, v89, v83
	v_cvt_pk_bf16_f32 v74, v90, v84
	v_cvt_pk_bf16_f32 v75, v91, v85
	v_mul_f32_e32 v82, v82, v82
	v_mul_f32_e32 v83, v83, v83
	v_mul_f32_e32 v84, v84, v84
	v_mul_f32_e32 v85, v85, v85
	v_fmac_f32_e32 v82, v88, v88
	v_fmac_f32_e32 v83, v89, v89
	v_fmac_f32_e32 v84, v90, v90
	v_fmac_f32_e32 v85, v91, v91
	v_add_f32_e32 v82, v82, v83
	v_add_f32_e32 v83, v84, v85
	v_add_f32_e32 v82, v82, v83
	global_store_dwordx4 v[86:87], v[72:75], off
	s_waitcnt vmcnt(13)
	v_lshlrev_b32_e32 v83, 16, v216
	v_and_b32_e32 v76, 0xffff0000, v216
	v_lshlrev_b32_e32 v84, 16, v217
	v_and_b32_e32 v77, 0xffff0000, v217
	v_lshlrev_b32_e32 v85, 16, v218
	v_and_b32_e32 v78, 0xffff0000, v218
	v_lshlrev_b32_e32 v88, 16, v219
	v_and_b32_e32 v79, 0xffff0000, v219
	v_add_f32_e32 v69, v69, v76
	v_add_f32_e32 v71, v71, v77
	v_add_f32_e32 v77, v65, v78
	v_add_f32_e32 v79, v67, v79
	v_add_f32_e32 v68, v68, v83
	v_add_f32_e32 v70, v70, v84
	v_add_f32_e32 v76, v64, v85
	v_add_f32_e32 v78, v66, v88
	v_mul_f32_e32 v64, v69, v69
	v_mul_f32_e32 v65, v71, v71
	v_mul_f32_e32 v66, v77, v77
	v_mul_f32_e32 v67, v79, v79
	v_fmac_f32_e32 v64, v68, v68
	v_fmac_f32_e32 v65, v70, v70
	v_fmac_f32_e32 v66, v76, v76
	v_fmac_f32_e32 v67, v78, v78
	v_add_f32_e32 v64, v64, v65
	v_add_f32_e32 v65, v66, v67
	v_add_f32_e32 v64, v64, v65
	v_add_f32_e32 v64, v82, v64
	v_mov_b32_e32 v65, v64
	s_nop 1
	v_permlane16_swap_b32_e32 v65, v64
	v_cvt_pk_bf16_f32 v66, v68, v69
	v_cvt_pk_bf16_f32 v67, v70, v71
	v_cvt_pk_bf16_f32 v68, v76, v77
	v_cvt_pk_bf16_f32 v69, v78, v79
	s_waitcnt lgkmcnt(0)
	v_add_f32_e32 v64, v64, v65
	v_mov_b32_e32 v65, v64
	s_nop 1
	v_permlane32_swap_b32_e32 v65, v64
	global_store_dwordx4 v[86:87], v[66:69], off offset:256
	s_and_saveexec_b64 s[38:39], s[4:5]
	s_cbranch_execz .LBB0_2012
	v_lshlrev_b64 v[66:67], 6, v[80:81]
	v_lshl_add_u64 v[66:67], s[18:19], 0, v[66:67]
	v_lshl_add_u64 v[66:67], s[36:37], 2, v[66:67]
	s_lshl_b32 s0, s50, 2
	v_lshl_add_u64 v[66:67], v[66:67], 0, s[0:1]
	s_waitcnt lgkmcnt(0)
	v_add_f32_e32 v64, v64, v65
	global_store_dword v[66:67], v64, off
.LBB0_2012:
	s_or_b64 exec, exec, s[38:39]
	v_add_u32_e32 v64, 0x80, v148
	s_waitcnt lgkmcnt(0)
	v_ashrrev_i32_e32 v65, 31, v64
	v_lshlrev_b64 v[66:67], 11, v[64:65]
	v_lshl_add_u64 v[66:67], s[14:15], 0, v[66:67]
	v_lshl_add_u64 v[70:71], v[146:147], 1, v[66:67]
	s_mov_b64 s[100:101], 0x58000
	v_lshl_add_u64 v[230:231], v[232:233], 0, s[100:101]
	global_load_dwordx4 v[212:215], v[230:231], off
	global_load_dwordx4 v[216:219], v[230:231], off offset:256
	s_waitcnt vmcnt(13)
	v_lshlrev_b32_e32 v72, 16, v188
	v_and_b32_e32 v66, 0xffff0000, v188
	v_lshlrev_b32_e32 v73, 16, v189
	v_and_b32_e32 v67, 0xffff0000, v189
	v_lshlrev_b32_e32 v74, 16, v190
	v_and_b32_e32 v68, 0xffff0000, v190
	v_lshlrev_b32_e32 v75, 16, v191
	v_and_b32_e32 v69, 0xffff0000, v191
	v_add_f32_e32 v72, v60, v72
	v_add_f32_e32 v66, v61, v66
	v_add_f32_e32 v73, v62, v73
	v_add_f32_e32 v67, v63, v67
	v_add_f32_e32 v74, v56, v74
	v_add_f32_e32 v68, v57, v68
	v_add_f32_e32 v75, v58, v75
	v_add_f32_e32 v69, v59, v69
	v_cvt_pk_bf16_f32 v56, v72, v66
	v_cvt_pk_bf16_f32 v57, v73, v67
	v_cvt_pk_bf16_f32 v58, v74, v68
	v_cvt_pk_bf16_f32 v59, v75, v69
	v_mul_f32_e32 v66, v66, v66
	v_mul_f32_e32 v67, v67, v67
	v_mul_f32_e32 v68, v68, v68
	v_mul_f32_e32 v69, v69, v69
	v_fmac_f32_e32 v66, v72, v72
	v_fmac_f32_e32 v67, v73, v73
	v_fmac_f32_e32 v68, v74, v74
	v_fmac_f32_e32 v69, v75, v75
	v_add_f32_e32 v66, v66, v67
	v_add_f32_e32 v67, v68, v69
	v_add_f32_e32 v66, v66, v67
	global_store_dwordx4 v[70:71], v[56:59], off
	s_waitcnt vmcnt(13)
	v_lshlrev_b32_e32 v67, 16, v192
	v_and_b32_e32 v60, 0xffff0000, v192
	v_lshlrev_b32_e32 v68, 16, v193
	v_and_b32_e32 v61, 0xffff0000, v193
	v_lshlrev_b32_e32 v69, 16, v194
	v_and_b32_e32 v62, 0xffff0000, v194
	v_lshlrev_b32_e32 v72, 16, v195
	v_and_b32_e32 v63, 0xffff0000, v195
	v_add_f32_e32 v53, v53, v60
	v_add_f32_e32 v55, v55, v61
	v_add_f32_e32 v61, v49, v62
	v_add_f32_e32 v63, v51, v63
	v_add_f32_e32 v52, v52, v67
	v_add_f32_e32 v54, v54, v68
	v_add_f32_e32 v60, v48, v69
	v_add_f32_e32 v62, v50, v72
	v_mul_f32_e32 v48, v53, v53
	v_mul_f32_e32 v49, v55, v55
	v_mul_f32_e32 v50, v61, v61
	v_mul_f32_e32 v51, v63, v63
	v_fmac_f32_e32 v48, v52, v52
	v_fmac_f32_e32 v49, v54, v54
	v_fmac_f32_e32 v50, v60, v60
	v_fmac_f32_e32 v51, v62, v62
	v_add_f32_e32 v48, v48, v49
	v_add_f32_e32 v49, v50, v51
	v_add_f32_e32 v48, v48, v49
	v_add_f32_e32 v48, v66, v48
	v_mov_b32_e32 v49, v48
	s_nop 1
	v_permlane16_swap_b32_e32 v49, v48
	v_cvt_pk_bf16_f32 v50, v52, v53
	v_cvt_pk_bf16_f32 v51, v54, v55
	v_cvt_pk_bf16_f32 v52, v60, v61
	v_cvt_pk_bf16_f32 v53, v62, v63
	s_waitcnt lgkmcnt(0)
	v_add_f32_e32 v48, v48, v49
	v_mov_b32_e32 v49, v48
	s_nop 1
	v_permlane32_swap_b32_e32 v49, v48
	global_store_dwordx4 v[70:71], v[50:53], off offset:256
	s_and_saveexec_b64 s[38:39], s[4:5]
	s_cbranch_execz .LBB0_2014
	v_lshlrev_b64 v[50:51], 6, v[64:65]
	v_lshl_add_u64 v[50:51], s[18:19], 0, v[50:51]
	v_lshl_add_u64 v[50:51], s[36:37], 2, v[50:51]
	s_lshl_b32 s0, s50, 2
	v_lshl_add_u64 v[50:51], v[50:51], 0, s[0:1]
	s_waitcnt lgkmcnt(0)
	v_add_f32_e32 v48, v48, v49
	global_store_dword v[50:51], v48, off
.LBB0_2014:
	s_or_b64 exec, exec, s[38:39]
	v_add_u32_e32 v48, 0x90, v148
	s_waitcnt lgkmcnt(0)
	v_ashrrev_i32_e32 v49, 31, v48
	v_lshlrev_b64 v[50:51], 11, v[48:49]
	v_lshl_add_u64 v[50:51], s[14:15], 0, v[50:51]
	v_lshl_add_u64 v[54:55], v[146:147], 1, v[50:51]
	s_waitcnt vmcnt(11)
	v_lshlrev_b32_e32 v56, 16, v196
	v_and_b32_e32 v50, 0xffff0000, v196
	v_lshlrev_b32_e32 v57, 16, v197
	v_and_b32_e32 v51, 0xffff0000, v197
	v_lshlrev_b32_e32 v58, 16, v198
	v_and_b32_e32 v52, 0xffff0000, v198
	v_lshlrev_b32_e32 v59, 16, v199
	v_and_b32_e32 v53, 0xffff0000, v199
	v_add_f32_e32 v56, v44, v56
	v_add_f32_e32 v50, v45, v50
	v_add_f32_e32 v57, v46, v57
	v_add_f32_e32 v51, v47, v51
	v_add_f32_e32 v58, v40, v58
	v_add_f32_e32 v52, v41, v52
	v_add_f32_e32 v59, v42, v59
	v_add_f32_e32 v53, v43, v53
	v_cvt_pk_bf16_f32 v40, v56, v50
	v_cvt_pk_bf16_f32 v41, v57, v51
	v_cvt_pk_bf16_f32 v42, v58, v52
	v_cvt_pk_bf16_f32 v43, v59, v53
	v_mul_f32_e32 v50, v50, v50
	v_mul_f32_e32 v51, v51, v51
	v_mul_f32_e32 v52, v52, v52
	v_mul_f32_e32 v53, v53, v53
	v_fmac_f32_e32 v50, v56, v56
	v_fmac_f32_e32 v51, v57, v57
	v_fmac_f32_e32 v52, v58, v58
	v_fmac_f32_e32 v53, v59, v59
	v_add_f32_e32 v50, v50, v51
	v_add_f32_e32 v51, v52, v53
	v_add_f32_e32 v50, v50, v51
	global_store_dwordx4 v[54:55], v[40:43], off
	s_waitcnt vmcnt(11)
	v_lshlrev_b32_e32 v51, 16, v200
	v_and_b32_e32 v44, 0xffff0000, v200
	v_lshlrev_b32_e32 v52, 16, v201
	v_and_b32_e32 v45, 0xffff0000, v201
	v_lshlrev_b32_e32 v53, 16, v202
	v_and_b32_e32 v46, 0xffff0000, v202
	v_lshlrev_b32_e32 v56, 16, v203
	v_and_b32_e32 v47, 0xffff0000, v203
	v_add_f32_e32 v37, v37, v44
	v_add_f32_e32 v39, v39, v45
	v_add_f32_e32 v45, v33, v46
	v_add_f32_e32 v47, v35, v47
	v_add_f32_e32 v36, v36, v51
	v_add_f32_e32 v38, v38, v52
	v_add_f32_e32 v44, v32, v53
	v_add_f32_e32 v46, v34, v56
	v_mul_f32_e32 v32, v37, v37
	v_mul_f32_e32 v33, v39, v39
	v_mul_f32_e32 v34, v45, v45
	v_mul_f32_e32 v35, v47, v47
	v_fmac_f32_e32 v32, v36, v36
	v_fmac_f32_e32 v33, v38, v38
	v_fmac_f32_e32 v34, v44, v44
	v_fmac_f32_e32 v35, v46, v46
	v_add_f32_e32 v32, v32, v33
	v_add_f32_e32 v33, v34, v35
	v_add_f32_e32 v32, v32, v33
	v_add_f32_e32 v32, v50, v32
	v_mov_b32_e32 v33, v32
	s_nop 1
	v_permlane16_swap_b32_e32 v33, v32
	v_cvt_pk_bf16_f32 v34, v36, v37
	v_cvt_pk_bf16_f32 v35, v38, v39
	v_cvt_pk_bf16_f32 v36, v44, v45
	v_cvt_pk_bf16_f32 v37, v46, v47
	s_waitcnt lgkmcnt(0)
	v_add_f32_e32 v32, v32, v33
	v_mov_b32_e32 v33, v32
	s_nop 1
	v_permlane32_swap_b32_e32 v33, v32
	global_store_dwordx4 v[54:55], v[34:37], off offset:256
	s_and_saveexec_b64 s[38:39], s[4:5]
	s_cbranch_execz .LBB0_2016
	v_lshlrev_b64 v[34:35], 6, v[48:49]
	v_lshl_add_u64 v[34:35], s[18:19], 0, v[34:35]
	v_lshl_add_u64 v[34:35], s[36:37], 2, v[34:35]
	s_lshl_b32 s0, s50, 2
	v_lshl_add_u64 v[34:35], v[34:35], 0, s[0:1]
	s_waitcnt lgkmcnt(0)
	v_add_f32_e32 v32, v32, v33
	global_store_dword v[34:35], v32, off
.LBB0_2016:
	s_or_b64 exec, exec, s[38:39]
	v_add_u32_e32 v32, 0xa0, v148
	s_waitcnt lgkmcnt(0)
	v_ashrrev_i32_e32 v33, 31, v32
	v_lshlrev_b64 v[34:35], 11, v[32:33]
	v_lshl_add_u64 v[34:35], s[14:15], 0, v[34:35]
	v_lshl_add_u64 v[38:39], v[146:147], 1, v[34:35]
	s_waitcnt vmcnt(9)
	v_lshlrev_b32_e32 v40, 16, v204
	v_and_b32_e32 v34, 0xffff0000, v204
	v_lshlrev_b32_e32 v41, 16, v205
	v_and_b32_e32 v35, 0xffff0000, v205
	v_lshlrev_b32_e32 v42, 16, v206
	v_and_b32_e32 v36, 0xffff0000, v206
	v_lshlrev_b32_e32 v43, 16, v207
	v_and_b32_e32 v37, 0xffff0000, v207
	v_add_f32_e32 v40, v28, v40
	v_add_f32_e32 v34, v29, v34
	v_add_f32_e32 v41, v30, v41
	v_add_f32_e32 v35, v31, v35
	v_add_f32_e32 v42, v24, v42
	v_add_f32_e32 v36, v25, v36
	v_add_f32_e32 v43, v26, v43
	v_add_f32_e32 v37, v27, v37
	v_cvt_pk_bf16_f32 v24, v40, v34
	v_cvt_pk_bf16_f32 v25, v41, v35
	v_cvt_pk_bf16_f32 v26, v42, v36
	v_cvt_pk_bf16_f32 v27, v43, v37
	v_mul_f32_e32 v34, v34, v34
	v_mul_f32_e32 v35, v35, v35
	v_mul_f32_e32 v36, v36, v36
	v_mul_f32_e32 v37, v37, v37
	v_fmac_f32_e32 v34, v40, v40
	v_fmac_f32_e32 v35, v41, v41
	v_fmac_f32_e32 v36, v42, v42
	v_fmac_f32_e32 v37, v43, v43
	v_add_f32_e32 v34, v34, v35
	v_add_f32_e32 v35, v36, v37
	v_add_f32_e32 v34, v34, v35
	global_store_dwordx4 v[38:39], v[24:27], off
	s_waitcnt vmcnt(9)
	v_lshlrev_b32_e32 v35, 16, v208
	v_and_b32_e32 v28, 0xffff0000, v208
	v_lshlrev_b32_e32 v36, 16, v209
	v_and_b32_e32 v29, 0xffff0000, v209
	v_lshlrev_b32_e32 v37, 16, v210
	v_and_b32_e32 v30, 0xffff0000, v210
	v_lshlrev_b32_e32 v40, 16, v211
	v_and_b32_e32 v31, 0xffff0000, v211
	v_add_f32_e32 v21, v21, v28
	v_add_f32_e32 v23, v23, v29
	v_add_f32_e32 v29, v17, v30
	v_add_f32_e32 v31, v19, v31
	v_add_f32_e32 v20, v20, v35
	v_add_f32_e32 v22, v22, v36
	v_add_f32_e32 v28, v16, v37
	v_add_f32_e32 v30, v18, v40
	v_mul_f32_e32 v16, v21, v21
	v_mul_f32_e32 v17, v23, v23
	v_mul_f32_e32 v18, v29, v29
	v_mul_f32_e32 v19, v31, v31
	v_fmac_f32_e32 v16, v20, v20
	v_fmac_f32_e32 v17, v22, v22
	v_fmac_f32_e32 v18, v28, v28
	v_fmac_f32_e32 v19, v30, v30
	v_add_f32_e32 v16, v16, v17
	v_add_f32_e32 v17, v18, v19
	v_add_f32_e32 v16, v16, v17
	v_add_f32_e32 v16, v34, v16
	v_mov_b32_e32 v17, v16
	s_nop 1
	v_permlane16_swap_b32_e32 v17, v16
	v_cvt_pk_bf16_f32 v18, v20, v21
	v_cvt_pk_bf16_f32 v19, v22, v23
	v_cvt_pk_bf16_f32 v20, v28, v29
	v_cvt_pk_bf16_f32 v21, v30, v31
	s_waitcnt lgkmcnt(0)
	v_add_f32_e32 v16, v16, v17
	v_mov_b32_e32 v17, v16
	s_nop 1
	v_permlane32_swap_b32_e32 v17, v16
	global_store_dwordx4 v[38:39], v[18:21], off offset:256
	s_and_saveexec_b64 s[38:39], s[4:5]
	s_cbranch_execz .LBB0_2018
	v_lshlrev_b64 v[18:19], 6, v[32:33]
	v_lshl_add_u64 v[18:19], s[18:19], 0, v[18:19]
	v_lshl_add_u64 v[18:19], s[36:37], 2, v[18:19]
	s_lshl_b32 s0, s50, 2
	v_lshl_add_u64 v[18:19], v[18:19], 0, s[0:1]
	s_waitcnt lgkmcnt(0)
	v_add_f32_e32 v16, v16, v17
	global_store_dword v[18:19], v16, off
.LBB0_2018:
	s_or_b64 exec, exec, s[38:39]
	v_add_u32_e32 v16, 0xb0, v148
	s_waitcnt lgkmcnt(0)
	v_ashrrev_i32_e32 v17, 31, v16
	v_lshlrev_b64 v[18:19], 11, v[16:17]
	v_lshl_add_u64 v[18:19], s[14:15], 0, v[18:19]
	v_lshl_add_u64 v[22:23], v[146:147], 1, v[18:19]
	s_waitcnt vmcnt(7)
	v_lshlrev_b32_e32 v24, 16, v212
	v_and_b32_e32 v18, 0xffff0000, v212
	v_lshlrev_b32_e32 v25, 16, v213
	v_and_b32_e32 v19, 0xffff0000, v213
	v_lshlrev_b32_e32 v26, 16, v214
	v_and_b32_e32 v20, 0xffff0000, v214
	v_lshlrev_b32_e32 v27, 16, v215
	v_and_b32_e32 v21, 0xffff0000, v215
	v_add_f32_e32 v24, v12, v24
	v_add_f32_e32 v18, v13, v18
	v_add_f32_e32 v25, v14, v25
	v_add_f32_e32 v19, v15, v19
	v_add_f32_e32 v26, v8, v26
	v_add_f32_e32 v20, v9, v20
	v_add_f32_e32 v27, v10, v27
	v_add_f32_e32 v21, v11, v21
	v_cvt_pk_bf16_f32 v8, v24, v18
	v_cvt_pk_bf16_f32 v9, v25, v19
	v_cvt_pk_bf16_f32 v10, v26, v20
	v_cvt_pk_bf16_f32 v11, v27, v21
	v_mul_f32_e32 v18, v18, v18
	v_mul_f32_e32 v19, v19, v19
	v_mul_f32_e32 v20, v20, v20
	v_mul_f32_e32 v21, v21, v21
	v_fmac_f32_e32 v18, v24, v24
	v_fmac_f32_e32 v19, v25, v25
	v_fmac_f32_e32 v20, v26, v26
	v_fmac_f32_e32 v21, v27, v27
	v_add_f32_e32 v18, v18, v19
	v_add_f32_e32 v19, v20, v21
	v_add_f32_e32 v18, v18, v19
	global_store_dwordx4 v[22:23], v[8:11], off
	s_waitcnt vmcnt(7)
	v_lshlrev_b32_e32 v19, 16, v216
	v_and_b32_e32 v12, 0xffff0000, v216
	v_lshlrev_b32_e32 v20, 16, v217
	v_and_b32_e32 v13, 0xffff0000, v217
	v_lshlrev_b32_e32 v21, 16, v218
	v_and_b32_e32 v14, 0xffff0000, v218
	v_lshlrev_b32_e32 v24, 16, v219
	v_and_b32_e32 v15, 0xffff0000, v219
	v_add_f32_e32 v5, v5, v12
	v_add_f32_e32 v7, v7, v13
	v_add_f32_e32 v13, v1, v14
	v_add_f32_e32 v15, v3, v15
	v_add_f32_e32 v4, v4, v19
	v_add_f32_e32 v6, v6, v20
	v_add_f32_e32 v12, v0, v21
	v_add_f32_e32 v14, v2, v24
	v_mul_f32_e32 v0, v5, v5
	v_mul_f32_e32 v1, v7, v7
	v_mul_f32_e32 v2, v13, v13
	v_mul_f32_e32 v3, v15, v15
	v_fmac_f32_e32 v0, v4, v4
	v_fmac_f32_e32 v1, v6, v6
	v_fmac_f32_e32 v2, v12, v12
	v_fmac_f32_e32 v3, v14, v14
	v_add_f32_e32 v0, v0, v1
	v_add_f32_e32 v1, v2, v3
	v_add_f32_e32 v0, v0, v1
	v_add_f32_e32 v0, v18, v0
	v_mov_b32_e32 v1, v0
	s_nop 1
	v_permlane16_swap_b32_e32 v1, v0
	v_cvt_pk_bf16_f32 v2, v4, v5
	v_cvt_pk_bf16_f32 v3, v6, v7
	v_cvt_pk_bf16_f32 v4, v12, v13
	v_cvt_pk_bf16_f32 v5, v14, v15
	s_waitcnt lgkmcnt(0)
	v_add_f32_e32 v0, v0, v1
	v_mov_b32_e32 v1, v0
	s_nop 1
	v_permlane32_swap_b32_e32 v1, v0
	global_store_dwordx4 v[22:23], v[2:5], off offset:256
	s_and_saveexec_b64 s[38:39], s[4:5]
	s_cbranch_execz .LBB0_2020
	v_lshlrev_b64 v[2:3], 6, v[16:17]
	v_lshl_add_u64 v[2:3], s[18:19], 0, v[2:3]
	v_lshl_add_u64 v[2:3], s[36:37], 2, v[2:3]
	s_lshl_b32 s0, s50, 2
	v_lshl_add_u64 v[2:3], v[2:3], 0, s[0:1]
	s_waitcnt lgkmcnt(0)
	v_add_f32_e32 v0, v0, v1
	global_store_dword v[2:3], v0, off
